# counted LDS waits inside the GEMM MFMA clusters: each MFMA waits only for the fragment reads that feed it (40 clusters in the five 8-phase GEMM bodies)
# speedup vs baseline: 1.0097x; 1.0097x over previous
; #define PG8_STAGE(bufoff, gbase, voff) do { _Pragma("unroll") for (int _i = 0; _i < 2; ++_i) \
;         __builtin_amdgcn_global_load_lds((const unsigned*)((const char*)(gbase) + (voff)[_i]), (LAS unsigned*)(lds + (bufoff) + ldsw + _i * 8192), 16, 0, 0); } while (0)
; #define PG8_LDA(dst, b, h) do { _Pragma("unroll") for (int m = 0; m < 4; ++m) _Pragma("unroll") for (int k = 0; k < 2; ++k) dst[m][k] = *(const LAS bf16x8*)(lds + PG8_SA(b, h) + aoff + m * 2048 + k * 1024); } while (0)
; #define PG8_LDB(dst, b, h) do { _Pragma("unroll") for (int n = 0; n < 2; ++n) _Pragma("unroll") for (int k = 0; k < 2; ++k) dst[n][k] = *(const LAS bf16x8*)(lds + PG8_SB(b, h) + boff + n * 2048 + k * 1024); } while (0)
; #define PG8_MMA(ai, bj, At, Bt) do { __builtin_amdgcn_s_setprio(1); _Pragma("unroll") for (int m = 0; m < 4; ++m) _Pragma("unroll") for (int n = 0; n < 2; ++n) _Pragma("unroll") for (int k = 0; k < 2; ++k) \
;         acc[ai][bj][m][n] = __builtin_amdgcn_mfma_f32_16x16x32_bf16(Bt[n][k], At[m][k], acc[ai][bj][m][n], 0, 0, 0); __builtin_amdgcn_s_setprio(0); } while (0)
; #define PG8_WAIT_V(n) asm volatile("s_waitcnt vmcnt(" #n ")" ::: "memory")
; #define PG8_WAIT_L(n) asm volatile("s_waitcnt lgkmcnt(" #n ")" ::: "memory")
; #define PG8_BAR __builtin_amdgcn_s_barrier()
; #define PG8_SCHED __builtin_amdgcn_sched_barrier(0)
; template <class Epi>
; __device__ __forceinline__ void gemm_phase(LAS unsigned char* lds, const Gemm g, const StaticOrder& S, const Epi& E) {
;     ...
;             PG8_LDB(B0, 0, 0); PG8_SCHED; PG8_LDA(At, 0, 0); PG8_STAGE(PG8_SA(1, 1), a1 + hstepA, voffA);
;             PG8_WAIT_L(8); PG8_BAR; PG8_WAIT_L(0); PG8_MMA(0, 0, At, B0); PG8_BAR; PG8_SCHED;
;             PG8_LDB(B1, 0, 1); PG8_STAGE(PG8_SB(0, 0), b2, voffB);
;             PG8_BAR; PG8_WAIT_L(0); PG8_MMA(0, 1, At, B1); PG8_BAR;
;             PG8_LDA(At, 0, 1); PG8_STAGE(PG8_SA(0, 0), a2, voffA);
;             PG8_BAR; PG8_WAIT_L(0); PG8_MMA(1, 0, At, B0); PG8_BAR; PG8_SCHED;
;             PG8_STAGE(PG8_SB(0, 1), b2 + hstepB, voffB);
;             PG8_WAIT_V(6); PG8_BAR; PG8_MMA(1, 1, At, B1); PG8_BAR;
.LBB0_126:
	ds_read_b128 v[156:159], v152
	ds_read_b128 v[160:163], v152 offset:1024
	ds_read_b128 v[164:167], v152 offset:2048
	ds_read_b128 v[168:171], v152 offset:3072
	s_add_u32 s68, s66, 0xfff80080
	s_addc_u32 s69, s67, -1
	s_cmp_eq_u32 s93, 28
	s_cselect_b32 s71, s31, s69
	s_cselect_b32 s70, s65, s68
	s_cselect_b32 s69, s29, s92
	s_cselect_b32 s68, s90, s91
	v_lshl_add_u64 v[146:147], s[66:67], 0, v[138:139]
	s_add_i32 m0, s77, 0xc000
	ds_read_b128 v[172:175], v153
	ds_read_b128 v[176:179], v153 offset:1024
	ds_read_b128 v[180:183], v153 offset:2048
	ds_read_b128 v[184:187], v153 offset:3072
	ds_read_b128 v[190:193], v153 offset:4096
	ds_read_b128 v[194:197], v153 offset:5120
	ds_read_b128 v[198:201], v153 offset:6144
	ds_read_b128 v[202:205], v153 offset:7168
	global_load_lds_dwordx4 v[146:147], off
	v_lshl_add_u64 v[146:147], s[66:67], 0, v[140:141]
	s_add_i32 m0, s77, 0xe000
	s_nop 0
	global_load_lds_dwordx4 v[146:147], off
	s_waitcnt lgkmcnt(8)
	s_barrier
	s_setprio 1
	s_waitcnt lgkmcnt(7)
	v_mfma_f32_16x16x32_bf16 v[124:127], v[156:159], v[172:175], v[124:127]
	v_mfma_f32_16x16x32_bf16 v[120:123], v[164:167], v[172:175], v[120:123]
	s_waitcnt lgkmcnt(5)
	v_mfma_f32_16x16x32_bf16 v[112:115], v[156:159], v[180:183], v[112:115]
	v_mfma_f32_16x16x32_bf16 v[104:107], v[164:167], v[180:183], v[104:107]
	s_waitcnt lgkmcnt(3)
	v_mfma_f32_16x16x32_bf16 v[96:99], v[156:159], v[190:193], v[96:99]
	v_mfma_f32_16x16x32_bf16 v[88:91], v[164:167], v[190:193], v[88:91]
	s_waitcnt lgkmcnt(1)
	v_mfma_f32_16x16x32_bf16 v[80:83], v[156:159], v[198:201], v[80:83]
	v_mfma_f32_16x16x32_bf16 v[72:75], v[164:167], v[198:201], v[72:75]
	v_mfma_f32_16x16x32_bf16 v[124:127], v[160:163], v[176:179], v[124:127]
	v_mfma_f32_16x16x32_bf16 v[120:123], v[168:171], v[176:179], v[120:123]
	v_mfma_f32_16x16x32_bf16 v[112:115], v[160:163], v[184:187], v[112:115]
	v_mfma_f32_16x16x32_bf16 v[104:107], v[168:171], v[184:187], v[104:107]
	v_mfma_f32_16x16x32_bf16 v[96:99], v[160:163], v[194:197], v[96:99]
	v_mfma_f32_16x16x32_bf16 v[88:91], v[168:171], v[194:197], v[88:91]
	s_waitcnt lgkmcnt(0)
	v_mfma_f32_16x16x32_bf16 v[80:83], v[160:163], v[202:205], v[80:83]
	v_mfma_f32_16x16x32_bf16 v[72:75], v[168:171], v[202:205], v[72:75]
	s_setprio 0
	s_barrier
	s_add_i32 s94, s87, s74
	v_lshl_add_u64 v[146:147], s[68:69], 0, v[132:133]
	s_mov_b32 m0, s94
	ds_read_b128 v[206:209], v154
	ds_read_b128 v[210:213], v154 offset:1024
	ds_read_b128 v[214:217], v154 offset:2048
	ds_read_b128 v[218:221], v154 offset:3072
	global_load_lds_dwordx4 v[146:147], off
	v_lshl_add_u64 v[222:223], s[68:69], 0, v[128:129]
	s_add_i32 m0, s94, 0x2000
	s_nop 0
	global_load_lds_dwordx4 v[222:223], off
	s_barrier
	s_setprio 1
	s_waitcnt lgkmcnt(3)
	v_mfma_f32_16x16x32_bf16 v[116:119], v[206:209], v[172:175], v[116:119]
	s_waitcnt lgkmcnt(1)
	v_mfma_f32_16x16x32_bf16 v[108:111], v[214:217], v[172:175], v[108:111]
	v_mfma_f32_16x16x32_bf16 v[100:103], v[206:209], v[180:183], v[100:103]
	v_mfma_f32_16x16x32_bf16 v[92:95], v[214:217], v[180:183], v[92:95]
	v_mfma_f32_16x16x32_bf16 v[84:87], v[206:209], v[190:193], v[84:87]
	v_mfma_f32_16x16x32_bf16 v[76:79], v[214:217], v[190:193], v[76:79]
	v_mfma_f32_16x16x32_bf16 v[68:71], v[206:209], v[198:201], v[68:71]
	v_mfma_f32_16x16x32_bf16 v[64:67], v[214:217], v[198:201], v[64:67]
	v_mfma_f32_16x16x32_bf16 v[116:119], v[210:213], v[176:179], v[116:119]
	s_waitcnt lgkmcnt(0)
	v_mfma_f32_16x16x32_bf16 v[108:111], v[218:221], v[176:179], v[108:111]
	v_mfma_f32_16x16x32_bf16 v[100:103], v[210:213], v[184:187], v[100:103]
	v_mfma_f32_16x16x32_bf16 v[92:95], v[218:221], v[184:187], v[92:95]
	v_mfma_f32_16x16x32_bf16 v[84:87], v[210:213], v[194:197], v[84:87]
	v_mfma_f32_16x16x32_bf16 v[76:79], v[218:221], v[194:197], v[76:79]
	v_mfma_f32_16x16x32_bf16 v[68:71], v[210:213], v[202:205], v[68:71]
	v_mfma_f32_16x16x32_bf16 v[64:67], v[218:221], v[202:205], v[64:67]
	s_setprio 0
	s_mov_b32 m0, s77
	v_lshl_add_u64 v[224:225], s[70:71], 0, v[134:135]
	s_barrier
	ds_read_b128 v[172:175], v153 offset:16384
	ds_read_b128 v[176:179], v153 offset:17408
	ds_read_b128 v[180:183], v153 offset:18432
	ds_read_b128 v[184:187], v153 offset:19456
	ds_read_b128 v[190:193], v153 offset:20480
	ds_read_b128 v[194:197], v153 offset:21504
	ds_read_b128 v[198:201], v153 offset:22528
	ds_read_b128 v[202:205], v153 offset:23552
	global_load_lds_dwordx4 v[224:225], off
	v_lshl_add_u64 v[226:227], s[70:71], 0, v[130:131]
	s_mov_b32 m0, s78
	s_nop 0
	global_load_lds_dwordx4 v[226:227], off
	s_barrier
	s_setprio 1
	s_waitcnt lgkmcnt(7)
	v_mfma_f32_16x16x32_bf16 v[60:63], v[156:159], v[172:175], v[60:63]
	v_mfma_f32_16x16x32_bf16 v[56:59], v[164:167], v[172:175], v[56:59]
	s_waitcnt lgkmcnt(5)
	v_mfma_f32_16x16x32_bf16 v[48:51], v[156:159], v[180:183], v[48:51]
	v_mfma_f32_16x16x32_bf16 v[40:43], v[164:167], v[180:183], v[40:43]
	s_waitcnt lgkmcnt(3)
	v_mfma_f32_16x16x32_bf16 v[36:39], v[156:159], v[190:193], v[36:39]
	v_mfma_f32_16x16x32_bf16 v[28:31], v[164:167], v[190:193], v[28:31]
	s_waitcnt lgkmcnt(1)
	v_mfma_f32_16x16x32_bf16 v[20:23], v[156:159], v[198:201], v[20:23]
	v_mfma_f32_16x16x32_bf16 v[12:15], v[164:167], v[198:201], v[12:15]
	v_mfma_f32_16x16x32_bf16 v[60:63], v[160:163], v[176:179], v[60:63]
	v_mfma_f32_16x16x32_bf16 v[56:59], v[168:171], v[176:179], v[56:59]
	v_mfma_f32_16x16x32_bf16 v[48:51], v[160:163], v[184:187], v[48:51]
	v_mfma_f32_16x16x32_bf16 v[40:43], v[168:171], v[184:187], v[40:43]
	v_mfma_f32_16x16x32_bf16 v[36:39], v[160:163], v[194:197], v[36:39]
	v_mfma_f32_16x16x32_bf16 v[28:31], v[168:171], v[194:197], v[28:31]
	s_waitcnt lgkmcnt(0)
	v_mfma_f32_16x16x32_bf16 v[20:23], v[160:163], v[202:205], v[20:23]
	v_mfma_f32_16x16x32_bf16 v[12:15], v[168:171], v[202:205], v[12:15]
	s_setprio 0
	s_barrier
; #define PG8_STAGE(bufoff, gbase, voff) do { _Pragma("unroll") for (int _i = 0; _i < 2; ++_i) \
;         __builtin_amdgcn_global_load_lds((const unsigned*)((const char*)(gbase) + (voff)[_i]), (LAS unsigned*)(lds + (bufoff) + ldsw + _i * 8192), 16, 0, 0); } while (0)
; #define PG8_LDA(dst, b, h) do { _Pragma("unroll") for (int m = 0; m < 4; ++m) _Pragma("unroll") for (int k = 0; k < 2; ++k) dst[m][k] = *(const LAS bf16x8*)(lds + PG8_SA(b, h) + aoff + m * 2048 + k * 1024); } while (0)
; #define PG8_LDB(dst, b, h) do { _Pragma("unroll") for (int n = 0; n < 2; ++n) _Pragma("unroll") for (int k = 0; k < 2; ++k) dst[n][k] = *(const LAS bf16x8*)(lds + PG8_SB(b, h) + boff + n * 2048 + k * 1024); } while (0)
; #define PG8_MMA(ai, bj, At, Bt) do { __builtin_amdgcn_s_setprio(1); _Pragma("unroll") for (int m = 0; m < 4; ++m) _Pragma("unroll") for (int n = 0; n < 2; ++n) _Pragma("unroll") for (int k = 0; k < 2; ++k) \
;         acc[ai][bj][m][n] = __builtin_amdgcn_mfma_f32_16x16x32_bf16(Bt[n][k], At[m][k], acc[ai][bj][m][n], 0, 0, 0); __builtin_amdgcn_s_setprio(0); } while (0)
; #define PG8_WAIT_V(n) asm volatile("s_waitcnt vmcnt(" #n ")" ::: "memory")
; #define PG8_WAIT_L(n) asm volatile("s_waitcnt lgkmcnt(" #n ")" ::: "memory")
; #define PG8_BAR __builtin_amdgcn_s_barrier()
; #define PG8_SCHED __builtin_amdgcn_sched_barrier(0)
; template <class Epi>
; __device__ __forceinline__ void gemm_phase(LAS unsigned char* lds, const Gemm g, const StaticOrder& S, const Epi& E) {
;     ...
;             PG8_WAIT_V(6); PG8_BAR; PG8_MMA(1, 1, At, B1); PG8_BAR;
;             PG8_LDB(B0, 1, 0); PG8_SCHED; PG8_LDA(At, 1, 0); PG8_STAGE(PG8_SA(0, 1), a2 + hstepA, voffA);
;             PG8_WAIT_L(8); PG8_BAR; PG8_WAIT_L(0); PG8_MMA(0, 0, At, B0); PG8_BAR; PG8_SCHED;
;             PG8_LDB(B1, 1, 1); PG8_STAGE(PG8_SB(1, 0), b3, voffB);
;             PG8_BAR; PG8_WAIT_L(0); PG8_MMA(0, 1, At, B1); PG8_BAR;
;             PG8_LDA(At, 1, 1); PG8_STAGE(PG8_SA(1, 0), a3, voffA);
;             PG8_BAR; PG8_WAIT_L(0); PG8_MMA(1, 0, At, B0); PG8_BAR; PG8_SCHED;
	s_add_u32 s94, s68, 0x80000
	s_addc_u32 s95, s69, 0
	s_add_i32 vcc_lo, s88, s74
	v_lshl_add_u64 v[156:157], s[94:95], 0, v[132:133]
	s_mov_b32 m0, vcc_lo
	s_nop 0
	global_load_lds_dwordx4 v[156:157], off
	v_lshl_add_u64 v[156:157], s[94:95], 0, v[128:129]
	s_add_i32 m0, vcc_lo, 0x2000
	s_nop 0
	global_load_lds_dwordx4 v[156:157], off
	s_waitcnt vmcnt(6)
	s_barrier
	s_setprio 1
	v_mfma_f32_16x16x32_bf16 v[52:55], v[206:209], v[172:175], v[52:55]
	v_mfma_f32_16x16x32_bf16 v[44:47], v[214:217], v[172:175], v[44:47]
	v_mfma_f32_16x16x32_bf16 v[32:35], v[206:209], v[180:183], v[32:35]
	v_mfma_f32_16x16x32_bf16 v[24:27], v[214:217], v[180:183], v[24:27]
	v_mfma_f32_16x16x32_bf16 v[16:19], v[206:209], v[190:193], v[16:19]
	v_mfma_f32_16x16x32_bf16 v[8:11], v[214:217], v[190:193], v[8:11]
	v_mfma_f32_16x16x32_bf16 v[4:7], v[206:209], v[198:201], v[4:7]
	v_mfma_f32_16x16x32_bf16 v[0:3], v[214:217], v[198:201], v[0:3]
	v_mfma_f32_16x16x32_bf16 v[52:55], v[210:213], v[176:179], v[52:55]
	v_mfma_f32_16x16x32_bf16 v[44:47], v[218:221], v[176:179], v[44:47]
	v_mfma_f32_16x16x32_bf16 v[32:35], v[210:213], v[184:187], v[32:35]
	v_mfma_f32_16x16x32_bf16 v[24:27], v[218:221], v[184:187], v[24:27]
	v_mfma_f32_16x16x32_bf16 v[16:19], v[210:213], v[194:197], v[16:19]
	v_mfma_f32_16x16x32_bf16 v[8:11], v[218:221], v[194:197], v[8:11]
	v_mfma_f32_16x16x32_bf16 v[4:7], v[210:213], v[202:205], v[4:7]
	v_mfma_f32_16x16x32_bf16 v[0:3], v[218:221], v[202:205], v[0:3]
	s_setprio 0
	s_add_i32 s94, 0, 0x18000
	v_add_u32_e32 v136, s94, v149
	s_barrier
	ds_read_b128 v[156:159], v136
	ds_read_b128 v[160:163], v136 offset:1024
	ds_read_b128 v[164:167], v136 offset:2048
	ds_read_b128 v[168:171], v136 offset:3072
	s_add_u32 s70, s70, 0x80000
	s_addc_u32 s71, s71, 0
	s_mov_b32 m0, s79
	v_lshl_add_u64 v[206:207], s[70:71], 0, v[134:135]
	ds_read_b128 v[172:175], v153 offset:32768
	ds_read_b128 v[176:179], v153 offset:33792
	ds_read_b128 v[180:183], v153 offset:34816
	ds_read_b128 v[184:187], v153 offset:35840
	ds_read_b128 v[190:193], v153 offset:36864
	ds_read_b128 v[194:197], v153 offset:37888
	ds_read_b128 v[198:201], v153 offset:38912
	ds_read_b128 v[202:205], v153 offset:39936
	global_load_lds_dwordx4 v[206:207], off
	v_lshl_add_u64 v[206:207], s[70:71], 0, v[130:131]
	s_mov_b32 m0, s80
	s_nop 0
	global_load_lds_dwordx4 v[206:207], off
	s_waitcnt lgkmcnt(8)
	s_barrier
	s_setprio 1
	s_waitcnt lgkmcnt(7)
	v_mfma_f32_16x16x32_bf16 v[124:127], v[156:159], v[172:175], v[124:127]
	v_mfma_f32_16x16x32_bf16 v[120:123], v[164:167], v[172:175], v[120:123]
	s_waitcnt lgkmcnt(5)
	v_mfma_f32_16x16x32_bf16 v[112:115], v[156:159], v[180:183], v[112:115]
	v_mfma_f32_16x16x32_bf16 v[104:107], v[164:167], v[180:183], v[104:107]
	s_waitcnt lgkmcnt(3)
	v_mfma_f32_16x16x32_bf16 v[96:99], v[156:159], v[190:193], v[96:99]
	v_mfma_f32_16x16x32_bf16 v[88:91], v[164:167], v[190:193], v[88:91]
	s_waitcnt lgkmcnt(1)
	v_mfma_f32_16x16x32_bf16 v[80:83], v[156:159], v[198:201], v[80:83]
	v_mfma_f32_16x16x32_bf16 v[72:75], v[164:167], v[198:201], v[72:75]
	v_mfma_f32_16x16x32_bf16 v[124:127], v[160:163], v[176:179], v[124:127]
	v_mfma_f32_16x16x32_bf16 v[120:123], v[168:171], v[176:179], v[120:123]
	v_mfma_f32_16x16x32_bf16 v[112:115], v[160:163], v[184:187], v[112:115]
	v_mfma_f32_16x16x32_bf16 v[104:107], v[168:171], v[184:187], v[104:107]
	v_mfma_f32_16x16x32_bf16 v[96:99], v[160:163], v[194:197], v[96:99]
	v_mfma_f32_16x16x32_bf16 v[88:91], v[168:171], v[194:197], v[88:91]
	s_waitcnt lgkmcnt(0)
	v_mfma_f32_16x16x32_bf16 v[80:83], v[160:163], v[202:205], v[80:83]
	v_mfma_f32_16x16x32_bf16 v[72:75], v[168:171], v[202:205], v[72:75]
	s_setprio 0
	s_barrier
	s_add_i32 s70, 0, 0x1c000
	s_add_i32 s71, s94, s74
	v_add_u32_e32 v136, s70, v149
	v_lshl_add_u64 v[146:147], v[146:147], 0, s[26:27]
	s_mov_b32 m0, s71
	ds_read_b128 v[206:209], v136
	ds_read_b128 v[210:213], v136 offset:1024
	ds_read_b128 v[214:217], v136 offset:2048
	ds_read_b128 v[218:221], v136 offset:3072
	global_load_lds_dwordx4 v[146:147], off
	v_lshl_add_u64 v[146:147], v[222:223], 0, s[26:27]
	s_add_i32 m0, s71, 0x2000
	s_nop 0
	global_load_lds_dwordx4 v[146:147], off
	s_barrier
; __device__ __forceinline__ unsigned cvt_pk_bf16(float lo, float hi) { unsigned r; asm volatile("v_cvt_pk_bf16_f32 %0, %1, %2" : "=v"(r) : "v"(lo), "v"(hi)); return r; }
; #define PG8_STAGE(bufoff, gbase, voff) do { _Pragma("unroll") for (int _i = 0; _i < 2; ++_i) \
;         __builtin_amdgcn_global_load_lds((const unsigned*)((const char*)(gbase) + (voff)[_i]), (LAS unsigned*)(lds + (bufoff) + ldsw + _i * 8192), 16, 0, 0); } while (0)
; #define PG8_WAIT_V(n) asm volatile("s_waitcnt vmcnt(" #n ")" ::: "memory")
; #define PG8_WAIT_L(n) asm volatile("s_waitcnt lgkmcnt(" #n ")" ::: "memory")
; #define PG8_BAR __builtin_amdgcn_s_barrier()
; #define PG8_SCHED __builtin_amdgcn_sched_barrier(0)
; template <class Epi>
; __device__ __forceinline__ void gemm_phase(LAS unsigned char* lds, const Gemm g, const StaticOrder& S, const Epi& E) {
;     ...
;             PG8_BAR; PG8_WAIT_L(0); PG8_MMA(1, 0, At, B0); PG8_BAR; PG8_SCHED;
;             PG8_STAGE(PG8_SB(1, 1), b3 + hstepB, voffB);
;             PG8_WAIT_V(6); PG8_BAR; PG8_MMA(1, 1, At, B1); PG8_BAR;
;     __device__ __forceinline__ void operator()(const AccT& acc, const Unit& u, int wr, int wc, int fr, int fq) const {
;         const int row0 = u.pm * 256 + wr * 64 + fr; const int pn = u.pn;
;         if (pn >= 25 && pn < 29) {
;             const int cb = (pn - 25) * 256 + wc * 32 + 8 * fq;
; #pragma unroll
;             for (int ai = 0; ai < 2; ++ai)
; #pragma unroll
;                 for (int m = 0; m < 4; ++m) { const int row = row0 + ai * 128 + m * 16; const int b = row >> 14, tt = row & (SEQ - 1);
; #pragma unroll
;                     for (int bj = 0; bj < 2; ++bj)
; #pragma unroll
;                         for (int n = 0; n < 2; ++n)
; #pragma unroll
;                             for (int j = 0; j < 4; ++j) { const int ch = cb + bj * 128 + 4 * n + j;
;                                 vt[((size_t)(b * 1024 + ch)) * SEQ + tt] = (u16)(cvt_pk_bf16(acc[ai][bj][m][n][j], 0.f) & 0xffffu); } }
;             return;
;         }
;         u16* base; int ld, colt;
;         if (pn < 13) { base = zs; ld = 3328; colt = pn * 256; }
;         else if (pn < 17) { base = zg; ld = 1024; colt = (pn - 13) * 256; }
;         else if (pn < 21) { base = qn; ld = 1024; colt = (pn - 17) * 256; }
;         else if (pn < 25) { base = kn; ld = 1024; colt = (pn - 21) * 256; }
;         else { base = gn; ld = 1024; colt = (pn - 29) * 256; }
	s_setprio 1
	s_waitcnt lgkmcnt(3)
	v_mfma_f32_16x16x32_bf16 v[116:119], v[206:209], v[172:175], v[116:119]
	s_waitcnt lgkmcnt(1)
	v_mfma_f32_16x16x32_bf16 v[108:111], v[214:217], v[172:175], v[108:111]
	v_mfma_f32_16x16x32_bf16 v[100:103], v[206:209], v[180:183], v[100:103]
	v_mfma_f32_16x16x32_bf16 v[92:95], v[214:217], v[180:183], v[92:95]
	v_mfma_f32_16x16x32_bf16 v[84:87], v[206:209], v[190:193], v[84:87]
	v_mfma_f32_16x16x32_bf16 v[76:79], v[214:217], v[190:193], v[76:79]
	v_mfma_f32_16x16x32_bf16 v[68:71], v[206:209], v[198:201], v[68:71]
	v_mfma_f32_16x16x32_bf16 v[64:67], v[214:217], v[198:201], v[64:67]
	v_mfma_f32_16x16x32_bf16 v[116:119], v[210:213], v[176:179], v[116:119]
	s_waitcnt lgkmcnt(0)
	v_mfma_f32_16x16x32_bf16 v[108:111], v[218:221], v[176:179], v[108:111]
	v_mfma_f32_16x16x32_bf16 v[100:103], v[210:213], v[184:187], v[100:103]
	v_mfma_f32_16x16x32_bf16 v[92:95], v[218:221], v[184:187], v[92:95]
	v_mfma_f32_16x16x32_bf16 v[84:87], v[210:213], v[194:197], v[84:87]
	v_mfma_f32_16x16x32_bf16 v[76:79], v[218:221], v[194:197], v[76:79]
	v_mfma_f32_16x16x32_bf16 v[68:71], v[210:213], v[202:205], v[68:71]
	v_mfma_f32_16x16x32_bf16 v[64:67], v[218:221], v[202:205], v[64:67]
	s_setprio 0
	s_mov_b32 m0, s83
	v_lshl_add_u64 v[146:147], v[224:225], 0, s[26:27]
	s_barrier
	ds_read_b128 v[172:175], v153 offset:49152
	ds_read_b128 v[176:179], v153 offset:50176
	ds_read_b128 v[180:183], v153 offset:51200
	ds_read_b128 v[184:187], v153 offset:52224
	ds_read_b128 v[190:193], v153 offset:53248
	ds_read_b128 v[194:197], v153 offset:54272
	ds_read_b128 v[198:201], v153 offset:55296
	ds_read_b128 v[202:205], v153 offset:56320
	global_load_lds_dwordx4 v[146:147], off
	v_lshl_add_u64 v[146:147], v[226:227], 0, s[26:27]
	s_mov_b32 m0, s84
	s_nop 0
	global_load_lds_dwordx4 v[146:147], off
	s_barrier
	s_setprio 1
	s_waitcnt lgkmcnt(7)
	v_mfma_f32_16x16x32_bf16 v[60:63], v[156:159], v[172:175], v[60:63]
	v_mfma_f32_16x16x32_bf16 v[56:59], v[164:167], v[172:175], v[56:59]
	s_waitcnt lgkmcnt(5)
	v_mfma_f32_16x16x32_bf16 v[48:51], v[156:159], v[180:183], v[48:51]
	v_mfma_f32_16x16x32_bf16 v[40:43], v[164:167], v[180:183], v[40:43]
	s_waitcnt lgkmcnt(3)
	v_mfma_f32_16x16x32_bf16 v[36:39], v[156:159], v[190:193], v[36:39]
	v_mfma_f32_16x16x32_bf16 v[28:31], v[164:167], v[190:193], v[28:31]
	s_waitcnt lgkmcnt(1)
	v_mfma_f32_16x16x32_bf16 v[20:23], v[156:159], v[198:201], v[20:23]
	v_mfma_f32_16x16x32_bf16 v[12:15], v[164:167], v[198:201], v[12:15]
	v_mfma_f32_16x16x32_bf16 v[60:63], v[160:163], v[176:179], v[60:63]
	v_mfma_f32_16x16x32_bf16 v[56:59], v[168:171], v[176:179], v[56:59]
	v_mfma_f32_16x16x32_bf16 v[48:51], v[160:163], v[184:187], v[48:51]
	v_mfma_f32_16x16x32_bf16 v[40:43], v[168:171], v[184:187], v[40:43]
	v_mfma_f32_16x16x32_bf16 v[36:39], v[160:163], v[194:197], v[36:39]
	v_mfma_f32_16x16x32_bf16 v[28:31], v[168:171], v[194:197], v[28:31]
	s_waitcnt lgkmcnt(0)
	v_mfma_f32_16x16x32_bf16 v[20:23], v[160:163], v[202:205], v[20:23]
	v_mfma_f32_16x16x32_bf16 v[12:15], v[168:171], v[202:205], v[12:15]
	s_setprio 0
	s_barrier
	s_add_u32 s68, s68, 0x80080
	s_addc_u32 s69, s69, 0
	s_add_i32 s70, s70, s74
	v_lshl_add_u64 v[146:147], s[68:69], 0, v[132:133]
	s_mov_b32 m0, s70
	s_nop 0
	global_load_lds_dwordx4 v[146:147], off
	v_lshl_add_u64 v[146:147], s[68:69], 0, v[128:129]
	s_add_i32 m0, s70, 0x2000
	s_nop 0
	global_load_lds_dwordx4 v[146:147], off
	s_waitcnt vmcnt(6)
	s_barrier
	s_setprio 1
	v_mfma_f32_16x16x32_bf16 v[52:55], v[206:209], v[172:175], v[52:55]
	v_mfma_f32_16x16x32_bf16 v[44:47], v[214:217], v[172:175], v[44:47]
	v_mfma_f32_16x16x32_bf16 v[32:35], v[206:209], v[180:183], v[32:35]
	v_mfma_f32_16x16x32_bf16 v[24:27], v[214:217], v[180:183], v[24:27]
	v_mfma_f32_16x16x32_bf16 v[16:19], v[206:209], v[190:193], v[16:19]
	v_mfma_f32_16x16x32_bf16 v[8:11], v[214:217], v[190:193], v[8:11]
	v_mfma_f32_16x16x32_bf16 v[4:7], v[206:209], v[198:201], v[4:7]
	v_mfma_f32_16x16x32_bf16 v[0:3], v[214:217], v[198:201], v[0:3]
	v_mfma_f32_16x16x32_bf16 v[52:55], v[210:213], v[176:179], v[52:55]
	v_mfma_f32_16x16x32_bf16 v[44:47], v[218:221], v[176:179], v[44:47]
	v_mfma_f32_16x16x32_bf16 v[32:35], v[210:213], v[184:187], v[32:35]
	v_mfma_f32_16x16x32_bf16 v[24:27], v[218:221], v[184:187], v[24:27]
	v_mfma_f32_16x16x32_bf16 v[16:19], v[210:213], v[194:197], v[16:19]
	v_mfma_f32_16x16x32_bf16 v[8:11], v[218:221], v[194:197], v[8:11]
	v_mfma_f32_16x16x32_bf16 v[4:7], v[210:213], v[202:205], v[4:7]
	v_mfma_f32_16x16x32_bf16 v[0:3], v[218:221], v[202:205], v[0:3]
	s_setprio 0
	s_add_i32 s93, s93, 2
	s_add_u32 s66, s66, 0x100
	s_addc_u32 s67, s67, 0
	s_add_u32 s91, s91, 0x100
	s_addc_u32 s92, s92, 0
	s_cmp_gt_u32 s93, 29
	s_barrier
	s_cbranch_scc0 .LBB0_126
	s_lshl_b32 s29, s64, 8
	s_add_i32 s29, s29, s82
	s_sub_i32 s31, s89, 25
	v_or_b32_e32 v155, s29, v148
	s_cmp_gt_u32 s31, 3
	s_mov_b64 s[64:65], -1
	s_cbranch_scc0 .LBB0_145
	s_cmp_gt_i32 s89, 12
	s_cbranch_scc0 .LBB0_142
	s_lshl_b32 s68, s89, 8
	s_cmp_gt_u32 s89, 16
	s_cbranch_scc0 .LBB0_139
	s_cmp_gt_u32 s89, 20
	s_cbranch_scc0 .LBB0_136
	s_cmp_gt_u32 s89, 24
	s_cbranch_scc0 .LBB0_133
	s_add_i32 s31, s68, 0xffffe300
	s_mov_b64 s[64:65], 0

; #define PG8_STAGE(bufoff, gbase, voff) do { _Pragma("unroll") for (int _i = 0; _i < 2; ++_i) \
;         __builtin_amdgcn_global_load_lds((const unsigned*)((const char*)(gbase) + (voff)[_i]), (LAS unsigned*)(lds + (bufoff) + ldsw + _i * 8192), 16, 0, 0); } while (0)
; #define PG8_LDA(dst, b, h) do { _Pragma("unroll") for (int m = 0; m < 4; ++m) _Pragma("unroll") for (int k = 0; k < 2; ++k) dst[m][k] = *(const LAS bf16x8*)(lds + PG8_SA(b, h) + aoff + m * 2048 + k * 1024); } while (0)
; #define PG8_WAIT_V(n) asm volatile("s_waitcnt vmcnt(" #n ")" ::: "memory")
; #define PG8_BAR __builtin_amdgcn_s_barrier()
; template <class Epi>
; __device__ __forceinline__ void gemm_phase(LAS unsigned char* lds, const Gemm g, const StaticOrder& S, const Epi& E) {
;     ...
;     PG8_STAGE(PG8_SB(0, 0), cB, voffB); PG8_STAGE(PG8_SA(0, 0), cA, voffA); PG8_STAGE(PG8_SB(0, 1), cB + hstepB, voffB); PG8_STAGE(PG8_SA(0, 1), cA + hstepA, voffA);
;     if (wr == 1) PG8_BAR;
;     PG8_WAIT_V(4); PG8_BAR;
;     PG8_STAGE(PG8_SB(1, 0), cB + kstep, voffB); PG8_STAGE(PG8_SA(1, 0), cA + kstep, voffA); PG8_STAGE(PG8_SB(1, 1), cB + hstepB + kstep, voffB);
;     PG8_WAIT_V(6); PG8_BAR;
;     for (;;) {
;         const bool has_next = S.next(ui + 1, nxt);
;         const char* nA = has_next ? (const char*)g.A + (size_t)nxt.pm * tstepA : cA; const char* nB = has_next ? (const char*)g.Bt + (size_t)nxt.pn * tstepB : cB;
;         for (int t = 0; t < nt; t += 2) {
;             const bool last = (t == nt - 2);
;             const char* a1 = cA + (size_t)(t + 1) * kstep;
;             const char* a2 = last ? nA : cA + (size_t)(t + 2) * kstep; const char* b2 = last ? nB : cB + (size_t)(t + 2) * kstep;
;             const char* a3 = a2 + kstep; const char* b3 = b2 + kstep;
;             PG8_LDB(B0, 0, 0); PG8_SCHED; PG8_LDA(At, 0, 0); PG8_STAGE(PG8_SA(1, 1), a1 + hstepA, voffA);
;             PG8_WAIT_L(8); PG8_BAR; PG8_WAIT_L(0); PG8_MMA(0, 0, At, B0); PG8_BAR; PG8_SCHED;
;             PG8_LDB(B1, 0, 1); PG8_STAGE(PG8_SB(0, 0), b2, voffB);
;             PG8_BAR; PG8_WAIT_L(0); PG8_MMA(0, 1, At, B1); PG8_BAR;
;             PG8_LDA(At, 0, 1); PG8_STAGE(PG8_SA(0, 0), a2, voffA);
;             PG8_BAR; PG8_WAIT_L(0); PG8_MMA(1, 0, At, B0); PG8_BAR; PG8_SCHED;
;             PG8_STAGE(PG8_SB(0, 1), b2 + hstepB, voffB);
;             PG8_WAIT_V(6); PG8_BAR; PG8_MMA(1, 1, At, B1); PG8_BAR;
.LBB0_352:
	s_ashr_i32 s31, s30, 31
	s_lshl_b64 s[38:39], s[30:31], 17
	v_mov_b64_e32 v[0:1], 0x400
	s_add_u32 s38, s71, s38
	v_cmp_lt_i64_e32 vcc, s[26:27], v[0:1]
	s_addc_u32 s39, s72, s39
	s_and_b64 s[40:41], vcc, exec
	s_cselect_b32 s67, s39, s65
	s_cselect_b32 s66, s38, s64
	s_ashr_i32 s29, s28, 31
	s_lshl_b64 s[40:41], s[28:29], 16
	s_add_u32 s40, s73, s40
	s_addc_u32 s41, s74, s41
	s_add_u32 s92, s64, 0x10080
	ds_read_b128 v[0:3], v171
	ds_read_b128 v[4:7], v171 offset:1024
	ds_read_b128 v[8:11], v171 offset:2048
	ds_read_b128 v[12:15], v171 offset:3072
	s_addc_u32 s93, s65, 0
	s_add_u32 s64, s66, 0x10000
	s_addc_u32 s65, s67, 0
	s_and_b64 s[68:69], vcc, exec
	s_cselect_b32 s60, s40, s60
	s_cselect_b32 s61, s41, s61
	s_add_u32 s68, s60, 0x8000
	s_addc_u32 s69, s61, 0
	v_lshl_add_u64 v[48:49], s[92:93], 0, v[132:133]
	s_add_i32 m0, s76, 0xc000
	ds_read_b128 v[16:19], v172
	ds_read_b128 v[20:23], v172 offset:1024
	ds_read_b128 v[24:27], v172 offset:2048
	ds_read_b128 v[28:31], v172 offset:3072
	ds_read_b128 v[32:35], v172 offset:4096
	ds_read_b128 v[36:39], v172 offset:5120
	ds_read_b128 v[40:43], v172 offset:6144
	ds_read_b128 v[44:47], v172 offset:7168
	global_load_lds_dwordx4 v[48:49], off
	v_lshl_add_u64 v[48:49], s[92:93], 0, v[136:137]
	s_add_i32 m0, s76, 0xe000
	s_nop 0
	global_load_lds_dwordx4 v[48:49], off
	s_waitcnt lgkmcnt(8)
	s_barrier
	s_setprio 1
	s_waitcnt lgkmcnt(7)
	v_mfma_f32_16x16x32_bf16 v[48:51], v[0:3], v[16:19], 0
	v_mfma_f32_16x16x32_bf16 v[52:55], v[8:11], v[16:19], 0
	s_waitcnt lgkmcnt(5)
	v_mfma_f32_16x16x32_bf16 v[56:59], v[0:3], v[24:27], 0
	v_mfma_f32_16x16x32_bf16 v[60:63], v[8:11], v[24:27], 0
	s_waitcnt lgkmcnt(3)
	v_mfma_f32_16x16x32_bf16 v[64:67], v[0:3], v[32:35], 0
	v_mfma_f32_16x16x32_bf16 v[68:71], v[8:11], v[32:35], 0
	s_waitcnt lgkmcnt(1)
	v_mfma_f32_16x16x32_bf16 v[72:75], v[0:3], v[40:43], 0
	v_mfma_f32_16x16x32_bf16 v[76:79], v[8:11], v[40:43], 0
	v_mfma_f32_16x16x32_bf16 v[48:51], v[4:7], v[20:23], v[48:51]
	v_mfma_f32_16x16x32_bf16 v[52:55], v[12:15], v[20:23], v[52:55]
	v_mfma_f32_16x16x32_bf16 v[56:59], v[4:7], v[28:31], v[56:59]
	v_mfma_f32_16x16x32_bf16 v[60:63], v[12:15], v[28:31], v[60:63]
	v_mfma_f32_16x16x32_bf16 v[64:67], v[4:7], v[36:39], v[64:67]
	v_mfma_f32_16x16x32_bf16 v[68:71], v[12:15], v[36:39], v[68:71]
	s_waitcnt lgkmcnt(0)
	v_mfma_f32_16x16x32_bf16 v[72:75], v[4:7], v[44:47], v[72:75]
	v_mfma_f32_16x16x32_bf16 v[76:79], v[12:15], v[44:47], v[76:79]
	s_setprio 0
	s_barrier
	s_add_i32 s3, s85, s75
	v_lshl_add_u64 v[186:187], s[60:61], 0, v[134:135]
	s_mov_b32 m0, s3
	ds_read_b128 v[80:83], v173
	ds_read_b128 v[84:87], v173 offset:1024
	ds_read_b128 v[88:91], v173 offset:2048
	ds_read_b128 v[92:95], v173 offset:3072
	global_load_lds_dwordx4 v[186:187], off
	v_lshl_add_u64 v[242:243], s[60:61], 0, v[138:139]
	s_add_i32 m0, s3, 0x2000
	s_nop 0
	global_load_lds_dwordx4 v[242:243], off
	s_barrier
	s_setprio 1
	s_waitcnt lgkmcnt(3)
	v_mfma_f32_16x16x32_bf16 v[96:99], v[80:83], v[16:19], 0
	s_waitcnt lgkmcnt(1)
	v_mfma_f32_16x16x32_bf16 v[16:19], v[88:91], v[16:19], 0
	v_mfma_f32_16x16x32_bf16 v[96:99], v[84:87], v[20:23], v[96:99]
	s_waitcnt lgkmcnt(0)
	v_mfma_f32_16x16x32_bf16 v[16:19], v[92:95], v[20:23], v[16:19]
	v_mfma_f32_16x16x32_bf16 v[20:23], v[80:83], v[24:27], 0
	v_mfma_f32_16x16x32_bf16 v[24:27], v[88:91], v[24:27], 0
	v_mfma_f32_16x16x32_bf16 v[20:23], v[84:87], v[28:31], v[20:23]
	v_mfma_f32_16x16x32_bf16 v[24:27], v[92:95], v[28:31], v[24:27]
	v_mfma_f32_16x16x32_bf16 v[28:31], v[80:83], v[32:35], 0
	v_mfma_f32_16x16x32_bf16 v[100:103], v[84:87], v[36:39], v[28:31]
	v_mfma_f32_16x16x32_bf16 v[28:31], v[88:91], v[32:35], 0
	v_mfma_f32_16x16x32_bf16 v[32:35], v[92:95], v[36:39], v[28:31]
	v_mfma_f32_16x16x32_bf16 v[28:31], v[80:83], v[40:43], 0
	v_mfma_f32_16x16x32_bf16 v[36:39], v[84:87], v[44:47], v[28:31]
	v_mfma_f32_16x16x32_bf16 v[28:31], v[88:91], v[40:43], 0
	v_mfma_f32_16x16x32_bf16 v[40:43], v[92:95], v[44:47], v[28:31]
	s_setprio 0
	s_mov_b32 m0, s76
	v_lshl_add_u64 v[188:189], s[66:67], 0, v[132:133]
	s_barrier
	s_nop 2
	ds_read_b128 v[28:31], v172 offset:16384
	ds_read_b128 v[44:47], v172 offset:17408
	ds_read_b128 v[104:107], v172 offset:18432
	ds_read_b128 v[108:111], v172 offset:19456
	ds_read_b128 v[112:115], v172 offset:20480
	ds_read_b128 v[116:119], v172 offset:21504
	ds_read_b128 v[120:123], v172 offset:22528
	ds_read_b128 v[124:127], v172 offset:23552
	global_load_lds_dwordx4 v[188:189], off
	v_lshl_add_u64 v[140:141], s[66:67], 0, v[136:137]
	s_mov_b32 m0, s77
	s_nop 0
	global_load_lds_dwordx4 v[140:141], off
	s_barrier
	s_setprio 1
	s_waitcnt lgkmcnt(7)
	v_mfma_f32_16x16x32_bf16 v[128:131], v[0:3], v[28:31], 0
	s_waitcnt lgkmcnt(5)
	v_mfma_f32_16x16x32_bf16 v[148:151], v[0:3], v[104:107], 0
	s_waitcnt lgkmcnt(3)
	v_mfma_f32_16x16x32_bf16 v[156:159], v[0:3], v[112:115], 0
	s_waitcnt lgkmcnt(1)
	v_mfma_f32_16x16x32_bf16 v[0:3], v[0:3], v[120:123], 0
	v_mfma_f32_16x16x32_bf16 v[128:131], v[4:7], v[44:47], v[128:131]
	v_mfma_f32_16x16x32_bf16 v[144:147], v[8:11], v[28:31], 0
	v_mfma_f32_16x16x32_bf16 v[148:151], v[4:7], v[108:111], v[148:151]
	v_mfma_f32_16x16x32_bf16 v[152:155], v[8:11], v[104:107], 0
	v_mfma_f32_16x16x32_bf16 v[156:159], v[4:7], v[116:119], v[156:159]
	s_waitcnt lgkmcnt(0)
	v_mfma_f32_16x16x32_bf16 v[0:3], v[4:7], v[124:127], v[0:3]
	v_mfma_f32_16x16x32_bf16 v[4:7], v[8:11], v[120:123], 0
	v_mfma_f32_16x16x32_bf16 v[144:147], v[12:15], v[44:47], v[144:147]
	v_mfma_f32_16x16x32_bf16 v[152:155], v[12:15], v[108:111], v[152:155]
	v_mfma_f32_16x16x32_bf16 v[160:163], v[8:11], v[112:115], 0
	v_mfma_f32_16x16x32_bf16 v[4:7], v[12:15], v[124:127], v[4:7]
	v_mfma_f32_16x16x32_bf16 v[160:163], v[12:15], v[116:119], v[160:163]
	s_setprio 0
	s_barrier
; #define PG8_STAGE(bufoff, gbase, voff) do { _Pragma("unroll") for (int _i = 0; _i < 2; ++_i) \
;         __builtin_amdgcn_global_load_lds((const unsigned*)((const char*)(gbase) + (voff)[_i]), (LAS unsigned*)(lds + (bufoff) + ldsw + _i * 8192), 16, 0, 0); } while (0)
; #define PG8_LDA(dst, b, h) do { _Pragma("unroll") for (int m = 0; m < 4; ++m) _Pragma("unroll") for (int k = 0; k < 2; ++k) dst[m][k] = *(const LAS bf16x8*)(lds + PG8_SA(b, h) + aoff + m * 2048 + k * 1024); } while (0)
; #define PG8_LDB(dst, b, h) do { _Pragma("unroll") for (int n = 0; n < 2; ++n) _Pragma("unroll") for (int k = 0; k < 2; ++k) dst[n][k] = *(const LAS bf16x8*)(lds + PG8_SB(b, h) + boff + n * 2048 + k * 1024); } while (0)
; #define PG8_MMA(ai, bj, At, Bt) do { __builtin_amdgcn_s_setprio(1); _Pragma("unroll") for (int m = 0; m < 4; ++m) _Pragma("unroll") for (int n = 0; n < 2; ++n) _Pragma("unroll") for (int k = 0; k < 2; ++k) \
;         acc[ai][bj][m][n] = __builtin_amdgcn_mfma_f32_16x16x32_bf16(Bt[n][k], At[m][k], acc[ai][bj][m][n], 0, 0, 0); __builtin_amdgcn_s_setprio(0); } while (0)
; #define PG8_WAIT_V(n) asm volatile("s_waitcnt vmcnt(" #n ")" ::: "memory")
; #define PG8_WAIT_L(n) asm volatile("s_waitcnt lgkmcnt(" #n ")" ::: "memory")
; #define PG8_BAR __builtin_amdgcn_s_barrier()
; #define PG8_SCHED __builtin_amdgcn_sched_barrier(0)
; template <class Epi>
; __device__ __forceinline__ void gemm_phase(LAS unsigned char* lds, const Gemm g, const StaticOrder& S, const Epi& E) {
;     ...
;             PG8_WAIT_V(6); PG8_BAR; PG8_MMA(1, 1, At, B1); PG8_BAR;
;             PG8_LDB(B0, 1, 0); PG8_SCHED; PG8_LDA(At, 1, 0); PG8_STAGE(PG8_SA(0, 1), a2 + hstepA, voffA);
;             PG8_WAIT_L(8); PG8_BAR; PG8_WAIT_L(0); PG8_MMA(0, 0, At, B0); PG8_BAR; PG8_SCHED;
;             PG8_LDB(B1, 1, 1); PG8_STAGE(PG8_SB(1, 0), b3, voffB);
;             PG8_BAR; PG8_WAIT_L(0); PG8_MMA(0, 1, At, B1); PG8_BAR;
;             PG8_LDA(At, 1, 1); PG8_STAGE(PG8_SA(1, 0), a3, voffA);
;             PG8_BAR; PG8_WAIT_L(0); PG8_MMA(1, 0, At, B0); PG8_BAR; PG8_SCHED;
	s_add_i32 s3, s86, s75
	v_lshl_add_u64 v[8:9], s[68:69], 0, v[134:135]
	s_mov_b32 m0, s3
	s_nop 0
	global_load_lds_dwordx4 v[8:9], off
	v_lshl_add_u64 v[8:9], s[68:69], 0, v[138:139]
	s_add_i32 m0, s3, 0x2000
	s_nop 0
	global_load_lds_dwordx4 v[8:9], off
	s_waitcnt vmcnt(6)
	s_barrier
	s_setprio 1
	v_mfma_f32_16x16x32_bf16 v[12:15], v[88:91], v[28:31], 0
	v_mfma_f32_16x16x32_bf16 v[164:167], v[92:95], v[44:47], v[12:15]
	v_mfma_f32_16x16x32_bf16 v[12:15], v[80:83], v[104:107], 0
	v_mfma_f32_16x16x32_bf16 v[174:177], v[84:87], v[108:111], v[12:15]
	v_mfma_f32_16x16x32_bf16 v[12:15], v[88:91], v[104:107], 0
	v_mfma_f32_16x16x32_bf16 v[178:181], v[92:95], v[108:111], v[12:15]
	v_mfma_f32_16x16x32_bf16 v[12:15], v[80:83], v[112:115], 0
	v_mfma_f32_16x16x32_bf16 v[182:185], v[84:87], v[116:119], v[12:15]
	v_mfma_f32_16x16x32_bf16 v[12:15], v[88:91], v[112:115], 0
	v_mfma_f32_16x16x32_bf16 v[8:11], v[80:83], v[28:31], 0
	v_mfma_f32_16x16x32_bf16 v[190:193], v[92:95], v[116:119], v[12:15]
	v_mfma_f32_16x16x32_bf16 v[12:15], v[80:83], v[120:123], 0
	v_mfma_f32_16x16x32_bf16 v[8:11], v[84:87], v[44:47], v[8:11]
	v_mfma_f32_16x16x32_bf16 v[194:197], v[84:87], v[124:127], v[12:15]
	v_mfma_f32_16x16x32_bf16 v[12:15], v[88:91], v[120:123], 0
	v_mfma_f32_16x16x32_bf16 v[198:201], v[92:95], v[124:127], v[12:15]
	s_setprio 0
	s_add_i32 s3, 0, 0x18000
	s_nop 4
	v_add_u32_e32 v12, s3, v169
	s_barrier
	ds_read_b128 v[202:205], v12
	ds_read_b128 v[206:209], v12 offset:1024
	ds_read_b128 v[210:213], v12 offset:2048
	ds_read_b128 v[214:217], v12 offset:3072
	s_mov_b32 m0, s78
	v_lshl_add_u64 v[84:85], s[64:65], 0, v[132:133]
	ds_read_b128 v[12:15], v172 offset:32768
	ds_read_b128 v[28:31], v172 offset:33792
	ds_read_b128 v[44:47], v172 offset:34816
	ds_read_b128 v[80:83], v172 offset:35840
	ds_read_b128 v[104:107], v172 offset:36864
	ds_read_b128 v[112:115], v172 offset:37888
	ds_read_b128 v[218:221], v172 offset:38912
	ds_read_b128 v[222:225], v172 offset:39936
	global_load_lds_dwordx4 v[84:85], off
	v_lshl_add_u64 v[84:85], s[64:65], 0, v[136:137]
	s_mov_b32 m0, s79
	s_nop 0
	global_load_lds_dwordx4 v[84:85], off
	s_waitcnt lgkmcnt(8)
	s_barrier
	s_setprio 1
	s_waitcnt lgkmcnt(7)
	v_mfma_f32_16x16x32_bf16 v[48:51], v[202:205], v[12:15], v[48:51]
	s_waitcnt lgkmcnt(6)
	v_mfma_f32_16x16x32_bf16 v[120:123], v[206:209], v[28:31], v[48:51]
	v_mfma_f32_16x16x32_bf16 v[48:51], v[210:213], v[12:15], v[52:55]
	v_mfma_f32_16x16x32_bf16 v[92:95], v[214:217], v[28:31], v[48:51]
	s_waitcnt lgkmcnt(5)
	v_mfma_f32_16x16x32_bf16 v[48:51], v[202:205], v[44:47], v[56:59]
	s_waitcnt lgkmcnt(4)
	v_mfma_f32_16x16x32_bf16 v[124:127], v[206:209], v[80:83], v[48:51]
	v_mfma_f32_16x16x32_bf16 v[48:51], v[210:213], v[44:47], v[60:63]
	v_mfma_f32_16x16x32_bf16 v[88:91], v[214:217], v[80:83], v[48:51]
	s_waitcnt lgkmcnt(3)
	v_mfma_f32_16x16x32_bf16 v[48:51], v[202:205], v[104:107], v[64:67]
	s_waitcnt lgkmcnt(2)
	v_mfma_f32_16x16x32_bf16 v[116:119], v[206:209], v[112:115], v[48:51]
	v_mfma_f32_16x16x32_bf16 v[48:51], v[210:213], v[104:107], v[68:71]
	v_mfma_f32_16x16x32_bf16 v[84:87], v[214:217], v[112:115], v[48:51]
	s_waitcnt lgkmcnt(1)
	v_mfma_f32_16x16x32_bf16 v[48:51], v[202:205], v[218:221], v[72:75]
	s_waitcnt lgkmcnt(0)
	v_mfma_f32_16x16x32_bf16 v[108:111], v[206:209], v[222:225], v[48:51]
	v_mfma_f32_16x16x32_bf16 v[48:51], v[210:213], v[218:221], v[76:79]
	v_mfma_f32_16x16x32_bf16 v[76:79], v[214:217], v[222:225], v[48:51]
	s_setprio 0
	s_barrier
	s_add_i32 s29, 0, 0x1c000
	s_nop 3
	v_add_u32_e32 v48, s29, v169
	s_add_i32 s3, s3, s75
	ds_read_b128 v[226:229], v48
	ds_read_b128 v[230:233], v48 offset:1024
	ds_read_b128 v[234:237], v48 offset:2048
	ds_read_b128 v[238:241], v48 offset:3072
	v_lshl_add_u64 v[48:49], v[186:187], 0, s[8:9]
	s_mov_b32 m0, s3
	s_nop 0
	global_load_lds_dwordx4 v[48:49], off
	v_lshl_add_u64 v[48:49], v[242:243], 0, s[8:9]
	s_add_i32 m0, s3, 0x2000
	s_nop 0
	global_load_lds_dwordx4 v[48:49], off
	s_barrier
	s_setprio 1
	s_waitcnt lgkmcnt(3)
	v_mfma_f32_16x16x32_bf16 v[48:51], v[226:229], v[12:15], v[96:99]
	s_waitcnt lgkmcnt(1)
	v_mfma_f32_16x16x32_bf16 v[12:15], v[234:237], v[12:15], v[16:19]
	v_mfma_f32_16x16x32_bf16 v[60:63], v[230:233], v[28:31], v[48:51]
	s_waitcnt lgkmcnt(0)
	v_mfma_f32_16x16x32_bf16 v[28:31], v[238:241], v[28:31], v[12:15]
	v_mfma_f32_16x16x32_bf16 v[12:15], v[226:229], v[44:47], v[20:23]
	v_mfma_f32_16x16x32_bf16 v[56:59], v[230:233], v[80:83], v[12:15]
	v_mfma_f32_16x16x32_bf16 v[12:15], v[234:237], v[44:47], v[24:27]
	v_mfma_f32_16x16x32_bf16 v[24:27], v[238:241], v[80:83], v[12:15]
	v_mfma_f32_16x16x32_bf16 v[12:15], v[226:229], v[104:107], v[100:103]
	v_mfma_f32_16x16x32_bf16 v[52:55], v[230:233], v[112:115], v[12:15]
	v_mfma_f32_16x16x32_bf16 v[12:15], v[234:237], v[104:107], v[32:35]
	v_mfma_f32_16x16x32_bf16 v[20:23], v[238:241], v[112:115], v[12:15]
	v_mfma_f32_16x16x32_bf16 v[12:15], v[226:229], v[218:221], v[36:39]
	v_mfma_f32_16x16x32_bf16 v[44:47], v[230:233], v[222:225], v[12:15]
	v_mfma_f32_16x16x32_bf16 v[12:15], v[234:237], v[218:221], v[40:43]
	v_mfma_f32_16x16x32_bf16 v[12:15], v[238:241], v[222:225], v[12:15]
	s_setprio 0
	s_mov_b32 m0, s80
	v_lshl_add_u64 v[40:41], v[188:189], 0, s[8:9]
	s_barrier
	ds_read_b128 v[16:19], v172 offset:49152
	ds_read_b128 v[32:35], v172 offset:50176
	ds_read_b128 v[36:39], v172 offset:51200
	ds_read_b128 v[218:221], v172 offset:52224
	ds_read_b128 v[222:225], v172 offset:53248
	ds_read_b128 v[242:245], v172 offset:54272
	ds_read_b128 v[246:249], v172 offset:55296
	ds_read_b128 v[250:253], v172 offset:56320
	global_load_lds_dwordx4 v[40:41], off
	v_lshl_add_u64 v[40:41], v[140:141], 0, s[8:9]
	s_mov_b32 m0, s81
	s_nop 0
	global_load_lds_dwordx4 v[40:41], off
	s_barrier
; __device__ __forceinline__ float sigmoidf_(float x) { return __builtin_amdgcn_rcpf(1.0f + __expf(-x)); }
; #define PG8_STAGE(bufoff, gbase, voff) do { _Pragma("unroll") for (int _i = 0; _i < 2; ++_i) \
;         __builtin_amdgcn_global_load_lds((const unsigned*)((const char*)(gbase) + (voff)[_i]), (LAS unsigned*)(lds + (bufoff) + ldsw + _i * 8192), 16, 0, 0); } while (0)
; #define PG8_MMA(ai, bj, At, Bt) do { __builtin_amdgcn_s_setprio(1); _Pragma("unroll") for (int m = 0; m < 4; ++m) _Pragma("unroll") for (int n = 0; n < 2; ++n) _Pragma("unroll") for (int k = 0; k < 2; ++k) \
;         acc[ai][bj][m][n] = __builtin_amdgcn_mfma_f32_16x16x32_bf16(Bt[n][k], At[m][k], acc[ai][bj][m][n], 0, 0, 0); __builtin_amdgcn_s_setprio(0); } while (0)
; #define PG8_WAIT_V(n) asm volatile("s_waitcnt vmcnt(" #n ")" ::: "memory")
; #define PG8_WAIT_L(n) asm volatile("s_waitcnt lgkmcnt(" #n ")" ::: "memory")
; #define PG8_BAR __builtin_amdgcn_s_barrier()
; #define PG8_SCHED __builtin_amdgcn_sched_barrier(0)
; template <class Epi>
; __device__ __forceinline__ void gemm_phase(LAS unsigned char* lds, const Gemm g, const StaticOrder& S, const Epi& E) {
;     ...
;             PG8_BAR; PG8_WAIT_L(0); PG8_MMA(1, 0, At, B0); PG8_BAR; PG8_SCHED;
;             PG8_STAGE(PG8_SB(1, 1), b3 + hstepB, voffB);
;             PG8_WAIT_V(6); PG8_BAR; PG8_MMA(1, 1, At, B1); PG8_BAR;
;     __device__ __forceinline__ void operator()(const AccT& acc, const Unit& u, int wr, int wc, int fr, int fq) const {
;     ...
;         } else {
; #pragma unroll
;             for (int bj = 0; bj < 2; ++bj)
; #pragma unroll
;                 for (int n = 0; n < 2; ++n) { const int col = col0 - 1024 + bj * 128 + n * 16; const f32x4 av0 = *(const f32x4*)(a0 + col);
; #pragma unroll
;                     for (int ai = 0; ai < 2; ++ai)
; #pragma unroll
;                         for (int m = 0; m < 4; ++m) { const int row = row0 + ai * 128 + m * 16; f32x4 o;
; #pragma unroll
;                             for (int j = 0; j < 4; ++j) o[j] = sigmoidf_(av0[j] + acc[ai][bj][m][n][j]);
;                             *(f32x4*)(IC + (size_t)row * RW + col) = o; asm volatile("" ::: "memory"); } }
	s_waitcnt lgkmcnt(0)
	s_setprio 1
	s_waitcnt lgkmcnt(0)
	v_mfma_f32_16x16x32_bf16 v[40:43], v[202:205], v[16:19], v[128:131]
	s_add_u32 s60, s60, 0x8080
	s_addc_u32 s61, s61, 0
	v_mfma_f32_16x16x32_bf16 v[112:115], v[206:209], v[32:35], v[40:43]
	v_mfma_f32_16x16x32_bf16 v[40:43], v[210:213], v[16:19], v[144:147]
	v_mfma_f32_16x16x32_bf16 v[80:83], v[214:217], v[32:35], v[40:43]
	v_mfma_f32_16x16x32_bf16 v[40:43], v[202:205], v[36:39], v[148:151]
	v_mfma_f32_16x16x32_bf16 v[104:107], v[206:209], v[218:221], v[40:43]
	v_mfma_f32_16x16x32_bf16 v[40:43], v[210:213], v[36:39], v[152:155]
	v_mfma_f32_16x16x32_bf16 v[72:75], v[214:217], v[218:221], v[40:43]
	v_mfma_f32_16x16x32_bf16 v[40:43], v[202:205], v[222:225], v[156:159]
	v_mfma_f32_16x16x32_bf16 v[0:3], v[202:205], v[246:249], v[0:3]
	v_mfma_f32_16x16x32_bf16 v[100:103], v[206:209], v[242:245], v[40:43]
	v_mfma_f32_16x16x32_bf16 v[40:43], v[210:213], v[222:225], v[160:163]
	v_mfma_f32_16x16x32_bf16 v[96:99], v[206:209], v[250:253], v[0:3]
	v_mfma_f32_16x16x32_bf16 v[0:3], v[210:213], v[246:249], v[4:7]
	v_mfma_f32_16x16x32_bf16 v[68:71], v[214:217], v[242:245], v[40:43]
	v_mfma_f32_16x16x32_bf16 v[64:67], v[214:217], v[250:253], v[0:3]
	s_setprio 0
	s_barrier
	s_add_i32 s3, s29, s75
	s_nop 2
	v_lshl_add_u64 v[0:1], s[60:61], 0, v[134:135]
	s_mov_b32 m0, s3
	s_nop 0
	global_load_lds_dwordx4 v[0:1], off
	v_lshl_add_u64 v[0:1], s[60:61], 0, v[138:139]
	s_add_i32 m0, s3, 0x2000
	s_nop 0
	global_load_lds_dwordx4 v[0:1], off
	s_waitcnt vmcnt(6)
	s_barrier
	s_setprio 1
	v_mfma_f32_16x16x32_bf16 v[0:3], v[226:229], v[16:19], v[8:11]
	v_mfma_f32_16x16x32_bf16 v[48:51], v[230:233], v[32:35], v[0:3]
	v_mfma_f32_16x16x32_bf16 v[0:3], v[234:237], v[16:19], v[164:167]
	v_mfma_f32_16x16x32_bf16 v[16:19], v[238:241], v[32:35], v[0:3]
	v_mfma_f32_16x16x32_bf16 v[0:3], v[226:229], v[36:39], v[174:177]
	v_mfma_f32_16x16x32_bf16 v[40:43], v[230:233], v[218:221], v[0:3]
	v_mfma_f32_16x16x32_bf16 v[0:3], v[234:237], v[36:39], v[178:181]
	v_mfma_f32_16x16x32_bf16 v[8:11], v[238:241], v[218:221], v[0:3]
	v_mfma_f32_16x16x32_bf16 v[0:3], v[226:229], v[222:225], v[182:185]
	v_mfma_f32_16x16x32_bf16 v[36:39], v[230:233], v[242:245], v[0:3]
	v_mfma_f32_16x16x32_bf16 v[0:3], v[234:237], v[222:225], v[190:193]
	v_mfma_f32_16x16x32_bf16 v[4:7], v[238:241], v[242:245], v[0:3]
	v_mfma_f32_16x16x32_bf16 v[0:3], v[226:229], v[246:249], v[194:197]
	v_mfma_f32_16x16x32_bf16 v[32:35], v[230:233], v[250:253], v[0:3]
	v_mfma_f32_16x16x32_bf16 v[0:3], v[234:237], v[246:249], v[198:201]
	v_mfma_f32_16x16x32_bf16 v[0:3], v[238:241], v[250:253], v[0:3]
	s_setprio 0
	v_lshl_add_u32 v150, s44, 8, v168
	v_lshl_or_b32 v152, s91, 8, v170
	v_or_b32_e32 v148, 16, v150
	v_or_b32_e32 v146, 32, v150
	v_or_b32_e32 v144, 48, v150
	s_mov_b64 s[44:45], -1
	s_cmp_lt_i32 s91, 4
	v_ashrrev_i32_e32 v153, 31, v152
	v_ashrrev_i32_e32 v151, 31, v150
	v_ashrrev_i32_e32 v149, 31, v148
	v_ashrrev_i32_e32 v147, 31, v146
	v_ashrrev_i32_e32 v145, 31, v144
	s_barrier
	s_cbranch_scc1 .LBB0_354
	v_lshlrev_b64 v[140:141], 2, v[152:153]
	v_lshl_add_u64 v[156:157], s[36:37], 0, v[140:141]
	global_load_dwordx4 v[128:131], v[156:157], off offset:-4096
	v_lshlrev_b64 v[154:155], 12, v[150:151]
	v_lshlrev_b64 v[160:161], 12, v[146:147]
	v_lshl_add_u64 v[154:155], s[6:7], 0, v[154:155]
	v_lshl_add_u64 v[162:163], s[6:7], 0, v[160:161]
	v_lshl_add_u64 v[160:161], v[154:155], 0, v[140:141]
	v_lshl_add_u64 v[154:155], v[162:163], 0, v[140:141]
	v_lshlrev_b64 v[158:159], 12, v[148:149]
	v_lshl_add_u64 v[158:159], s[6:7], 0, v[158:159]
	v_lshl_add_u64 v[158:159], v[158:159], 0, v[140:141]
	s_mov_b64 s[44:45], 0
	s_waitcnt vmcnt(0)
	v_add_f32_e32 v162, v120, v128
	v_add_f32_e32 v163, v121, v129
	v_add_f32_e32 v164, v122, v130
	v_add_f32_e32 v165, v123, v131
	v_mul_f32_e32 v162, 0xbfb8aa3b, v162
	v_mul_f32_e32 v163, 0xbfb8aa3b, v163
	v_mul_f32_e32 v164, 0xbfb8aa3b, v164
	v_mul_f32_e32 v165, 0xbfb8aa3b, v165
	v_exp_f32_e32 v162, v162
	v_exp_f32_e32 v163, v163
	v_exp_f32_e32 v164, v164
	v_exp_f32_e32 v165, v165
	v_add_f32_e32 v162, 1.0, v162
	v_add_f32_e32 v163, 1.0, v163
	v_add_f32_e32 v164, 1.0, v164
	v_add_f32_e32 v165, 1.0, v165
	v_rcp_f32_e32 v162, v162
	v_rcp_f32_e32 v163, v163
	v_rcp_f32_e32 v164, v164
	v_rcp_f32_e32 v165, v165
	v_add_f32_e32 v166, v124, v128
	v_add_f32_e32 v167, v125, v129
	v_add_f32_e32 v174, v126, v130
	v_add_f32_e32 v175, v127, v131
	v_add_f32_e32 v176, v116, v128
	v_add_f32_e32 v177, v117, v129
	v_mul_f32_e32 v166, 0xbfb8aa3b, v166
	v_mul_f32_e32 v167, 0xbfb8aa3b, v167
	v_mul_f32_e32 v174, 0xbfb8aa3b, v174
	v_mul_f32_e32 v175, 0xbfb8aa3b, v175
	v_mul_f32_e32 v176, 0xbfb8aa3b, v176
	v_mul_f32_e32 v177, 0xbfb8aa3b, v177
	v_exp_f32_e32 v166, v166
	v_exp_f32_e32 v167, v167
	v_exp_f32_e32 v174, v174
	v_exp_f32_e32 v175, v175
	global_store_dwordx4 v[160:161], v[162:165], off offset:-4096
	v_exp_f32_e32 v176, v176
	v_exp_f32_e32 v177, v177
	v_lshlrev_b64 v[162:163], 12, v[144:145]
	v_lshl_add_u64 v[162:163], s[6:7], 0, v[162:163]
	v_lshl_add_u64 v[162:163], v[162:163], 0, v[140:141]
	v_add_f32_e32 v140, v112, v128
	v_mul_f32_e32 v140, 0xbfb8aa3b, v140
	v_add_f32_e32 v141, v113, v129
	v_add_f32_e32 v166, 1.0, v166
	v_add_f32_e32 v167, 1.0, v167
	v_add_f32_e32 v184, 1.0, v174
	v_add_f32_e32 v185, 1.0, v175
	v_exp_f32_e32 v140, v140
	v_mul_f32_e32 v141, 0xbfb8aa3b, v141
	v_add_f32_e32 v186, 1.0, v176
	v_add_f32_e32 v187, 1.0, v177
	v_rcp_f32_e32 v174, v166
	v_rcp_f32_e32 v175, v167
	v_rcp_f32_e32 v176, v184
	v_rcp_f32_e32 v177, v185
	v_exp_f32_e32 v141, v141
	v_add_f32_e32 v140, 1.0, v140
	global_store_dwordx4 v[158:159], v[174:177], off offset:-4096
; __device__ __forceinline__ float sigmoidf_(float x) { return __builtin_amdgcn_rcpf(1.0f + __expf(-x)); }
;     __device__ __forceinline__ void operator()(const AccT& acc, const Unit& u, int wr, int wc, int fr, int fq) const {
;     ...
;             for (int bj = 0; bj < 2; ++bj)
; #pragma unroll
;                 for (int n = 0; n < 2; ++n) { const int col = col0 - 1024 + bj * 128 + n * 16; const f32x4 av0 = *(const f32x4*)(a0 + col);
; #pragma unroll
;                     for (int ai = 0; ai < 2; ++ai)
; #pragma unroll
;                         for (int m = 0; m < 4; ++m) { const int row = row0 + ai * 128 + m * 16; f32x4 o;
; #pragma unroll
;                             for (int j = 0; j < 4; ++j) o[j] = sigmoidf_(av0[j] + acc[ai][bj][m][n][j]);
;                             *(f32x4*)(IC + (size_t)row * RW + col) = o; asm volatile("" ::: "memory"); } }
	v_add_f32_e32 v164, v115, v131
	v_mul_f32_e32 v164, 0xbfb8aa3b, v164
	v_rcp_f32_e32 v174, v140
	v_add_f32_e32 v140, 1.0, v141
	v_add_f32_e32 v141, v114, v130
	v_mul_f32_e32 v141, 0xbfb8aa3b, v141
	v_exp_f32_e32 v141, v141
	v_exp_f32_e32 v164, v164
	v_add_f32_e32 v178, v118, v130
	v_add_f32_e32 v179, v119, v131
	v_add_f32_e32 v180, v108, v128
	v_add_f32_e32 v181, v109, v129
	v_mul_f32_e32 v178, 0xbfb8aa3b, v178
	v_mul_f32_e32 v179, 0xbfb8aa3b, v179
	v_mul_f32_e32 v180, 0xbfb8aa3b, v180
	v_mul_f32_e32 v181, 0xbfb8aa3b, v181
	v_exp_f32_e32 v178, v178
	v_exp_f32_e32 v179, v179
	v_rcp_f32_e32 v175, v140
	v_add_f32_e32 v140, 1.0, v141
	v_exp_f32_e32 v180, v180
	v_exp_f32_e32 v181, v181
	v_rcp_f32_e32 v176, v140
	v_add_f32_e32 v140, 1.0, v164
	v_rcp_f32_e32 v177, v140
	v_add_f32_e32 v140, v104, v128
	v_mul_f32_e32 v140, 0xbfb8aa3b, v140
	v_add_f32_e32 v141, v105, v129
	v_add_f32_e32 v188, 1.0, v178
	v_add_f32_e32 v189, 1.0, v179
	v_exp_f32_e32 v140, v140
	v_mul_f32_e32 v141, 0xbfb8aa3b, v141
	v_add_f32_e32 v190, 1.0, v180
	v_add_f32_e32 v191, 1.0, v181
	v_rcp_f32_e32 v178, v186
	v_rcp_f32_e32 v179, v187
	v_rcp_f32_e32 v180, v188
	v_rcp_f32_e32 v181, v189
	v_exp_f32_e32 v141, v141
	v_add_f32_e32 v140, 1.0, v140
	global_store_dwordx4 v[154:155], v[178:181], off offset:-4096
	v_add_f32_e32 v164, v107, v131
	v_mul_f32_e32 v164, 0xbfb8aa3b, v164
	v_rcp_f32_e32 v178, v140
	v_add_f32_e32 v140, 1.0, v141
	v_add_f32_e32 v141, v106, v130
	v_mul_f32_e32 v141, 0xbfb8aa3b, v141
	v_exp_f32_e32 v141, v141
	v_add_f32_e32 v182, v110, v130
	v_add_f32_e32 v183, v111, v131
	v_exp_f32_e32 v164, v164
	v_mul_f32_e32 v182, 0xbfb8aa3b, v182
	v_mul_f32_e32 v183, 0xbfb8aa3b, v183
	v_exp_f32_e32 v182, v182
	v_exp_f32_e32 v183, v183
	v_rcp_f32_e32 v179, v140
	v_add_f32_e32 v140, 1.0, v141
	v_rcp_f32_e32 v180, v140
	v_add_f32_e32 v140, 1.0, v164
	v_rcp_f32_e32 v181, v140
	v_add_f32_e32 v140, v100, v128
	v_add_f32_e32 v192, 1.0, v182
	v_add_f32_e32 v193, 1.0, v183
	v_mul_f32_e32 v140, 0xbfb8aa3b, v140
	v_add_f32_e32 v141, v101, v129
	v_rcp_f32_e32 v182, v190
	v_rcp_f32_e32 v183, v191
	v_rcp_f32_e32 v184, v192
	v_rcp_f32_e32 v185, v193
	v_exp_f32_e32 v140, v140
	v_mul_f32_e32 v141, 0xbfb8aa3b, v141
	v_exp_f32_e32 v141, v141
	global_store_dwordx4 v[162:163], v[182:185], off offset:-4096
	v_lshl_add_u64 v[166:167], v[160:161], 0, s[16:17]
	v_add_f32_e32 v140, 1.0, v140
	global_store_dwordx4 v[166:167], v[174:177], off offset:-4096
	v_add_f32_e32 v128, v96, v128
	v_mul_f32_e32 v128, 0xbfb8aa3b, v128
	v_rcp_f32_e32 v174, v140
	v_add_f32_e32 v140, 1.0, v141
	v_add_f32_e32 v141, v102, v130
	v_mul_f32_e32 v141, 0xbfb8aa3b, v141
	v_add_f32_e32 v175, v103, v131
	v_exp_f32_e32 v141, v141
	v_mul_f32_e32 v175, 0xbfb8aa3b, v175
	v_exp_f32_e32 v177, v175
	v_rcp_f32_e32 v175, v140
	v_add_f32_e32 v140, 1.0, v141
	v_rcp_f32_e32 v176, v140
	v_add_f32_e32 v140, 1.0, v177
	v_add_f32_e32 v130, v98, v130
	v_rcp_f32_e32 v177, v140
	v_exp_f32_e32 v140, v128
	v_add_f32_e32 v128, v97, v129
	v_mul_f32_e32 v130, 0xbfb8aa3b, v130
	v_add_f32_e32 v131, v99, v131
	v_mul_f32_e32 v128, 0xbfb8aa3b, v128
	v_exp_f32_e32 v130, v130
	v_mul_f32_e32 v131, 0xbfb8aa3b, v131
	v_exp_f32_e32 v141, v128
	v_exp_f32_e32 v131, v131
	v_lshl_add_u64 v[164:165], v[160:161], 0, s[18:19]
	v_add_f32_e32 v140, 1.0, v140
	v_add_f32_e32 v130, 1.0, v130
	global_store_dwordx4 v[164:165], v[178:181], off offset:-4096
	v_lshl_add_u64 v[128:129], v[160:161], 0, s[20:21]
	global_store_dwordx4 v[128:129], v[174:177], off offset:-4096
	v_rcp_f32_e32 v178, v140
	v_add_f32_e32 v140, 1.0, v141
	v_rcp_f32_e32 v180, v130
	v_add_f32_e32 v130, 1.0, v131
	v_rcp_f32_e32 v179, v140
	v_rcp_f32_e32 v181, v130
	v_lshl_add_u64 v[130:131], v[160:161], 0, s[22:23]
	global_store_dwordx4 v[130:131], v[178:181], off offset:-4096
	global_load_dwordx4 v[174:177], v[156:157], off offset:-4032
	s_waitcnt vmcnt(0)
	v_add_f32_e32 v140, v92, v174
	v_mul_f32_e32 v140, 0xbfb8aa3b, v140
	v_add_f32_e32 v141, v93, v175
	v_exp_f32_e32 v140, v140
	v_mul_f32_e32 v141, 0xbfb8aa3b, v141
	v_exp_f32_e32 v141, v141
	v_add_f32_e32 v179, v95, v177
	v_add_f32_e32 v140, 1.0, v140
	v_rcp_f32_e32 v178, v140
	v_add_f32_e32 v140, 1.0, v141
	v_add_f32_e32 v141, v94, v176
	v_mul_f32_e32 v141, 0xbfb8aa3b, v141
	v_exp_f32_e32 v141, v141
	v_mul_f32_e32 v179, 0xbfb8aa3b, v179
	v_exp_f32_e32 v181, v179
	v_rcp_f32_e32 v179, v140
	v_add_f32_e32 v140, 1.0, v141
	v_add_f32_e32 v141, v88, v174
	v_rcp_f32_e32 v180, v140
	v_add_f32_e32 v140, 1.0, v181
	v_mul_f32_e32 v141, 0xbfb8aa3b, v141
	v_add_f32_e32 v181, v89, v175
	v_exp_f32_e32 v141, v141
	v_mul_f32_e32 v181, 0xbfb8aa3b, v181
	v_exp_f32_e32 v183, v181
	v_rcp_f32_e32 v181, v140
	v_add_f32_e32 v140, 1.0, v141
	v_add_f32_e32 v141, v90, v176
	v_rcp_f32_e32 v182, v140
	v_add_f32_e32 v140, 1.0, v183
	v_mul_f32_e32 v141, 0xbfb8aa3b, v141
	v_add_f32_e32 v183, v91, v177
	v_exp_f32_e32 v141, v141
	v_mul_f32_e32 v183, 0xbfb8aa3b, v183
	v_exp_f32_e32 v185, v183
	v_rcp_f32_e32 v183, v140
	v_add_f32_e32 v140, 1.0, v141
	v_rcp_f32_e32 v184, v140
	v_add_f32_e32 v140, 1.0, v185
	v_rcp_f32_e32 v185, v140
	v_add_f32_e32 v140, v84, v174
	v_mul_f32_e32 v140, 0xbfb8aa3b, v140
	v_add_f32_e32 v141, v85, v175
	v_exp_f32_e32 v140, v140
	v_mul_f32_e32 v141, 0xbfb8aa3b, v141
	v_exp_f32_e32 v141, v141
	global_store_dwordx4 v[160:161], v[178:181], off offset:-4032
	v_add_f32_e32 v140, 1.0, v140
	global_store_dwordx4 v[158:159], v[182:185], off offset:-4032
	v_rcp_f32_e32 v178, v140
	v_add_f32_e32 v140, 1.0, v141
	v_add_f32_e32 v141, v86, v176
	v_mul_f32_e32 v141, 0xbfb8aa3b, v141
	v_add_f32_e32 v179, v87, v177
	v_exp_f32_e32 v141, v141
	v_mul_f32_e32 v179, 0xbfb8aa3b, v179
; __device__ __forceinline__ float sigmoidf_(float x) { return __builtin_amdgcn_rcpf(1.0f + __expf(-x)); }
;     __device__ __forceinline__ void operator()(const AccT& acc, const Unit& u, int wr, int wc, int fr, int fq) const {
;     ...
;             for (int bj = 0; bj < 2; ++bj)
; #pragma unroll
;                 for (int n = 0; n < 2; ++n) { const int col = col0 - 1024 + bj * 128 + n * 16; const f32x4 av0 = *(const f32x4*)(a0 + col);
; #pragma unroll
;                     for (int ai = 0; ai < 2; ++ai)
; #pragma unroll
;                         for (int m = 0; m < 4; ++m) { const int row = row0 + ai * 128 + m * 16; f32x4 o;
; #pragma unroll
;                             for (int j = 0; j < 4; ++j) o[j] = sigmoidf_(av0[j] + acc[ai][bj][m][n][j]);
;                             *(f32x4*)(IC + (size_t)row * RW + col) = o; asm volatile("" ::: "memory"); } }
	v_exp_f32_e32 v181, v179
	v_rcp_f32_e32 v179, v140
	v_add_f32_e32 v140, 1.0, v141
	v_rcp_f32_e32 v180, v140
	v_add_f32_e32 v140, 1.0, v181
	v_rcp_f32_e32 v181, v140
	v_add_f32_e32 v140, v76, v174
	v_mul_f32_e32 v140, 0xbfb8aa3b, v140
	v_add_f32_e32 v141, v77, v175
	v_exp_f32_e32 v140, v140
	v_mul_f32_e32 v141, 0xbfb8aa3b, v141
	v_exp_f32_e32 v141, v141
	v_add_f32_e32 v140, 1.0, v140
	global_store_dwordx4 v[154:155], v[178:181], off offset:-4032
	s_nop 1
	v_rcp_f32_e32 v178, v140
	v_add_f32_e32 v140, 1.0, v141
	v_add_f32_e32 v141, v78, v176
	v_mul_f32_e32 v141, 0xbfb8aa3b, v141
	v_add_f32_e32 v179, v79, v177
	v_exp_f32_e32 v141, v141
	v_mul_f32_e32 v179, 0xbfb8aa3b, v179
	v_exp_f32_e32 v181, v179
	v_rcp_f32_e32 v179, v140
	v_add_f32_e32 v140, 1.0, v141
	v_add_f32_e32 v141, v80, v174
	v_rcp_f32_e32 v180, v140
	v_add_f32_e32 v140, 1.0, v181
	v_mul_f32_e32 v141, 0xbfb8aa3b, v141
	v_add_f32_e32 v181, v81, v175
	v_exp_f32_e32 v141, v141
	v_mul_f32_e32 v181, 0xbfb8aa3b, v181
	v_exp_f32_e32 v183, v181
	v_rcp_f32_e32 v181, v140
	v_add_f32_e32 v140, 1.0, v141
	v_add_f32_e32 v141, v82, v176
	v_rcp_f32_e32 v182, v140
	v_add_f32_e32 v140, 1.0, v183
	v_mul_f32_e32 v141, 0xbfb8aa3b, v141
	v_add_f32_e32 v183, v83, v177
	v_exp_f32_e32 v141, v141
	v_mul_f32_e32 v183, 0xbfb8aa3b, v183
	v_exp_f32_e32 v185, v183
	v_rcp_f32_e32 v183, v140
	v_add_f32_e32 v140, 1.0, v141
	v_rcp_f32_e32 v184, v140
	v_add_f32_e32 v140, 1.0, v185
	v_rcp_f32_e32 v185, v140
	v_add_f32_e32 v140, v72, v174
	v_mul_f32_e32 v140, 0xbfb8aa3b, v140
	v_add_f32_e32 v141, v73, v175
	v_exp_f32_e32 v140, v140
	v_mul_f32_e32 v141, 0xbfb8aa3b, v141
	v_exp_f32_e32 v141, v141
	global_store_dwordx4 v[162:163], v[178:181], off offset:-4032
	v_add_f32_e32 v140, 1.0, v140
	global_store_dwordx4 v[166:167], v[182:185], off offset:-4032
	v_rcp_f32_e32 v178, v140
	v_add_f32_e32 v140, 1.0, v141
	v_add_f32_e32 v141, v74, v176
	v_mul_f32_e32 v141, 0xbfb8aa3b, v141
	v_add_f32_e32 v179, v75, v177
	v_exp_f32_e32 v141, v141
	v_mul_f32_e32 v179, 0xbfb8aa3b, v179
	v_exp_f32_e32 v181, v179
	v_rcp_f32_e32 v179, v140
	v_add_f32_e32 v140, 1.0, v141
	v_rcp_f32_e32 v180, v140
	v_add_f32_e32 v140, 1.0, v181
	v_rcp_f32_e32 v181, v140
	v_add_f32_e32 v140, v68, v174
	v_mul_f32_e32 v140, 0xbfb8aa3b, v140
	v_add_f32_e32 v141, v69, v175
	v_exp_f32_e32 v140, v140
	v_mul_f32_e32 v141, 0xbfb8aa3b, v141
	v_exp_f32_e32 v141, v141
	v_add_f32_e32 v140, 1.0, v140
	global_store_dwordx4 v[164:165], v[178:181], off offset:-4032
	s_nop 1
	v_rcp_f32_e32 v178, v140
	v_add_f32_e32 v140, 1.0, v141
	v_add_f32_e32 v141, v70, v176
	v_mul_f32_e32 v141, 0xbfb8aa3b, v141
	v_exp_f32_e32 v141, v141
	v_add_f32_e32 v179, v71, v177
	v_mul_f32_e32 v179, 0xbfb8aa3b, v179
	v_exp_f32_e32 v181, v179
	v_rcp_f32_e32 v179, v140
	v_add_f32_e32 v140, 1.0, v141
	v_add_f32_e32 v141, v64, v174
	v_mul_f32_e32 v141, 0xbfb8aa3b, v141
	v_add_f32_e32 v174, v65, v175
	v_exp_f32_e32 v141, v141
	v_mul_f32_e32 v174, 0xbfb8aa3b, v174
	v_exp_f32_e32 v175, v174
	v_rcp_f32_e32 v180, v140
	v_add_f32_e32 v140, 1.0, v181
	v_rcp_f32_e32 v181, v140
	v_add_f32_e32 v140, 1.0, v141
	v_add_f32_e32 v141, v66, v176
	v_rcp_f32_e32 v174, v140
	v_add_f32_e32 v140, 1.0, v175
	v_mul_f32_e32 v141, 0xbfb8aa3b, v141
	v_add_f32_e32 v175, v67, v177
	v_exp_f32_e32 v141, v141
	v_mul_f32_e32 v175, 0xbfb8aa3b, v175
	v_exp_f32_e32 v177, v175
	v_rcp_f32_e32 v175, v140
	v_add_f32_e32 v140, 1.0, v141
	v_rcp_f32_e32 v176, v140
	v_add_f32_e32 v140, 1.0, v177
	v_rcp_f32_e32 v177, v140
	global_store_dwordx4 v[128:129], v[178:181], off offset:-4032
	global_store_dwordx4 v[130:131], v[174:177], off offset:-4032
	global_load_dwordx4 v[174:177], v[156:157], off offset:-3584
	s_waitcnt vmcnt(0)
	v_add_f32_e32 v140, v60, v174
	v_mul_f32_e32 v140, 0xbfb8aa3b, v140
	v_add_f32_e32 v141, v61, v175
	v_exp_f32_e32 v140, v140
	v_mul_f32_e32 v141, 0xbfb8aa3b, v141
	v_exp_f32_e32 v141, v141
	v_add_f32_e32 v179, v63, v177
	v_add_f32_e32 v140, 1.0, v140
	v_rcp_f32_e32 v178, v140
	v_add_f32_e32 v140, 1.0, v141
	v_add_f32_e32 v141, v62, v176
	v_mul_f32_e32 v141, 0xbfb8aa3b, v141
	v_exp_f32_e32 v141, v141
	v_mul_f32_e32 v179, 0xbfb8aa3b, v179
	v_exp_f32_e32 v181, v179
	v_rcp_f32_e32 v179, v140
	v_add_f32_e32 v140, 1.0, v141
	v_add_f32_e32 v141, v56, v174
	v_rcp_f32_e32 v180, v140
	v_add_f32_e32 v140, 1.0, v181
	v_mul_f32_e32 v141, 0xbfb8aa3b, v141
	v_add_f32_e32 v181, v57, v175
	v_exp_f32_e32 v141, v141
	v_mul_f32_e32 v181, 0xbfb8aa3b, v181
	v_exp_f32_e32 v183, v181
	v_rcp_f32_e32 v181, v140
	v_add_f32_e32 v140, 1.0, v141
	v_add_f32_e32 v141, v58, v176
	v_rcp_f32_e32 v182, v140
	v_add_f32_e32 v140, 1.0, v183
	v_mul_f32_e32 v141, 0xbfb8aa3b, v141
	v_add_f32_e32 v183, v59, v177
	v_exp_f32_e32 v141, v141
	v_mul_f32_e32 v183, 0xbfb8aa3b, v183
	v_exp_f32_e32 v185, v183
	v_rcp_f32_e32 v183, v140
	v_add_f32_e32 v140, 1.0, v141
	v_rcp_f32_e32 v184, v140
	v_add_f32_e32 v140, 1.0, v185
	v_rcp_f32_e32 v185, v140
	v_add_f32_e32 v140, v52, v174
	v_mul_f32_e32 v140, 0xbfb8aa3b, v140
	v_add_f32_e32 v141, v53, v175
	v_exp_f32_e32 v140, v140
	v_mul_f32_e32 v141, 0xbfb8aa3b, v141
	v_exp_f32_e32 v141, v141
	global_store_dwordx4 v[160:161], v[178:181], off offset:-3584
	v_add_f32_e32 v140, 1.0, v140
	global_store_dwordx4 v[158:159], v[182:185], off offset:-3584
	v_rcp_f32_e32 v178, v140
	v_add_f32_e32 v140, 1.0, v141
	v_add_f32_e32 v141, v54, v176
	v_mul_f32_e32 v141, 0xbfb8aa3b, v141
	v_add_f32_e32 v179, v55, v177
	v_exp_f32_e32 v141, v141
	v_mul_f32_e32 v179, 0xbfb8aa3b, v179
	v_exp_f32_e32 v181, v179
	v_rcp_f32_e32 v179, v140
	v_add_f32_e32 v140, 1.0, v141
	v_rcp_f32_e32 v180, v140
	v_add_f32_e32 v140, 1.0, v181
	v_rcp_f32_e32 v181, v140
; __device__ __forceinline__ float sigmoidf_(float x) { return __builtin_amdgcn_rcpf(1.0f + __expf(-x)); }
;     __device__ __forceinline__ void operator()(const AccT& acc, const Unit& u, int wr, int wc, int fr, int fq) const {
;     ...
;             for (int bj = 0; bj < 2; ++bj)
; #pragma unroll
;                 for (int n = 0; n < 2; ++n) { const int col = col0 - 1024 + bj * 128 + n * 16; const f32x4 av0 = *(const f32x4*)(a0 + col);
; #pragma unroll
;                     for (int ai = 0; ai < 2; ++ai)
; #pragma unroll
;                         for (int m = 0; m < 4; ++m) { const int row = row0 + ai * 128 + m * 16; f32x4 o;
; #pragma unroll
;                             for (int j = 0; j < 4; ++j) o[j] = sigmoidf_(av0[j] + acc[ai][bj][m][n][j]);
;                             *(f32x4*)(IC + (size_t)row * RW + col) = o; asm volatile("" ::: "memory"); } }
	v_add_f32_e32 v140, v44, v174
	v_mul_f32_e32 v140, 0xbfb8aa3b, v140
	v_add_f32_e32 v141, v45, v175
	v_exp_f32_e32 v140, v140
	v_mul_f32_e32 v141, 0xbfb8aa3b, v141
	v_exp_f32_e32 v141, v141
	v_add_f32_e32 v140, 1.0, v140
	global_store_dwordx4 v[154:155], v[178:181], off offset:-3584
	s_nop 1
	v_rcp_f32_e32 v178, v140
	v_add_f32_e32 v140, 1.0, v141
	v_add_f32_e32 v141, v46, v176
	v_mul_f32_e32 v141, 0xbfb8aa3b, v141
	v_add_f32_e32 v179, v47, v177
	v_exp_f32_e32 v141, v141
	v_mul_f32_e32 v179, 0xbfb8aa3b, v179
	v_exp_f32_e32 v181, v179
	v_rcp_f32_e32 v179, v140
	v_add_f32_e32 v140, 1.0, v141
	v_add_f32_e32 v141, v48, v174
	v_rcp_f32_e32 v180, v140
	v_add_f32_e32 v140, 1.0, v181
	v_mul_f32_e32 v141, 0xbfb8aa3b, v141
	v_add_f32_e32 v181, v49, v175
	v_exp_f32_e32 v141, v141
	v_mul_f32_e32 v181, 0xbfb8aa3b, v181
	v_exp_f32_e32 v183, v181
	v_rcp_f32_e32 v181, v140
	v_add_f32_e32 v140, 1.0, v141
	v_add_f32_e32 v141, v50, v176
	v_rcp_f32_e32 v182, v140
	v_add_f32_e32 v140, 1.0, v183
	v_mul_f32_e32 v141, 0xbfb8aa3b, v141
	v_add_f32_e32 v183, v51, v177
	v_exp_f32_e32 v141, v141
	v_mul_f32_e32 v183, 0xbfb8aa3b, v183
	v_exp_f32_e32 v185, v183
	v_rcp_f32_e32 v183, v140
	v_add_f32_e32 v140, 1.0, v141
	v_rcp_f32_e32 v184, v140
	v_add_f32_e32 v140, 1.0, v185
	v_rcp_f32_e32 v185, v140
	v_add_f32_e32 v140, v40, v174
	v_mul_f32_e32 v140, 0xbfb8aa3b, v140
	v_add_f32_e32 v141, v41, v175
	v_exp_f32_e32 v140, v140
	v_mul_f32_e32 v141, 0xbfb8aa3b, v141
	v_exp_f32_e32 v141, v141
	global_store_dwordx4 v[162:163], v[178:181], off offset:-3584
	v_add_f32_e32 v140, 1.0, v140
	global_store_dwordx4 v[166:167], v[182:185], off offset:-3584
	v_rcp_f32_e32 v178, v140
	v_add_f32_e32 v140, 1.0, v141
	v_add_f32_e32 v141, v42, v176
	v_mul_f32_e32 v141, 0xbfb8aa3b, v141
	v_add_f32_e32 v179, v43, v177
	v_exp_f32_e32 v141, v141
	v_mul_f32_e32 v179, 0xbfb8aa3b, v179
	v_exp_f32_e32 v181, v179
	v_rcp_f32_e32 v179, v140
	v_add_f32_e32 v140, 1.0, v141
	v_rcp_f32_e32 v180, v140
	v_add_f32_e32 v140, 1.0, v181
	v_rcp_f32_e32 v181, v140
	v_add_f32_e32 v140, v36, v174
	v_mul_f32_e32 v140, 0xbfb8aa3b, v140
	v_add_f32_e32 v141, v37, v175
	v_exp_f32_e32 v140, v140
	v_mul_f32_e32 v141, 0xbfb8aa3b, v141
	v_exp_f32_e32 v141, v141
	v_add_f32_e32 v140, 1.0, v140
	global_store_dwordx4 v[164:165], v[178:181], off offset:-3584
	s_nop 1
	v_rcp_f32_e32 v178, v140
	v_add_f32_e32 v140, 1.0, v141
	v_add_f32_e32 v141, v38, v176
	v_mul_f32_e32 v141, 0xbfb8aa3b, v141
	v_exp_f32_e32 v141, v141
	v_add_f32_e32 v179, v39, v177
	v_mul_f32_e32 v179, 0xbfb8aa3b, v179
	v_exp_f32_e32 v181, v179
	v_rcp_f32_e32 v179, v140
	v_add_f32_e32 v140, 1.0, v141
	v_add_f32_e32 v141, v32, v174
	v_mul_f32_e32 v141, 0xbfb8aa3b, v141
	v_add_f32_e32 v174, v33, v175
	v_exp_f32_e32 v141, v141
	v_mul_f32_e32 v174, 0xbfb8aa3b, v174
	v_exp_f32_e32 v175, v174
	v_rcp_f32_e32 v180, v140
	v_add_f32_e32 v140, 1.0, v181
	v_rcp_f32_e32 v181, v140
	v_add_f32_e32 v140, 1.0, v141
	v_add_f32_e32 v141, v34, v176
	v_rcp_f32_e32 v174, v140
	v_add_f32_e32 v140, 1.0, v175
	v_mul_f32_e32 v141, 0xbfb8aa3b, v141
	v_add_f32_e32 v175, v35, v177
	v_exp_f32_e32 v141, v141
	v_mul_f32_e32 v175, 0xbfb8aa3b, v175
	v_exp_f32_e32 v177, v175
	v_rcp_f32_e32 v175, v140
	v_add_f32_e32 v140, 1.0, v141
	v_rcp_f32_e32 v176, v140
	v_add_f32_e32 v140, 1.0, v177
	v_rcp_f32_e32 v177, v140
	global_store_dwordx4 v[128:129], v[178:181], off offset:-3584
	global_store_dwordx4 v[130:131], v[174:177], off offset:-3584
	global_load_dwordx4 v[174:177], v[156:157], off offset:-3520
	s_waitcnt vmcnt(0)
; __device__ __forceinline__ float sigmoidf_(float x) { return __builtin_amdgcn_rcpf(1.0f + __expf(-x)); }
;     __device__ __forceinline__ void operator()(const AccT& acc, const Unit& u, int wr, int wc, int fr, int fq) const {
;     ...
;             for (int bj = 0; bj < 2; ++bj)
; #pragma unroll
;                 for (int n = 0; n < 2; ++n) { const int col = col0 - 1024 + bj * 128 + n * 16; const f32x4 av0 = *(const f32x4*)(a0 + col);
; #pragma unroll
;                     for (int ai = 0; ai < 2; ++ai)
; #pragma unroll
;                         for (int m = 0; m < 4; ++m) { const int row = row0 + ai * 128 + m * 16; f32x4 o;
; #pragma unroll
;                             for (int j = 0; j < 4; ++j) o[j] = sigmoidf_(av0[j] + acc[ai][bj][m][n][j]);
;                             *(f32x4*)(IC + (size_t)row * RW + col) = o; asm volatile("" ::: "memory"); } }
	v_add_f32_e32 v140, v28, v174
	v_mul_f32_e32 v140, 0xbfb8aa3b, v140
	v_add_f32_e32 v141, v29, v175
	v_exp_f32_e32 v140, v140
	v_mul_f32_e32 v141, 0xbfb8aa3b, v141
	v_exp_f32_e32 v141, v141
	v_add_f32_e32 v156, v31, v177
	v_add_f32_e32 v140, 1.0, v140
	v_rcp_f32_e32 v178, v140
	v_add_f32_e32 v140, 1.0, v141
	v_add_f32_e32 v141, v30, v176
	v_mul_f32_e32 v141, 0xbfb8aa3b, v141
	v_exp_f32_e32 v141, v141
	v_mul_f32_e32 v156, 0xbfb8aa3b, v156
	v_exp_f32_e32 v156, v156
	v_rcp_f32_e32 v179, v140
	v_add_f32_e32 v140, 1.0, v141
	v_add_f32_e32 v141, v24, v174
	v_rcp_f32_e32 v180, v140
	v_add_f32_e32 v140, 1.0, v156
	v_mul_f32_e32 v141, 0xbfb8aa3b, v141
	v_add_f32_e32 v156, v25, v175
	v_exp_f32_e32 v141, v141
	v_mul_f32_e32 v156, 0xbfb8aa3b, v156
	v_exp_f32_e32 v156, v156
	v_rcp_f32_e32 v181, v140
	v_add_f32_e32 v140, 1.0, v141
	v_add_f32_e32 v141, v26, v176
	v_rcp_f32_e32 v182, v140
	v_add_f32_e32 v140, 1.0, v156
	v_mul_f32_e32 v141, 0xbfb8aa3b, v141
	v_add_f32_e32 v156, v27, v177
	v_exp_f32_e32 v141, v141
	v_mul_f32_e32 v156, 0xbfb8aa3b, v156
	v_exp_f32_e32 v156, v156
	v_rcp_f32_e32 v183, v140
	v_add_f32_e32 v140, 1.0, v141
	v_rcp_f32_e32 v184, v140
	v_add_f32_e32 v140, 1.0, v156
	v_rcp_f32_e32 v185, v140
	v_add_f32_e32 v140, v20, v174
	v_mul_f32_e32 v140, 0xbfb8aa3b, v140
	v_add_f32_e32 v141, v21, v175
	v_exp_f32_e32 v140, v140
	v_mul_f32_e32 v141, 0xbfb8aa3b, v141
	v_exp_f32_e32 v141, v141
	v_add_f32_e32 v157, v23, v177
	v_add_f32_e32 v140, 1.0, v140
	v_rcp_f32_e32 v156, v140
	v_add_f32_e32 v140, 1.0, v141
	v_add_f32_e32 v141, v22, v176
	v_mul_f32_e32 v141, 0xbfb8aa3b, v141
	global_store_dwordx4 v[160:161], v[178:181], off offset:-3520
	v_exp_f32_e32 v141, v141
	v_mul_f32_e32 v157, 0xbfb8aa3b, v157
	global_store_dwordx4 v[158:159], v[182:185], off offset:-3520
	v_exp_f32_e32 v159, v157
	v_rcp_f32_e32 v157, v140
	v_add_f32_e32 v140, 1.0, v141
	v_rcp_f32_e32 v158, v140
	v_add_f32_e32 v140, 1.0, v159
	v_rcp_f32_e32 v159, v140
	v_add_f32_e32 v140, v12, v174
	v_mul_f32_e32 v140, 0xbfb8aa3b, v140
	v_add_f32_e32 v141, v13, v175
	v_exp_f32_e32 v140, v140
	v_mul_f32_e32 v141, 0xbfb8aa3b, v141
	v_exp_f32_e32 v141, v141
	v_add_f32_e32 v140, 1.0, v140
	global_store_dwordx4 v[154:155], v[156:159], off offset:-3520
	v_rcp_f32_e32 v154, v140
	v_add_f32_e32 v140, 1.0, v141
	v_add_f32_e32 v141, v14, v176
	v_mul_f32_e32 v141, 0xbfb8aa3b, v141
	v_add_f32_e32 v155, v15, v177
	v_exp_f32_e32 v141, v141
	v_mul_f32_e32 v155, 0xbfb8aa3b, v155
	v_exp_f32_e32 v157, v155
	v_rcp_f32_e32 v155, v140
	v_add_f32_e32 v140, 1.0, v141
	v_add_f32_e32 v141, v16, v174
	v_rcp_f32_e32 v156, v140
	v_add_f32_e32 v140, 1.0, v157
	v_mul_f32_e32 v141, 0xbfb8aa3b, v141
	v_add_f32_e32 v157, v17, v175
	v_exp_f32_e32 v141, v141
	v_mul_f32_e32 v157, 0xbfb8aa3b, v157
	v_exp_f32_e32 v159, v157
	v_rcp_f32_e32 v157, v140
	v_add_f32_e32 v140, 1.0, v141
	v_add_f32_e32 v141, v18, v176
	v_rcp_f32_e32 v158, v140
	v_add_f32_e32 v140, 1.0, v159
	v_mul_f32_e32 v141, 0xbfb8aa3b, v141
	v_add_f32_e32 v159, v19, v177
	v_exp_f32_e32 v141, v141
	v_mul_f32_e32 v159, 0xbfb8aa3b, v159
	v_exp_f32_e32 v161, v159
	v_rcp_f32_e32 v159, v140
	v_add_f32_e32 v140, 1.0, v141
	v_rcp_f32_e32 v160, v140
	v_add_f32_e32 v140, 1.0, v161
	v_rcp_f32_e32 v161, v140
	v_add_f32_e32 v140, v8, v174
	v_mul_f32_e32 v140, 0xbfb8aa3b, v140
	v_add_f32_e32 v141, v9, v175
	v_exp_f32_e32 v140, v140
	v_mul_f32_e32 v141, 0xbfb8aa3b, v141
	v_exp_f32_e32 v141, v141
	v_add_f32_e32 v140, 1.0, v140
	global_store_dwordx4 v[162:163], v[154:157], off offset:-3520
	global_store_dwordx4 v[166:167], v[158:161], off offset:-3520
	s_nop 0
	v_rcp_f32_e32 v154, v140
	v_add_f32_e32 v140, 1.0, v141
	v_add_f32_e32 v141, v10, v176
	v_mul_f32_e32 v141, 0xbfb8aa3b, v141
	v_add_f32_e32 v155, v11, v177
	v_exp_f32_e32 v141, v141
	v_mul_f32_e32 v155, 0xbfb8aa3b, v155
	v_exp_f32_e32 v157, v155
	v_rcp_f32_e32 v155, v140
	v_add_f32_e32 v140, 1.0, v141
	v_rcp_f32_e32 v156, v140
	v_add_f32_e32 v140, 1.0, v157
	v_rcp_f32_e32 v157, v140
	v_add_f32_e32 v140, v4, v174
	v_mul_f32_e32 v140, 0xbfb8aa3b, v140
	v_add_f32_e32 v141, v5, v175
	v_exp_f32_e32 v140, v140
	v_mul_f32_e32 v141, 0xbfb8aa3b, v141
	v_exp_f32_e32 v141, v141
	global_store_dwordx4 v[164:165], v[154:157], off offset:-3520
	v_add_f32_e32 v140, 1.0, v140
	s_nop 0
	v_rcp_f32_e32 v154, v140
	v_add_f32_e32 v140, 1.0, v141
	v_add_f32_e32 v141, v6, v176
	v_mul_f32_e32 v141, 0xbfb8aa3b, v141
	v_add_f32_e32 v155, v7, v177
	v_exp_f32_e32 v141, v141
	v_mul_f32_e32 v155, 0xbfb8aa3b, v155
	v_exp_f32_e32 v157, v155
	v_rcp_f32_e32 v155, v140
	v_add_f32_e32 v140, 1.0, v141
	v_add_f32_e32 v141, v0, v174
	v_rcp_f32_e32 v156, v140
	v_add_f32_e32 v140, 1.0, v157
	v_mul_f32_e32 v141, 0xbfb8aa3b, v141
	v_add_f32_e32 v157, v1, v175
	v_exp_f32_e32 v141, v141
	v_mul_f32_e32 v157, 0xbfb8aa3b, v157
	v_exp_f32_e32 v159, v157
	v_rcp_f32_e32 v157, v140
	v_add_f32_e32 v140, 1.0, v141
	v_add_f32_e32 v141, v2, v176
	v_rcp_f32_e32 v158, v140
	v_add_f32_e32 v140, 1.0, v159
	v_mul_f32_e32 v141, 0xbfb8aa3b, v141
	v_add_f32_e32 v159, v3, v177
	v_exp_f32_e32 v141, v141
	v_mul_f32_e32 v159, 0xbfb8aa3b, v159
	v_exp_f32_e32 v161, v159
	v_rcp_f32_e32 v159, v140
	v_add_f32_e32 v140, 1.0, v141
	v_rcp_f32_e32 v160, v140
	v_add_f32_e32 v140, 1.0, v161
	v_rcp_f32_e32 v161, v140
	global_store_dwordx4 v[128:129], v[154:157], off offset:-3520
	global_store_dwordx4 v[130:131], v[158:161], off offset:-3520

; #define PG8_STAGE(bufoff, gbase, voff) do { _Pragma("unroll") for (int _i = 0; _i < 2; ++_i) \
;         __builtin_amdgcn_global_load_lds((const unsigned*)((const char*)(gbase) + (voff)[_i]), (LAS unsigned*)(lds + (bufoff) + ldsw + _i * 8192), 16, 0, 0); } while (0)
; #define PG8_LDA(dst, b, h) do { _Pragma("unroll") for (int m = 0; m < 4; ++m) _Pragma("unroll") for (int k = 0; k < 2; ++k) dst[m][k] = *(const LAS bf16x8*)(lds + PG8_SA(b, h) + aoff + m * 2048 + k * 1024); } while (0)
; #define PG8_WAIT_V(n) asm volatile("s_waitcnt vmcnt(" #n ")" ::: "memory")
; #define PG8_BAR __builtin_amdgcn_s_barrier()
; template <class Epi>
; __device__ __forceinline__ void gemm_phase(LAS unsigned char* lds, const Gemm g, const StaticOrder& S, const Epi& E) {
;     ...
;     PG8_STAGE(PG8_SB(0, 0), cB, voffB); PG8_STAGE(PG8_SA(0, 0), cA, voffA); PG8_STAGE(PG8_SB(0, 1), cB + hstepB, voffB); PG8_STAGE(PG8_SA(0, 1), cA + hstepA, voffA);
;     if (wr == 1) PG8_BAR;
;     PG8_WAIT_V(4); PG8_BAR;
;     PG8_STAGE(PG8_SB(1, 0), cB + kstep, voffB); PG8_STAGE(PG8_SA(1, 0), cA + kstep, voffA); PG8_STAGE(PG8_SB(1, 1), cB + hstepB + kstep, voffB);
;     PG8_WAIT_V(6); PG8_BAR;
;     for (;;) {
;         const bool has_next = S.next(ui + 1, nxt);
;         const char* nA = has_next ? (const char*)g.A + (size_t)nxt.pm * tstepA : cA; const char* nB = has_next ? (const char*)g.Bt + (size_t)nxt.pn * tstepB : cB;
;         for (int t = 0; t < nt; t += 2) {
;             const bool last = (t == nt - 2);
;             const char* a1 = cA + (size_t)(t + 1) * kstep;
;             const char* a2 = last ? nA : cA + (size_t)(t + 2) * kstep; const char* b2 = last ? nB : cB + (size_t)(t + 2) * kstep;
;             const char* a3 = a2 + kstep; const char* b3 = b2 + kstep;
;             PG8_LDB(B0, 0, 0); PG8_SCHED; PG8_LDA(At, 0, 0); PG8_STAGE(PG8_SA(1, 1), a1 + hstepA, voffA);
;             PG8_WAIT_L(8); PG8_BAR; PG8_WAIT_L(0); PG8_MMA(0, 0, At, B0); PG8_BAR; PG8_SCHED;
;             PG8_LDB(B1, 0, 1); PG8_STAGE(PG8_SB(0, 0), b2, voffB);
;             PG8_BAR; PG8_WAIT_L(0); PG8_MMA(0, 1, At, B1); PG8_BAR;
;             PG8_LDA(At, 0, 1); PG8_STAGE(PG8_SA(0, 0), a2, voffA);
;             PG8_BAR; PG8_WAIT_L(0); PG8_MMA(1, 0, At, B0); PG8_BAR; PG8_SCHED;
;             PG8_STAGE(PG8_SB(0, 1), b2 + hstepB, voffB);
;             PG8_WAIT_V(6); PG8_BAR; PG8_MMA(1, 1, At, B1); PG8_BAR;
.LBB0_766:
	s_ashr_i32 s31, s30, 31
	s_lshl_b64 s[38:39], s[30:31], 17
	v_mov_b64_e32 v[0:1], 0x400
	s_add_u32 s38, s69, s38
	v_cmp_lt_i64_e32 vcc, s[26:27], v[0:1]
	s_addc_u32 s39, s70, s39
	s_and_b64 s[40:41], vcc, exec
	s_cselect_b32 s65, s39, s61
	s_cselect_b32 s64, s38, s60
	s_ashr_i32 s29, s28, 31
	s_lshl_b64 s[40:41], s[28:29], 16
	s_add_u32 s40, s71, s40
	s_addc_u32 s41, s72, s41
	s_add_u32 s90, s60, 0x10080
	ds_read_b128 v[0:3], v171
	ds_read_b128 v[4:7], v171 offset:1024
	ds_read_b128 v[8:11], v171 offset:2048
	ds_read_b128 v[12:15], v171 offset:3072
	s_addc_u32 s91, s61, 0
	s_add_u32 s60, s64, 0x10000
	s_addc_u32 s61, s65, 0
	s_and_b64 s[66:67], vcc, exec
	s_cselect_b32 s50, s40, s50
	s_cselect_b32 s51, s41, s51
	s_add_u32 s66, s50, 0x8000
	s_addc_u32 s67, s51, 0
	v_lshl_add_u64 v[48:49], s[90:91], 0, v[132:133]
	s_add_i32 m0, s74, 0xc000
	ds_read_b128 v[16:19], v172
	ds_read_b128 v[20:23], v172 offset:1024
	ds_read_b128 v[24:27], v172 offset:2048
	ds_read_b128 v[28:31], v172 offset:3072
	ds_read_b128 v[32:35], v172 offset:4096
	ds_read_b128 v[36:39], v172 offset:5120
	ds_read_b128 v[40:43], v172 offset:6144
	ds_read_b128 v[44:47], v172 offset:7168
	global_load_lds_dwordx4 v[48:49], off
	v_lshl_add_u64 v[48:49], s[90:91], 0, v[136:137]
	s_add_i32 m0, s74, 0xe000
	s_nop 0
	global_load_lds_dwordx4 v[48:49], off
	s_waitcnt lgkmcnt(8)
	s_barrier
	s_setprio 1
	s_waitcnt lgkmcnt(7)
	v_mfma_f32_16x16x32_bf16 v[48:51], v[0:3], v[16:19], 0
	v_mfma_f32_16x16x32_bf16 v[52:55], v[8:11], v[16:19], 0
	s_waitcnt lgkmcnt(5)
	v_mfma_f32_16x16x32_bf16 v[56:59], v[0:3], v[24:27], 0
	v_mfma_f32_16x16x32_bf16 v[60:63], v[8:11], v[24:27], 0
	s_waitcnt lgkmcnt(3)
	v_mfma_f32_16x16x32_bf16 v[64:67], v[0:3], v[32:35], 0
	v_mfma_f32_16x16x32_bf16 v[68:71], v[8:11], v[32:35], 0
	s_waitcnt lgkmcnt(1)
	v_mfma_f32_16x16x32_bf16 v[72:75], v[0:3], v[40:43], 0
	v_mfma_f32_16x16x32_bf16 v[76:79], v[8:11], v[40:43], 0
	v_mfma_f32_16x16x32_bf16 v[48:51], v[4:7], v[20:23], v[48:51]
	v_mfma_f32_16x16x32_bf16 v[52:55], v[12:15], v[20:23], v[52:55]
	v_mfma_f32_16x16x32_bf16 v[56:59], v[4:7], v[28:31], v[56:59]
	v_mfma_f32_16x16x32_bf16 v[60:63], v[12:15], v[28:31], v[60:63]
	v_mfma_f32_16x16x32_bf16 v[64:67], v[4:7], v[36:39], v[64:67]
	v_mfma_f32_16x16x32_bf16 v[68:71], v[12:15], v[36:39], v[68:71]
	s_waitcnt lgkmcnt(0)
	v_mfma_f32_16x16x32_bf16 v[72:75], v[4:7], v[44:47], v[72:75]
	v_mfma_f32_16x16x32_bf16 v[76:79], v[12:15], v[44:47], v[76:79]
	s_setprio 0
	s_barrier
	s_add_i32 s3, s83, s73
	v_lshl_add_u64 v[186:187], s[50:51], 0, v[134:135]
	s_mov_b32 m0, s3
	ds_read_b128 v[80:83], v173
	ds_read_b128 v[84:87], v173 offset:1024
	ds_read_b128 v[88:91], v173 offset:2048
	ds_read_b128 v[92:95], v173 offset:3072
	global_load_lds_dwordx4 v[186:187], off
	v_lshl_add_u64 v[188:189], s[50:51], 0, v[138:139]
	s_add_i32 m0, s3, 0x2000
	s_nop 0
	global_load_lds_dwordx4 v[188:189], off
	s_barrier
	s_setprio 1
	s_waitcnt lgkmcnt(3)
	v_mfma_f32_16x16x32_bf16 v[96:99], v[80:83], v[16:19], 0
	s_waitcnt lgkmcnt(1)
	v_mfma_f32_16x16x32_bf16 v[16:19], v[88:91], v[16:19], 0
	v_mfma_f32_16x16x32_bf16 v[96:99], v[84:87], v[20:23], v[96:99]
	s_waitcnt lgkmcnt(0)
	v_mfma_f32_16x16x32_bf16 v[16:19], v[92:95], v[20:23], v[16:19]
	v_mfma_f32_16x16x32_bf16 v[20:23], v[80:83], v[24:27], 0
	v_mfma_f32_16x16x32_bf16 v[24:27], v[88:91], v[24:27], 0
	v_mfma_f32_16x16x32_bf16 v[20:23], v[84:87], v[28:31], v[20:23]
	v_mfma_f32_16x16x32_bf16 v[24:27], v[92:95], v[28:31], v[24:27]
	v_mfma_f32_16x16x32_bf16 v[28:31], v[80:83], v[32:35], 0
	v_mfma_f32_16x16x32_bf16 v[100:103], v[84:87], v[36:39], v[28:31]
	v_mfma_f32_16x16x32_bf16 v[28:31], v[88:91], v[32:35], 0
	v_mfma_f32_16x16x32_bf16 v[32:35], v[92:95], v[36:39], v[28:31]
	v_mfma_f32_16x16x32_bf16 v[28:31], v[80:83], v[40:43], 0
	v_mfma_f32_16x16x32_bf16 v[36:39], v[84:87], v[44:47], v[28:31]
	v_mfma_f32_16x16x32_bf16 v[28:31], v[88:91], v[40:43], 0
	v_mfma_f32_16x16x32_bf16 v[40:43], v[92:95], v[44:47], v[28:31]
	s_setprio 0
	s_mov_b32 m0, s74
	v_lshl_add_u64 v[140:141], s[64:65], 0, v[132:133]
	s_barrier
	s_nop 2
	ds_read_b128 v[28:31], v172 offset:16384
	ds_read_b128 v[44:47], v172 offset:17408
	ds_read_b128 v[104:107], v172 offset:18432
	ds_read_b128 v[108:111], v172 offset:19456
	ds_read_b128 v[112:115], v172 offset:20480
	ds_read_b128 v[116:119], v172 offset:21504
	ds_read_b128 v[120:123], v172 offset:22528
	ds_read_b128 v[124:127], v172 offset:23552
	global_load_lds_dwordx4 v[140:141], off
	v_lshl_add_u64 v[142:143], s[64:65], 0, v[136:137]
	s_mov_b32 m0, s75
	s_nop 0
	global_load_lds_dwordx4 v[142:143], off
	s_barrier
	s_setprio 1
	s_waitcnt lgkmcnt(7)
	v_mfma_f32_16x16x32_bf16 v[128:131], v[0:3], v[28:31], 0
	s_waitcnt lgkmcnt(5)
	v_mfma_f32_16x16x32_bf16 v[148:151], v[0:3], v[104:107], 0
	s_waitcnt lgkmcnt(3)
	v_mfma_f32_16x16x32_bf16 v[156:159], v[0:3], v[112:115], 0
	s_waitcnt lgkmcnt(1)
	v_mfma_f32_16x16x32_bf16 v[0:3], v[0:3], v[120:123], 0
	v_mfma_f32_16x16x32_bf16 v[128:131], v[4:7], v[44:47], v[128:131]
	v_mfma_f32_16x16x32_bf16 v[144:147], v[8:11], v[28:31], 0
	v_mfma_f32_16x16x32_bf16 v[148:151], v[4:7], v[108:111], v[148:151]
	v_mfma_f32_16x16x32_bf16 v[152:155], v[8:11], v[104:107], 0
	v_mfma_f32_16x16x32_bf16 v[156:159], v[4:7], v[116:119], v[156:159]
	s_waitcnt lgkmcnt(0)
	v_mfma_f32_16x16x32_bf16 v[0:3], v[4:7], v[124:127], v[0:3]
	v_mfma_f32_16x16x32_bf16 v[4:7], v[8:11], v[120:123], 0
	v_mfma_f32_16x16x32_bf16 v[144:147], v[12:15], v[44:47], v[144:147]
	v_mfma_f32_16x16x32_bf16 v[152:155], v[12:15], v[108:111], v[152:155]
	v_mfma_f32_16x16x32_bf16 v[160:163], v[8:11], v[112:115], 0
	v_mfma_f32_16x16x32_bf16 v[4:7], v[12:15], v[124:127], v[4:7]
	v_mfma_f32_16x16x32_bf16 v[160:163], v[12:15], v[116:119], v[160:163]
	s_setprio 0
	s_barrier
; #define PG8_STAGE(bufoff, gbase, voff) do { _Pragma("unroll") for (int _i = 0; _i < 2; ++_i) \
;         __builtin_amdgcn_global_load_lds((const unsigned*)((const char*)(gbase) + (voff)[_i]), (LAS unsigned*)(lds + (bufoff) + ldsw + _i * 8192), 16, 0, 0); } while (0)
; #define PG8_LDA(dst, b, h) do { _Pragma("unroll") for (int m = 0; m < 4; ++m) _Pragma("unroll") for (int k = 0; k < 2; ++k) dst[m][k] = *(const LAS bf16x8*)(lds + PG8_SA(b, h) + aoff + m * 2048 + k * 1024); } while (0)
; #define PG8_LDB(dst, b, h) do { _Pragma("unroll") for (int n = 0; n < 2; ++n) _Pragma("unroll") for (int k = 0; k < 2; ++k) dst[n][k] = *(const LAS bf16x8*)(lds + PG8_SB(b, h) + boff + n * 2048 + k * 1024); } while (0)
; #define PG8_MMA(ai, bj, At, Bt) do { __builtin_amdgcn_s_setprio(1); _Pragma("unroll") for (int m = 0; m < 4; ++m) _Pragma("unroll") for (int n = 0; n < 2; ++n) _Pragma("unroll") for (int k = 0; k < 2; ++k) \
;         acc[ai][bj][m][n] = __builtin_amdgcn_mfma_f32_16x16x32_bf16(Bt[n][k], At[m][k], acc[ai][bj][m][n], 0, 0, 0); __builtin_amdgcn_s_setprio(0); } while (0)
; #define PG8_WAIT_V(n) asm volatile("s_waitcnt vmcnt(" #n ")" ::: "memory")
; #define PG8_WAIT_L(n) asm volatile("s_waitcnt lgkmcnt(" #n ")" ::: "memory")
; #define PG8_BAR __builtin_amdgcn_s_barrier()
; #define PG8_SCHED __builtin_amdgcn_sched_barrier(0)
; template <class Epi>
; __device__ __forceinline__ void gemm_phase(LAS unsigned char* lds, const Gemm g, const StaticOrder& S, const Epi& E) {
;     ...
;             PG8_WAIT_V(6); PG8_BAR; PG8_MMA(1, 1, At, B1); PG8_BAR;
;             PG8_LDB(B0, 1, 0); PG8_SCHED; PG8_LDA(At, 1, 0); PG8_STAGE(PG8_SA(0, 1), a2 + hstepA, voffA);
;             PG8_WAIT_L(8); PG8_BAR; PG8_WAIT_L(0); PG8_MMA(0, 0, At, B0); PG8_BAR; PG8_SCHED;
;             PG8_LDB(B1, 1, 1); PG8_STAGE(PG8_SB(1, 0), b3, voffB);
;             PG8_BAR; PG8_WAIT_L(0); PG8_MMA(0, 1, At, B1); PG8_BAR;
;             PG8_LDA(At, 1, 1); PG8_STAGE(PG8_SA(1, 0), a3, voffA);
;             PG8_BAR; PG8_WAIT_L(0); PG8_MMA(1, 0, At, B0); PG8_BAR; PG8_SCHED;
	s_add_i32 s3, s84, s73
	v_lshl_add_u64 v[8:9], s[66:67], 0, v[134:135]
	s_mov_b32 m0, s3
	s_nop 0
	global_load_lds_dwordx4 v[8:9], off
	v_lshl_add_u64 v[8:9], s[66:67], 0, v[138:139]
	s_add_i32 m0, s3, 0x2000
	s_nop 0
	global_load_lds_dwordx4 v[8:9], off
	s_waitcnt vmcnt(6)
	s_barrier
	s_setprio 1
	v_mfma_f32_16x16x32_bf16 v[12:15], v[88:91], v[28:31], 0
	v_mfma_f32_16x16x32_bf16 v[164:167], v[92:95], v[44:47], v[12:15]
	v_mfma_f32_16x16x32_bf16 v[12:15], v[80:83], v[104:107], 0
	v_mfma_f32_16x16x32_bf16 v[174:177], v[84:87], v[108:111], v[12:15]
	v_mfma_f32_16x16x32_bf16 v[12:15], v[88:91], v[104:107], 0
	v_mfma_f32_16x16x32_bf16 v[178:181], v[92:95], v[108:111], v[12:15]
	v_mfma_f32_16x16x32_bf16 v[12:15], v[80:83], v[112:115], 0
	v_mfma_f32_16x16x32_bf16 v[182:185], v[84:87], v[116:119], v[12:15]
	v_mfma_f32_16x16x32_bf16 v[12:15], v[88:91], v[112:115], 0
	v_mfma_f32_16x16x32_bf16 v[8:11], v[80:83], v[28:31], 0
	v_mfma_f32_16x16x32_bf16 v[190:193], v[92:95], v[116:119], v[12:15]
	v_mfma_f32_16x16x32_bf16 v[12:15], v[80:83], v[120:123], 0
	v_mfma_f32_16x16x32_bf16 v[8:11], v[84:87], v[44:47], v[8:11]
	v_mfma_f32_16x16x32_bf16 v[194:197], v[84:87], v[124:127], v[12:15]
	v_mfma_f32_16x16x32_bf16 v[12:15], v[88:91], v[120:123], 0
	v_mfma_f32_16x16x32_bf16 v[198:201], v[92:95], v[124:127], v[12:15]
	s_setprio 0
	s_add_i32 s3, 0, 0x18000
	s_nop 4
	v_add_u32_e32 v12, s3, v169
	s_barrier
	ds_read_b128 v[202:205], v12
	ds_read_b128 v[206:209], v12 offset:1024
	ds_read_b128 v[210:213], v12 offset:2048
	ds_read_b128 v[214:217], v12 offset:3072
	s_mov_b32 m0, s76
	v_lshl_add_u64 v[84:85], s[60:61], 0, v[132:133]
	ds_read_b128 v[12:15], v172 offset:32768
	ds_read_b128 v[28:31], v172 offset:33792
	ds_read_b128 v[44:47], v172 offset:34816
	ds_read_b128 v[80:83], v172 offset:35840
	ds_read_b128 v[104:107], v172 offset:36864
	ds_read_b128 v[112:115], v172 offset:37888
	ds_read_b128 v[218:221], v172 offset:38912
	ds_read_b128 v[222:225], v172 offset:39936
	global_load_lds_dwordx4 v[84:85], off
	v_lshl_add_u64 v[84:85], s[60:61], 0, v[136:137]
	s_mov_b32 m0, s77
	s_nop 0
	global_load_lds_dwordx4 v[84:85], off
	s_waitcnt lgkmcnt(8)
	s_barrier
	s_setprio 1
	s_waitcnt lgkmcnt(7)
	v_mfma_f32_16x16x32_bf16 v[48:51], v[202:205], v[12:15], v[48:51]
	s_waitcnt lgkmcnt(6)
	v_mfma_f32_16x16x32_bf16 v[120:123], v[206:209], v[28:31], v[48:51]
	v_mfma_f32_16x16x32_bf16 v[48:51], v[210:213], v[12:15], v[52:55]
	v_mfma_f32_16x16x32_bf16 v[92:95], v[214:217], v[28:31], v[48:51]
	s_waitcnt lgkmcnt(5)
	v_mfma_f32_16x16x32_bf16 v[48:51], v[202:205], v[44:47], v[56:59]
	s_waitcnt lgkmcnt(4)
	v_mfma_f32_16x16x32_bf16 v[124:127], v[206:209], v[80:83], v[48:51]
	v_mfma_f32_16x16x32_bf16 v[48:51], v[210:213], v[44:47], v[60:63]
	v_mfma_f32_16x16x32_bf16 v[88:91], v[214:217], v[80:83], v[48:51]
	s_waitcnt lgkmcnt(3)
	v_mfma_f32_16x16x32_bf16 v[48:51], v[202:205], v[104:107], v[64:67]
	s_waitcnt lgkmcnt(2)
	v_mfma_f32_16x16x32_bf16 v[116:119], v[206:209], v[112:115], v[48:51]
	v_mfma_f32_16x16x32_bf16 v[48:51], v[210:213], v[104:107], v[68:71]
	v_mfma_f32_16x16x32_bf16 v[84:87], v[214:217], v[112:115], v[48:51]
	s_waitcnt lgkmcnt(1)
	v_mfma_f32_16x16x32_bf16 v[48:51], v[202:205], v[218:221], v[72:75]
	s_waitcnt lgkmcnt(0)
	v_mfma_f32_16x16x32_bf16 v[108:111], v[206:209], v[222:225], v[48:51]
	v_mfma_f32_16x16x32_bf16 v[48:51], v[210:213], v[218:221], v[76:79]
	v_mfma_f32_16x16x32_bf16 v[76:79], v[214:217], v[222:225], v[48:51]
	s_setprio 0
	s_barrier
	s_add_i32 s29, 0, 0x1c000
	s_nop 3
	v_add_u32_e32 v48, s29, v169
	s_add_i32 s3, s3, s73
	ds_read_b128 v[226:229], v48
	ds_read_b128 v[230:233], v48 offset:1024
	ds_read_b128 v[234:237], v48 offset:2048
	ds_read_b128 v[238:241], v48 offset:3072
	v_lshl_add_u64 v[48:49], v[186:187], 0, s[16:17]
	s_mov_b32 m0, s3
	s_nop 0
	global_load_lds_dwordx4 v[48:49], off
	v_lshl_add_u64 v[48:49], v[188:189], 0, s[16:17]
	s_add_i32 m0, s3, 0x2000
	s_nop 0
	global_load_lds_dwordx4 v[48:49], off
	s_barrier
	s_setprio 1
	s_waitcnt lgkmcnt(3)
	v_mfma_f32_16x16x32_bf16 v[48:51], v[226:229], v[12:15], v[96:99]
	s_waitcnt lgkmcnt(1)
	v_mfma_f32_16x16x32_bf16 v[12:15], v[234:237], v[12:15], v[16:19]
	v_mfma_f32_16x16x32_bf16 v[60:63], v[230:233], v[28:31], v[48:51]
	s_waitcnt lgkmcnt(0)
	v_mfma_f32_16x16x32_bf16 v[28:31], v[238:241], v[28:31], v[12:15]
	v_mfma_f32_16x16x32_bf16 v[12:15], v[226:229], v[44:47], v[20:23]
	v_mfma_f32_16x16x32_bf16 v[56:59], v[230:233], v[80:83], v[12:15]
	v_mfma_f32_16x16x32_bf16 v[12:15], v[234:237], v[44:47], v[24:27]
	v_mfma_f32_16x16x32_bf16 v[24:27], v[238:241], v[80:83], v[12:15]
	v_mfma_f32_16x16x32_bf16 v[12:15], v[226:229], v[104:107], v[100:103]
	v_mfma_f32_16x16x32_bf16 v[52:55], v[230:233], v[112:115], v[12:15]
	v_mfma_f32_16x16x32_bf16 v[12:15], v[234:237], v[104:107], v[32:35]
	v_mfma_f32_16x16x32_bf16 v[20:23], v[238:241], v[112:115], v[12:15]
	v_mfma_f32_16x16x32_bf16 v[12:15], v[226:229], v[218:221], v[36:39]
	v_mfma_f32_16x16x32_bf16 v[44:47], v[230:233], v[222:225], v[12:15]
	v_mfma_f32_16x16x32_bf16 v[12:15], v[234:237], v[218:221], v[40:43]
	v_mfma_f32_16x16x32_bf16 v[12:15], v[238:241], v[222:225], v[12:15]
	s_setprio 0
	s_mov_b32 m0, s78
	v_lshl_add_u64 v[40:41], v[140:141], 0, s[16:17]
	s_barrier
	ds_read_b128 v[16:19], v172 offset:49152
	ds_read_b128 v[32:35], v172 offset:50176
	ds_read_b128 v[36:39], v172 offset:51200
	ds_read_b128 v[218:221], v172 offset:52224
	ds_read_b128 v[222:225], v172 offset:53248
	ds_read_b128 v[242:245], v172 offset:54272
	ds_read_b128 v[246:249], v172 offset:55296
	ds_read_b128 v[250:253], v172 offset:56320
	global_load_lds_dwordx4 v[40:41], off
	v_lshl_add_u64 v[40:41], v[142:143], 0, s[16:17]
	s_mov_b32 m0, s79
	s_nop 0
	global_load_lds_dwordx4 v[40:41], off
	s_barrier
; __device__ __forceinline__ float sigmoidf_(float x) { return __builtin_amdgcn_rcpf(1.0f + __expf(-x)); }
; #define PG8_STAGE(bufoff, gbase, voff) do { _Pragma("unroll") for (int _i = 0; _i < 2; ++_i) \
;         __builtin_amdgcn_global_load_lds((const unsigned*)((const char*)(gbase) + (voff)[_i]), (LAS unsigned*)(lds + (bufoff) + ldsw + _i * 8192), 16, 0, 0); } while (0)
; #define PG8_MMA(ai, bj, At, Bt) do { __builtin_amdgcn_s_setprio(1); _Pragma("unroll") for (int m = 0; m < 4; ++m) _Pragma("unroll") for (int n = 0; n < 2; ++n) _Pragma("unroll") for (int k = 0; k < 2; ++k) \
;         acc[ai][bj][m][n] = __builtin_amdgcn_mfma_f32_16x16x32_bf16(Bt[n][k], At[m][k], acc[ai][bj][m][n], 0, 0, 0); __builtin_amdgcn_s_setprio(0); } while (0)
; #define PG8_WAIT_V(n) asm volatile("s_waitcnt vmcnt(" #n ")" ::: "memory")
; #define PG8_WAIT_L(n) asm volatile("s_waitcnt lgkmcnt(" #n ")" ::: "memory")
; #define PG8_BAR __builtin_amdgcn_s_barrier()
; #define PG8_SCHED __builtin_amdgcn_sched_barrier(0)
; template <class Epi>
; __device__ __forceinline__ void gemm_phase(LAS unsigned char* lds, const Gemm g, const StaticOrder& S, const Epi& E) {
;     ...
;             PG8_BAR; PG8_WAIT_L(0); PG8_MMA(1, 0, At, B0); PG8_BAR; PG8_SCHED;
;             PG8_STAGE(PG8_SB(1, 1), b3 + hstepB, voffB);
;             PG8_WAIT_V(6); PG8_BAR; PG8_MMA(1, 1, At, B1); PG8_BAR;
;     __device__ __forceinline__ void operator()(const AccT& acc, const Unit& u, int wr, int wc, int fr, int fq) const {
;     ...
;         } else {
; #pragma unroll
;             for (int bj = 0; bj < 2; ++bj)
; #pragma unroll
;                 for (int n = 0; n < 2; ++n) { const int col = col0 - 1024 + bj * 128 + n * 16; const f32x4 av0 = *(const f32x4*)(a0 + col);
; #pragma unroll
;                     for (int ai = 0; ai < 2; ++ai)
; #pragma unroll
;                         for (int m = 0; m < 4; ++m) { const int row = row0 + ai * 128 + m * 16; f32x4 o;
; #pragma unroll
;                             for (int j = 0; j < 4; ++j) o[j] = sigmoidf_(av0[j] + acc[ai][bj][m][n][j]);
;                             *(f32x4*)(IC + (size_t)row * RW + col) = o; asm volatile("" ::: "memory"); } }
	s_waitcnt lgkmcnt(0)
	s_setprio 1
	s_waitcnt lgkmcnt(0)
	v_mfma_f32_16x16x32_bf16 v[40:43], v[202:205], v[16:19], v[128:131]
	s_add_u32 s50, s50, 0x8080
	s_addc_u32 s51, s51, 0
	v_mfma_f32_16x16x32_bf16 v[112:115], v[206:209], v[32:35], v[40:43]
	v_mfma_f32_16x16x32_bf16 v[40:43], v[210:213], v[16:19], v[144:147]
	v_mfma_f32_16x16x32_bf16 v[80:83], v[214:217], v[32:35], v[40:43]
	v_mfma_f32_16x16x32_bf16 v[40:43], v[202:205], v[36:39], v[148:151]
	v_mfma_f32_16x16x32_bf16 v[104:107], v[206:209], v[218:221], v[40:43]
	v_mfma_f32_16x16x32_bf16 v[40:43], v[210:213], v[36:39], v[152:155]
	v_mfma_f32_16x16x32_bf16 v[72:75], v[214:217], v[218:221], v[40:43]
	v_mfma_f32_16x16x32_bf16 v[40:43], v[202:205], v[222:225], v[156:159]
	v_mfma_f32_16x16x32_bf16 v[0:3], v[202:205], v[246:249], v[0:3]
	v_mfma_f32_16x16x32_bf16 v[100:103], v[206:209], v[242:245], v[40:43]
	v_mfma_f32_16x16x32_bf16 v[40:43], v[210:213], v[222:225], v[160:163]
	v_mfma_f32_16x16x32_bf16 v[96:99], v[206:209], v[250:253], v[0:3]
	v_mfma_f32_16x16x32_bf16 v[0:3], v[210:213], v[246:249], v[4:7]
	v_mfma_f32_16x16x32_bf16 v[68:71], v[214:217], v[242:245], v[40:43]
	v_mfma_f32_16x16x32_bf16 v[64:67], v[214:217], v[250:253], v[0:3]
	s_setprio 0
	s_barrier
	s_add_i32 s3, s29, s73
	s_nop 2
	v_lshl_add_u64 v[0:1], s[50:51], 0, v[134:135]
	s_mov_b32 m0, s3
	s_nop 0
	global_load_lds_dwordx4 v[0:1], off
	v_lshl_add_u64 v[0:1], s[50:51], 0, v[138:139]
	s_add_i32 m0, s3, 0x2000
	s_nop 0
	global_load_lds_dwordx4 v[0:1], off
	s_waitcnt vmcnt(6)
	s_barrier
	s_setprio 1
	v_mfma_f32_16x16x32_bf16 v[0:3], v[226:229], v[16:19], v[8:11]
	v_mfma_f32_16x16x32_bf16 v[48:51], v[230:233], v[32:35], v[0:3]
	v_mfma_f32_16x16x32_bf16 v[0:3], v[234:237], v[16:19], v[164:167]
	v_mfma_f32_16x16x32_bf16 v[16:19], v[238:241], v[32:35], v[0:3]
	v_mfma_f32_16x16x32_bf16 v[0:3], v[226:229], v[36:39], v[174:177]
	v_mfma_f32_16x16x32_bf16 v[40:43], v[230:233], v[218:221], v[0:3]
	v_mfma_f32_16x16x32_bf16 v[0:3], v[234:237], v[36:39], v[178:181]
	v_mfma_f32_16x16x32_bf16 v[8:11], v[238:241], v[218:221], v[0:3]
	v_mfma_f32_16x16x32_bf16 v[0:3], v[226:229], v[222:225], v[182:185]
	v_mfma_f32_16x16x32_bf16 v[36:39], v[230:233], v[242:245], v[0:3]
	v_mfma_f32_16x16x32_bf16 v[0:3], v[234:237], v[222:225], v[190:193]
	v_mfma_f32_16x16x32_bf16 v[4:7], v[238:241], v[242:245], v[0:3]
	v_mfma_f32_16x16x32_bf16 v[0:3], v[226:229], v[246:249], v[194:197]
	v_mfma_f32_16x16x32_bf16 v[32:35], v[230:233], v[250:253], v[0:3]
	v_mfma_f32_16x16x32_bf16 v[0:3], v[234:237], v[246:249], v[198:201]
	v_mfma_f32_16x16x32_bf16 v[0:3], v[238:241], v[250:253], v[0:3]
	s_setprio 0
	v_lshl_add_u32 v152, s44, 8, v168
	v_lshl_or_b32 v144, s89, 8, v170
	v_or_b32_e32 v150, 16, v152
	v_or_b32_e32 v148, 32, v152
	v_or_b32_e32 v146, 48, v152
	s_mov_b64 s[44:45], -1
	s_cmp_lt_i32 s89, 4
	v_ashrrev_i32_e32 v145, 31, v144
	v_ashrrev_i32_e32 v153, 31, v152
	v_ashrrev_i32_e32 v151, 31, v150
	v_ashrrev_i32_e32 v149, 31, v148
	v_ashrrev_i32_e32 v147, 31, v146
	s_barrier
	s_cbranch_scc1 .LBB0_768
	v_lshlrev_b64 v[140:141], 2, v[144:145]
	v_lshl_add_u64 v[156:157], s[36:37], 0, v[140:141]
	global_load_dwordx4 v[128:131], v[156:157], off
	v_lshlrev_b64 v[142:143], 12, v[152:153]
	v_lshlrev_b64 v[154:155], 12, v[150:151]
	v_lshlrev_b64 v[158:159], 12, v[148:149]
	v_lshl_add_u64 v[142:143], s[8:9], 0, v[142:143]
	v_lshl_add_u64 v[154:155], s[8:9], 0, v[154:155]
	v_lshl_add_u64 v[162:163], s[8:9], 0, v[158:159]
	v_lshl_add_u64 v[160:161], v[142:143], 0, v[140:141]
	v_lshl_add_u64 v[158:159], v[154:155], 0, v[140:141]
	v_lshl_add_u64 v[154:155], v[162:163], 0, v[140:141]
	s_mov_b64 s[44:45], 0
	s_waitcnt vmcnt(0)
	v_add_f32_e32 v142, v120, v128
	v_add_f32_e32 v143, v121, v129
	v_add_f32_e32 v162, v122, v130
	v_add_f32_e32 v163, v123, v131
	v_add_f32_e32 v164, v124, v128
	v_add_f32_e32 v165, v125, v129
	v_mul_f32_e32 v142, 0xbfb8aa3b, v142
	v_mul_f32_e32 v143, 0xbfb8aa3b, v143
	v_mul_f32_e32 v162, 0xbfb8aa3b, v162
	v_mul_f32_e32 v163, 0xbfb8aa3b, v163
	v_mul_f32_e32 v164, 0xbfb8aa3b, v164
	v_mul_f32_e32 v165, 0xbfb8aa3b, v165
	v_exp_f32_e32 v142, v142
	v_exp_f32_e32 v143, v143
	v_exp_f32_e32 v162, v162
	v_exp_f32_e32 v163, v163
	v_exp_f32_e32 v164, v164
	v_exp_f32_e32 v165, v165
	v_add_f32_e32 v142, 1.0, v142
	v_add_f32_e32 v143, 1.0, v143
	v_add_f32_e32 v182, 1.0, v162
	v_add_f32_e32 v183, 1.0, v163
	v_add_f32_e32 v166, v126, v130
	v_add_f32_e32 v167, v127, v131
	v_add_f32_e32 v184, 1.0, v164
	v_add_f32_e32 v185, 1.0, v165
	v_rcp_f32_e32 v162, v142
	v_rcp_f32_e32 v163, v143
	v_rcp_f32_e32 v164, v182
	v_rcp_f32_e32 v165, v183
	v_add_f32_e32 v174, v116, v128
	v_add_f32_e32 v175, v117, v129
	v_add_f32_e32 v176, v118, v130
	v_add_f32_e32 v177, v119, v131
	v_mul_f32_e32 v166, 0xbfb8aa3b, v166
	v_mul_f32_e32 v167, 0xbfb8aa3b, v167
	v_mul_f32_e32 v174, 0xbfb8aa3b, v174
	v_mul_f32_e32 v175, 0xbfb8aa3b, v175
	v_mul_f32_e32 v176, 0xbfb8aa3b, v176
	v_mul_f32_e32 v177, 0xbfb8aa3b, v177
	v_exp_f32_e32 v166, v166
	v_exp_f32_e32 v167, v167
	v_lshlrev_b64 v[142:143], 12, v[146:147]
	v_exp_f32_e32 v174, v174
	v_exp_f32_e32 v175, v175
	v_exp_f32_e32 v176, v176
	v_exp_f32_e32 v177, v177
	v_lshl_add_u64 v[142:143], s[8:9], 0, v[142:143]
	global_store_dwordx4 v[160:161], v[162:165], off offset:-4096
	v_add_f32_e32 v166, 1.0, v166
	v_add_f32_e32 v167, 1.0, v167
	v_lshl_add_u64 v[162:163], v[142:143], 0, v[140:141]
	v_add_f32_e32 v140, v112, v128
	v_mul_f32_e32 v140, 0xbfb8aa3b, v140
	v_add_f32_e32 v141, v113, v129
	v_exp_f32_e32 v140, v140
	v_mul_f32_e32 v141, 0xbfb8aa3b, v141
	v_add_f32_e32 v186, 1.0, v174
	v_add_f32_e32 v187, 1.0, v175
	v_add_f32_e32 v188, 1.0, v176
	v_add_f32_e32 v189, 1.0, v177
; __device__ __forceinline__ float sigmoidf_(float x) { return __builtin_amdgcn_rcpf(1.0f + __expf(-x)); }
;     __device__ __forceinline__ void operator()(const AccT& acc, const Unit& u, int wr, int wc, int fr, int fq) const {
;     ...
;             for (int bj = 0; bj < 2; ++bj)
; #pragma unroll
;                 for (int n = 0; n < 2; ++n) { const int col = col0 - 1024 + bj * 128 + n * 16; const f32x4 av0 = *(const f32x4*)(a0 + col);
; #pragma unroll
;                     for (int ai = 0; ai < 2; ++ai)
; #pragma unroll
;                         for (int m = 0; m < 4; ++m) { const int row = row0 + ai * 128 + m * 16; f32x4 o;
; #pragma unroll
;                             for (int j = 0; j < 4; ++j) o[j] = sigmoidf_(av0[j] + acc[ai][bj][m][n][j]);
;                             *(f32x4*)(IC + (size_t)row * RW + col) = o; asm volatile("" ::: "memory"); } }
	v_rcp_f32_e32 v174, v184
	v_rcp_f32_e32 v175, v185
	v_rcp_f32_e32 v176, v166
	v_rcp_f32_e32 v177, v167
	v_exp_f32_e32 v141, v141
	v_add_f32_e32 v140, 1.0, v140
	global_store_dwordx4 v[158:159], v[174:177], off offset:-4096
	v_add_f32_e32 v142, v115, v131
	v_mul_f32_e32 v142, 0xbfb8aa3b, v142
	v_rcp_f32_e32 v174, v140
	v_add_f32_e32 v140, 1.0, v141
	v_add_f32_e32 v141, v114, v130
	v_mul_f32_e32 v141, 0xbfb8aa3b, v141
	v_exp_f32_e32 v141, v141
	v_exp_f32_e32 v142, v142
	v_add_f32_e32 v178, v108, v128
	v_add_f32_e32 v179, v109, v129
	v_add_f32_e32 v180, v110, v130
	v_add_f32_e32 v181, v111, v131
	v_mul_f32_e32 v178, 0xbfb8aa3b, v178
	v_mul_f32_e32 v179, 0xbfb8aa3b, v179
	v_mul_f32_e32 v180, 0xbfb8aa3b, v180
	v_mul_f32_e32 v181, 0xbfb8aa3b, v181
	v_rcp_f32_e32 v175, v140
	v_add_f32_e32 v140, 1.0, v141
	v_exp_f32_e32 v178, v178
	v_exp_f32_e32 v179, v179
	v_exp_f32_e32 v180, v180
	v_exp_f32_e32 v181, v181
	v_rcp_f32_e32 v176, v140
	v_add_f32_e32 v140, 1.0, v142
	v_rcp_f32_e32 v177, v140
	v_add_f32_e32 v140, v104, v128
	v_mul_f32_e32 v140, 0xbfb8aa3b, v140
	v_add_f32_e32 v141, v105, v129
	v_exp_f32_e32 v140, v140
	v_mul_f32_e32 v141, 0xbfb8aa3b, v141
	v_add_f32_e32 v190, 1.0, v178
	v_add_f32_e32 v191, 1.0, v179
	v_add_f32_e32 v192, 1.0, v180
	v_add_f32_e32 v193, 1.0, v181
	v_rcp_f32_e32 v178, v186
	v_rcp_f32_e32 v179, v187
	v_rcp_f32_e32 v180, v188
	v_rcp_f32_e32 v181, v189
	v_exp_f32_e32 v141, v141
	v_add_f32_e32 v140, 1.0, v140
	global_store_dwordx4 v[154:155], v[178:181], off offset:-4096
	v_add_f32_e32 v142, v107, v131
	v_mul_f32_e32 v142, 0xbfb8aa3b, v142
	v_rcp_f32_e32 v178, v140
	v_add_f32_e32 v140, 1.0, v141
	v_add_f32_e32 v141, v106, v130
	v_mul_f32_e32 v141, 0xbfb8aa3b, v141
	v_exp_f32_e32 v141, v141
	v_exp_f32_e32 v142, v142
	v_rcp_f32_e32 v179, v140
	v_rcp_f32_e32 v182, v190
	v_add_f32_e32 v140, 1.0, v141
	v_rcp_f32_e32 v180, v140
	v_add_f32_e32 v140, 1.0, v142
	v_rcp_f32_e32 v181, v140
	v_add_f32_e32 v140, v100, v128
	v_mul_f32_e32 v140, 0xbfb8aa3b, v140
	v_add_f32_e32 v141, v101, v129
	v_rcp_f32_e32 v183, v191
	v_rcp_f32_e32 v184, v192
	v_rcp_f32_e32 v185, v193
	v_exp_f32_e32 v140, v140
	v_mul_f32_e32 v141, 0xbfb8aa3b, v141
	v_exp_f32_e32 v141, v141
	global_store_dwordx4 v[162:163], v[182:185], off offset:-4096
	v_lshl_add_u64 v[166:167], v[160:161], 0, s[18:19]
	v_add_f32_e32 v140, 1.0, v140
	global_store_dwordx4 v[166:167], v[174:177], off offset:-4096
	v_add_f32_e32 v142, v103, v131
	v_mul_f32_e32 v142, 0xbfb8aa3b, v142
	v_rcp_f32_e32 v174, v140
	v_add_f32_e32 v140, 1.0, v141
	v_add_f32_e32 v141, v102, v130
	v_mul_f32_e32 v141, 0xbfb8aa3b, v141
	v_exp_f32_e32 v141, v141
	v_exp_f32_e32 v142, v142
	v_rcp_f32_e32 v175, v140
	v_add_f32_e32 v128, v96, v128
	v_add_f32_e32 v140, 1.0, v141
	v_rcp_f32_e32 v176, v140
	v_add_f32_e32 v140, 1.0, v142
	v_mul_f32_e32 v128, 0xbfb8aa3b, v128
	v_add_f32_e32 v130, v98, v130
	v_rcp_f32_e32 v177, v140
	v_exp_f32_e32 v140, v128
	v_add_f32_e32 v128, v97, v129
	v_mul_f32_e32 v130, 0xbfb8aa3b, v130
	v_add_f32_e32 v131, v99, v131
	v_mul_f32_e32 v128, 0xbfb8aa3b, v128
	v_exp_f32_e32 v130, v130
	v_mul_f32_e32 v131, 0xbfb8aa3b, v131
	v_exp_f32_e32 v141, v128
	v_exp_f32_e32 v131, v131
	v_lshl_add_u64 v[164:165], v[160:161], 0, s[20:21]
	v_add_f32_e32 v140, 1.0, v140
	v_add_f32_e32 v130, 1.0, v130
	global_store_dwordx4 v[164:165], v[178:181], off offset:-4096
	v_lshl_add_u64 v[128:129], v[160:161], 0, s[22:23]
	global_store_dwordx4 v[128:129], v[174:177], off offset:-4096
	v_rcp_f32_e32 v178, v140
	v_add_f32_e32 v140, 1.0, v141
	v_rcp_f32_e32 v180, v130
	v_add_f32_e32 v130, 1.0, v131
	v_rcp_f32_e32 v179, v140
	v_rcp_f32_e32 v181, v130
	v_lshl_add_u64 v[130:131], v[160:161], 0, s[24:25]
	global_store_dwordx4 v[130:131], v[178:181], off offset:-4096
	global_load_dwordx4 v[174:177], v[156:157], off offset:64
	s_waitcnt vmcnt(0)
	v_add_f32_e32 v140, v92, v174
	v_mul_f32_e32 v140, 0xbfb8aa3b, v140
	v_add_f32_e32 v141, v93, v175
	v_exp_f32_e32 v140, v140
	v_mul_f32_e32 v141, 0xbfb8aa3b, v141
	v_exp_f32_e32 v141, v141
	v_add_f32_e32 v142, v95, v177
	v_add_f32_e32 v140, 1.0, v140
	v_rcp_f32_e32 v178, v140
	v_add_f32_e32 v140, 1.0, v141
	v_add_f32_e32 v141, v94, v176
	v_mul_f32_e32 v141, 0xbfb8aa3b, v141
	v_exp_f32_e32 v141, v141
	v_mul_f32_e32 v142, 0xbfb8aa3b, v142
	v_exp_f32_e32 v142, v142
	v_rcp_f32_e32 v179, v140
	v_add_f32_e32 v140, 1.0, v141
	v_add_f32_e32 v141, v88, v174
	v_rcp_f32_e32 v180, v140
	v_add_f32_e32 v140, 1.0, v142
	v_mul_f32_e32 v141, 0xbfb8aa3b, v141
	v_add_f32_e32 v142, v89, v175
	v_exp_f32_e32 v141, v141
	v_mul_f32_e32 v142, 0xbfb8aa3b, v142
	v_exp_f32_e32 v142, v142
	v_rcp_f32_e32 v181, v140
	v_add_f32_e32 v140, 1.0, v141
	v_add_f32_e32 v141, v90, v176
	v_rcp_f32_e32 v182, v140
	v_add_f32_e32 v140, 1.0, v142
	v_mul_f32_e32 v141, 0xbfb8aa3b, v141
	v_add_f32_e32 v142, v91, v177
	v_exp_f32_e32 v141, v141
	v_mul_f32_e32 v142, 0xbfb8aa3b, v142
	v_exp_f32_e32 v142, v142
	v_rcp_f32_e32 v183, v140
	v_add_f32_e32 v140, 1.0, v141
	v_rcp_f32_e32 v184, v140
	v_add_f32_e32 v140, 1.0, v142
	v_rcp_f32_e32 v185, v140
	v_add_f32_e32 v140, v84, v174
	v_mul_f32_e32 v140, 0xbfb8aa3b, v140
	v_add_f32_e32 v141, v85, v175
	v_exp_f32_e32 v140, v140
	v_mul_f32_e32 v141, 0xbfb8aa3b, v141
	v_exp_f32_e32 v141, v141
	global_store_dwordx4 v[160:161], v[178:181], off offset:-4032
	v_add_f32_e32 v140, 1.0, v140
	v_add_f32_e32 v142, v87, v177
	v_rcp_f32_e32 v178, v140
	v_add_f32_e32 v140, 1.0, v141
	v_add_f32_e32 v141, v86, v176
	v_mul_f32_e32 v141, 0xbfb8aa3b, v141
	v_exp_f32_e32 v141, v141
	v_mul_f32_e32 v142, 0xbfb8aa3b, v142
	v_exp_f32_e32 v142, v142
	v_rcp_f32_e32 v179, v140
	v_add_f32_e32 v140, 1.0, v141
; __device__ __forceinline__ float sigmoidf_(float x) { return __builtin_amdgcn_rcpf(1.0f + __expf(-x)); }
;     __device__ __forceinline__ void operator()(const AccT& acc, const Unit& u, int wr, int wc, int fr, int fq) const {
;     ...
;             for (int bj = 0; bj < 2; ++bj)
; #pragma unroll
;                 for (int n = 0; n < 2; ++n) { const int col = col0 - 1024 + bj * 128 + n * 16; const f32x4 av0 = *(const f32x4*)(a0 + col);
; #pragma unroll
;                     for (int ai = 0; ai < 2; ++ai)
; #pragma unroll
;                         for (int m = 0; m < 4; ++m) { const int row = row0 + ai * 128 + m * 16; f32x4 o;
; #pragma unroll
;                             for (int j = 0; j < 4; ++j) o[j] = sigmoidf_(av0[j] + acc[ai][bj][m][n][j]);
;                             *(f32x4*)(IC + (size_t)row * RW + col) = o; asm volatile("" ::: "memory"); } }
	v_rcp_f32_e32 v180, v140
	v_add_f32_e32 v140, 1.0, v142
	v_rcp_f32_e32 v181, v140
	v_add_f32_e32 v140, v76, v174
	v_mul_f32_e32 v140, 0xbfb8aa3b, v140
	v_add_f32_e32 v141, v77, v175
	v_exp_f32_e32 v140, v140
	v_mul_f32_e32 v141, 0xbfb8aa3b, v141
	v_exp_f32_e32 v141, v141
	global_store_dwordx4 v[158:159], v[182:185], off offset:-4032
	v_add_f32_e32 v140, 1.0, v140
	global_store_dwordx4 v[154:155], v[178:181], off offset:-4032
	v_add_f32_e32 v142, v79, v177
	v_mul_f32_e32 v142, 0xbfb8aa3b, v142
	v_rcp_f32_e32 v178, v140
	v_add_f32_e32 v140, 1.0, v141
	v_add_f32_e32 v141, v78, v176
	v_mul_f32_e32 v141, 0xbfb8aa3b, v141
	v_exp_f32_e32 v141, v141
	v_exp_f32_e32 v142, v142
	v_rcp_f32_e32 v179, v140
	v_add_f32_e32 v140, 1.0, v141
	v_add_f32_e32 v141, v80, v174
	v_rcp_f32_e32 v180, v140
	v_add_f32_e32 v140, 1.0, v142
	v_mul_f32_e32 v141, 0xbfb8aa3b, v141
	v_add_f32_e32 v142, v81, v175
	v_exp_f32_e32 v141, v141
	v_mul_f32_e32 v142, 0xbfb8aa3b, v142
	v_exp_f32_e32 v142, v142
	v_rcp_f32_e32 v181, v140
	v_add_f32_e32 v140, 1.0, v141
	v_add_f32_e32 v141, v82, v176
	v_rcp_f32_e32 v182, v140
	v_add_f32_e32 v140, 1.0, v142
	v_mul_f32_e32 v141, 0xbfb8aa3b, v141
	v_add_f32_e32 v142, v83, v177
	v_exp_f32_e32 v141, v141
	v_mul_f32_e32 v142, 0xbfb8aa3b, v142
	v_exp_f32_e32 v142, v142
	v_rcp_f32_e32 v183, v140
	v_add_f32_e32 v140, 1.0, v141
	v_rcp_f32_e32 v184, v140
	v_add_f32_e32 v140, 1.0, v142
	v_rcp_f32_e32 v185, v140
	v_add_f32_e32 v140, v72, v174
	v_mul_f32_e32 v140, 0xbfb8aa3b, v140
	v_add_f32_e32 v141, v73, v175
	v_exp_f32_e32 v140, v140
	v_mul_f32_e32 v141, 0xbfb8aa3b, v141
	v_exp_f32_e32 v141, v141
	global_store_dwordx4 v[162:163], v[178:181], off offset:-4032
	v_add_f32_e32 v140, 1.0, v140
	v_add_f32_e32 v142, v75, v177
	v_rcp_f32_e32 v178, v140
	v_add_f32_e32 v140, 1.0, v141
	v_add_f32_e32 v141, v74, v176
	v_mul_f32_e32 v141, 0xbfb8aa3b, v141
	v_exp_f32_e32 v141, v141
	v_mul_f32_e32 v142, 0xbfb8aa3b, v142
	v_exp_f32_e32 v142, v142
	v_rcp_f32_e32 v179, v140
	v_add_f32_e32 v140, 1.0, v141
	v_rcp_f32_e32 v180, v140
	v_add_f32_e32 v140, 1.0, v142
	v_rcp_f32_e32 v181, v140
	v_add_f32_e32 v140, v68, v174
	v_mul_f32_e32 v140, 0xbfb8aa3b, v140
	v_add_f32_e32 v141, v69, v175
	v_exp_f32_e32 v140, v140
	v_mul_f32_e32 v141, 0xbfb8aa3b, v141
	v_exp_f32_e32 v141, v141
	global_store_dwordx4 v[166:167], v[182:185], off offset:-4032
	v_add_f32_e32 v140, 1.0, v140
	global_store_dwordx4 v[164:165], v[178:181], off offset:-4032
	v_add_f32_e32 v142, v71, v177
	v_mul_f32_e32 v142, 0xbfb8aa3b, v142
	v_rcp_f32_e32 v178, v140
	v_add_f32_e32 v140, 1.0, v141
	v_add_f32_e32 v141, v70, v176
	v_mul_f32_e32 v141, 0xbfb8aa3b, v141
	v_exp_f32_e32 v141, v141
	v_exp_f32_e32 v142, v142
	v_rcp_f32_e32 v179, v140
	v_add_f32_e32 v140, 1.0, v141
	v_add_f32_e32 v141, v64, v174
	v_rcp_f32_e32 v180, v140
	v_add_f32_e32 v140, 1.0, v142
	v_mul_f32_e32 v141, 0xbfb8aa3b, v141
	v_add_f32_e32 v142, v65, v175
	v_exp_f32_e32 v141, v141
	v_mul_f32_e32 v142, 0xbfb8aa3b, v142
	v_exp_f32_e32 v142, v142
	v_rcp_f32_e32 v181, v140
	v_add_f32_e32 v140, 1.0, v141
	v_add_f32_e32 v141, v66, v176
	v_rcp_f32_e32 v174, v140
	v_add_f32_e32 v140, 1.0, v142
	v_mul_f32_e32 v141, 0xbfb8aa3b, v141
	v_add_f32_e32 v142, v67, v177
	v_exp_f32_e32 v141, v141
	v_mul_f32_e32 v142, 0xbfb8aa3b, v142
	v_exp_f32_e32 v142, v142
	v_rcp_f32_e32 v175, v140
	v_add_f32_e32 v140, 1.0, v141
	v_rcp_f32_e32 v176, v140
	v_add_f32_e32 v140, 1.0, v142
	v_rcp_f32_e32 v177, v140
	global_store_dwordx4 v[128:129], v[178:181], off offset:-4032
	global_store_dwordx4 v[130:131], v[174:177], off offset:-4032
	global_load_dwordx4 v[174:177], v[156:157], off offset:512
	s_waitcnt vmcnt(0)
	v_add_f32_e32 v140, v60, v174
	v_mul_f32_e32 v140, 0xbfb8aa3b, v140
	v_add_f32_e32 v141, v61, v175
	v_exp_f32_e32 v140, v140
	v_mul_f32_e32 v141, 0xbfb8aa3b, v141
	v_exp_f32_e32 v141, v141
	v_add_f32_e32 v142, v63, v177
	v_add_f32_e32 v140, 1.0, v140
	v_rcp_f32_e32 v178, v140
	v_add_f32_e32 v140, 1.0, v141
	v_add_f32_e32 v141, v62, v176
	v_mul_f32_e32 v141, 0xbfb8aa3b, v141
	v_exp_f32_e32 v141, v141
	v_mul_f32_e32 v142, 0xbfb8aa3b, v142
	v_exp_f32_e32 v142, v142
	v_rcp_f32_e32 v179, v140
	v_add_f32_e32 v140, 1.0, v141
	v_add_f32_e32 v141, v56, v174
	v_rcp_f32_e32 v180, v140
	v_add_f32_e32 v140, 1.0, v142
	v_mul_f32_e32 v141, 0xbfb8aa3b, v141
	v_add_f32_e32 v142, v57, v175
	v_exp_f32_e32 v141, v141
	v_mul_f32_e32 v142, 0xbfb8aa3b, v142
	v_exp_f32_e32 v142, v142
	v_rcp_f32_e32 v181, v140
	v_add_f32_e32 v140, 1.0, v141
	v_add_f32_e32 v141, v58, v176
	v_rcp_f32_e32 v182, v140
	v_add_f32_e32 v140, 1.0, v142
	v_mul_f32_e32 v141, 0xbfb8aa3b, v141
	v_add_f32_e32 v142, v59, v177
	v_exp_f32_e32 v141, v141
	v_mul_f32_e32 v142, 0xbfb8aa3b, v142
	v_exp_f32_e32 v142, v142
	v_rcp_f32_e32 v183, v140
	v_add_f32_e32 v140, 1.0, v141
	v_rcp_f32_e32 v184, v140
	v_add_f32_e32 v140, 1.0, v142
	v_rcp_f32_e32 v185, v140
	v_add_f32_e32 v140, v52, v174
	v_mul_f32_e32 v140, 0xbfb8aa3b, v140
	v_add_f32_e32 v141, v53, v175
	v_exp_f32_e32 v140, v140
	v_mul_f32_e32 v141, 0xbfb8aa3b, v141
	v_exp_f32_e32 v141, v141
	global_store_dwordx4 v[160:161], v[178:181], off offset:-3584
	v_add_f32_e32 v140, 1.0, v140
	v_add_f32_e32 v142, v55, v177
	v_rcp_f32_e32 v178, v140
	v_add_f32_e32 v140, 1.0, v141
	v_add_f32_e32 v141, v54, v176
	v_mul_f32_e32 v141, 0xbfb8aa3b, v141
	v_exp_f32_e32 v141, v141
	v_mul_f32_e32 v142, 0xbfb8aa3b, v142
	v_exp_f32_e32 v142, v142
	v_rcp_f32_e32 v179, v140
	v_add_f32_e32 v140, 1.0, v141
	v_rcp_f32_e32 v180, v140
	v_add_f32_e32 v140, 1.0, v142
	v_rcp_f32_e32 v181, v140
	v_add_f32_e32 v140, v44, v174
	v_mul_f32_e32 v140, 0xbfb8aa3b, v140
	v_add_f32_e32 v141, v45, v175
; __device__ __forceinline__ float sigmoidf_(float x) { return __builtin_amdgcn_rcpf(1.0f + __expf(-x)); }
;     __device__ __forceinline__ void operator()(const AccT& acc, const Unit& u, int wr, int wc, int fr, int fq) const {
;     ...
;             for (int bj = 0; bj < 2; ++bj)
; #pragma unroll
;                 for (int n = 0; n < 2; ++n) { const int col = col0 - 1024 + bj * 128 + n * 16; const f32x4 av0 = *(const f32x4*)(a0 + col);
; #pragma unroll
;                     for (int ai = 0; ai < 2; ++ai)
; #pragma unroll
;                         for (int m = 0; m < 4; ++m) { const int row = row0 + ai * 128 + m * 16; f32x4 o;
; #pragma unroll
;                             for (int j = 0; j < 4; ++j) o[j] = sigmoidf_(av0[j] + acc[ai][bj][m][n][j]);
;                             *(f32x4*)(IC + (size_t)row * RW + col) = o; asm volatile("" ::: "memory"); } }
	v_exp_f32_e32 v140, v140
	v_mul_f32_e32 v141, 0xbfb8aa3b, v141
	v_exp_f32_e32 v141, v141
	global_store_dwordx4 v[158:159], v[182:185], off offset:-3584
	v_add_f32_e32 v140, 1.0, v140
	global_store_dwordx4 v[154:155], v[178:181], off offset:-3584
	v_add_f32_e32 v142, v47, v177
	v_mul_f32_e32 v142, 0xbfb8aa3b, v142
	v_rcp_f32_e32 v178, v140
	v_add_f32_e32 v140, 1.0, v141
	v_add_f32_e32 v141, v46, v176
	v_mul_f32_e32 v141, 0xbfb8aa3b, v141
	v_exp_f32_e32 v141, v141
	v_exp_f32_e32 v142, v142
	v_rcp_f32_e32 v179, v140
	v_add_f32_e32 v140, 1.0, v141
	v_add_f32_e32 v141, v48, v174
	v_rcp_f32_e32 v180, v140
	v_add_f32_e32 v140, 1.0, v142
	v_mul_f32_e32 v141, 0xbfb8aa3b, v141
	v_add_f32_e32 v142, v49, v175
	v_exp_f32_e32 v141, v141
	v_mul_f32_e32 v142, 0xbfb8aa3b, v142
	v_exp_f32_e32 v142, v142
	v_rcp_f32_e32 v181, v140
	v_add_f32_e32 v140, 1.0, v141
	v_add_f32_e32 v141, v50, v176
	v_rcp_f32_e32 v182, v140
	v_add_f32_e32 v140, 1.0, v142
	v_mul_f32_e32 v141, 0xbfb8aa3b, v141
	v_add_f32_e32 v142, v51, v177
	v_exp_f32_e32 v141, v141
	v_mul_f32_e32 v142, 0xbfb8aa3b, v142
	v_exp_f32_e32 v142, v142
	v_rcp_f32_e32 v183, v140
	v_add_f32_e32 v140, 1.0, v141
	v_rcp_f32_e32 v184, v140
	v_add_f32_e32 v140, 1.0, v142
	v_rcp_f32_e32 v185, v140
	v_add_f32_e32 v140, v40, v174
	v_mul_f32_e32 v140, 0xbfb8aa3b, v140
	v_add_f32_e32 v141, v41, v175
	v_exp_f32_e32 v140, v140
	v_mul_f32_e32 v141, 0xbfb8aa3b, v141
	v_exp_f32_e32 v141, v141
	global_store_dwordx4 v[162:163], v[178:181], off offset:-3584
	v_add_f32_e32 v140, 1.0, v140
	v_add_f32_e32 v142, v43, v177
	v_rcp_f32_e32 v178, v140
	v_add_f32_e32 v140, 1.0, v141
	v_add_f32_e32 v141, v42, v176
	v_mul_f32_e32 v141, 0xbfb8aa3b, v141
	v_exp_f32_e32 v141, v141
	v_mul_f32_e32 v142, 0xbfb8aa3b, v142
	v_exp_f32_e32 v142, v142
	v_rcp_f32_e32 v179, v140
	v_add_f32_e32 v140, 1.0, v141
	v_rcp_f32_e32 v180, v140
	v_add_f32_e32 v140, 1.0, v142
	v_rcp_f32_e32 v181, v140
	v_add_f32_e32 v140, v36, v174
	v_mul_f32_e32 v140, 0xbfb8aa3b, v140
	v_add_f32_e32 v141, v37, v175
	v_exp_f32_e32 v140, v140
	v_mul_f32_e32 v141, 0xbfb8aa3b, v141
	v_exp_f32_e32 v141, v141
	global_store_dwordx4 v[166:167], v[182:185], off offset:-3584
	v_add_f32_e32 v140, 1.0, v140
	global_store_dwordx4 v[164:165], v[178:181], off offset:-3584
	v_add_f32_e32 v142, v39, v177
	v_mul_f32_e32 v142, 0xbfb8aa3b, v142
	v_rcp_f32_e32 v178, v140
	v_add_f32_e32 v140, 1.0, v141
	v_add_f32_e32 v141, v38, v176
	v_mul_f32_e32 v141, 0xbfb8aa3b, v141
	v_exp_f32_e32 v141, v141
	v_exp_f32_e32 v142, v142
	v_rcp_f32_e32 v179, v140
	v_add_f32_e32 v140, 1.0, v141
	v_add_f32_e32 v141, v32, v174
	v_rcp_f32_e32 v180, v140
	v_add_f32_e32 v140, 1.0, v142
	v_mul_f32_e32 v141, 0xbfb8aa3b, v141
	v_add_f32_e32 v142, v33, v175
	v_exp_f32_e32 v141, v141
	v_mul_f32_e32 v142, 0xbfb8aa3b, v142
	v_exp_f32_e32 v142, v142
	v_rcp_f32_e32 v181, v140
	v_add_f32_e32 v140, 1.0, v141
	v_add_f32_e32 v141, v34, v176
	v_rcp_f32_e32 v174, v140
	v_add_f32_e32 v140, 1.0, v142
	v_mul_f32_e32 v141, 0xbfb8aa3b, v141
	v_add_f32_e32 v142, v35, v177
	v_exp_f32_e32 v141, v141
	v_mul_f32_e32 v142, 0xbfb8aa3b, v142
	v_exp_f32_e32 v142, v142
	v_rcp_f32_e32 v175, v140
	v_add_f32_e32 v140, 1.0, v141
	v_rcp_f32_e32 v176, v140
	v_add_f32_e32 v140, 1.0, v142
	v_rcp_f32_e32 v177, v140
	global_store_dwordx4 v[128:129], v[178:181], off offset:-3584
	global_store_dwordx4 v[130:131], v[174:177], off offset:-3584
	global_load_dwordx4 v[174:177], v[156:157], off offset:576
	s_waitcnt vmcnt(0)
; __device__ __forceinline__ float sigmoidf_(float x) { return __builtin_amdgcn_rcpf(1.0f + __expf(-x)); }
;     __device__ __forceinline__ void operator()(const AccT& acc, const Unit& u, int wr, int wc, int fr, int fq) const {
;     ...
;             for (int bj = 0; bj < 2; ++bj)
; #pragma unroll
;                 for (int n = 0; n < 2; ++n) { const int col = col0 - 1024 + bj * 128 + n * 16; const f32x4 av0 = *(const f32x4*)(a0 + col);
; #pragma unroll
;                     for (int ai = 0; ai < 2; ++ai)
; #pragma unroll
;                         for (int m = 0; m < 4; ++m) { const int row = row0 + ai * 128 + m * 16; f32x4 o;
; #pragma unroll
;                             for (int j = 0; j < 4; ++j) o[j] = sigmoidf_(av0[j] + acc[ai][bj][m][n][j]);
;                             *(f32x4*)(IC + (size_t)row * RW + col) = o; asm volatile("" ::: "memory"); } }
	v_add_f32_e32 v140, v28, v174
	v_mul_f32_e32 v140, 0xbfb8aa3b, v140
	v_add_f32_e32 v141, v29, v175
	v_exp_f32_e32 v140, v140
	v_mul_f32_e32 v141, 0xbfb8aa3b, v141
	v_exp_f32_e32 v141, v141
	v_add_f32_e32 v142, v31, v177
	v_add_f32_e32 v140, 1.0, v140
	v_rcp_f32_e32 v178, v140
	v_add_f32_e32 v140, 1.0, v141
	v_add_f32_e32 v141, v30, v176
	v_mul_f32_e32 v141, 0xbfb8aa3b, v141
	v_exp_f32_e32 v141, v141
	v_mul_f32_e32 v142, 0xbfb8aa3b, v142
	v_exp_f32_e32 v142, v142
	v_rcp_f32_e32 v179, v140
	v_add_f32_e32 v140, 1.0, v141
	v_add_f32_e32 v141, v24, v174
	v_rcp_f32_e32 v180, v140
	v_add_f32_e32 v140, 1.0, v142
	v_mul_f32_e32 v141, 0xbfb8aa3b, v141
	v_add_f32_e32 v142, v25, v175
	v_exp_f32_e32 v141, v141
	v_mul_f32_e32 v142, 0xbfb8aa3b, v142
	v_exp_f32_e32 v142, v142
	v_rcp_f32_e32 v181, v140
	v_add_f32_e32 v140, 1.0, v141
	v_add_f32_e32 v141, v26, v176
	v_rcp_f32_e32 v182, v140
	v_add_f32_e32 v140, 1.0, v142
	v_mul_f32_e32 v141, 0xbfb8aa3b, v141
	v_add_f32_e32 v142, v27, v177
	v_exp_f32_e32 v141, v141
	v_mul_f32_e32 v142, 0xbfb8aa3b, v142
	v_exp_f32_e32 v142, v142
	v_rcp_f32_e32 v183, v140
	v_add_f32_e32 v140, 1.0, v141
	v_rcp_f32_e32 v184, v140
	v_add_f32_e32 v140, 1.0, v142
	v_rcp_f32_e32 v185, v140
	v_add_f32_e32 v140, v20, v174
	v_mul_f32_e32 v140, 0xbfb8aa3b, v140
	v_add_f32_e32 v141, v21, v175
	v_exp_f32_e32 v140, v140
	v_mul_f32_e32 v141, 0xbfb8aa3b, v141
	v_exp_f32_e32 v141, v141
	v_add_f32_e32 v142, v23, v177
	v_add_f32_e32 v140, 1.0, v140
	v_rcp_f32_e32 v156, v140
	v_add_f32_e32 v140, 1.0, v141
	v_add_f32_e32 v141, v22, v176
	v_mul_f32_e32 v141, 0xbfb8aa3b, v141
	v_exp_f32_e32 v141, v141
	v_mul_f32_e32 v142, 0xbfb8aa3b, v142
	v_exp_f32_e32 v142, v142
	global_store_dwordx4 v[160:161], v[178:181], off offset:-3520
	v_rcp_f32_e32 v157, v140
	v_add_f32_e32 v140, 1.0, v141
	global_store_dwordx4 v[158:159], v[182:185], off offset:-3520
	v_rcp_f32_e32 v158, v140
	v_add_f32_e32 v140, 1.0, v142
	v_rcp_f32_e32 v159, v140
	v_add_f32_e32 v140, v12, v174
	v_mul_f32_e32 v140, 0xbfb8aa3b, v140
	v_add_f32_e32 v141, v13, v175
	v_exp_f32_e32 v140, v140
	v_mul_f32_e32 v141, 0xbfb8aa3b, v141
	v_exp_f32_e32 v141, v141
	v_add_f32_e32 v140, 1.0, v140
	global_store_dwordx4 v[154:155], v[156:159], off offset:-3520
	v_rcp_f32_e32 v154, v140
	v_add_f32_e32 v140, 1.0, v141
	v_add_f32_e32 v141, v14, v176
	v_mul_f32_e32 v141, 0xbfb8aa3b, v141
	v_add_f32_e32 v142, v15, v177
	v_exp_f32_e32 v141, v141
	v_mul_f32_e32 v142, 0xbfb8aa3b, v142
	v_exp_f32_e32 v142, v142
	v_rcp_f32_e32 v155, v140
	v_add_f32_e32 v140, 1.0, v141
	v_add_f32_e32 v141, v16, v174
	v_rcp_f32_e32 v156, v140
	v_add_f32_e32 v140, 1.0, v142
	v_mul_f32_e32 v141, 0xbfb8aa3b, v141
	v_add_f32_e32 v142, v17, v175
	v_exp_f32_e32 v141, v141
	v_mul_f32_e32 v142, 0xbfb8aa3b, v142
	v_exp_f32_e32 v142, v142
	v_rcp_f32_e32 v157, v140
	v_add_f32_e32 v140, 1.0, v141
	v_add_f32_e32 v141, v18, v176
	v_rcp_f32_e32 v158, v140
	v_add_f32_e32 v140, 1.0, v142
	v_mul_f32_e32 v141, 0xbfb8aa3b, v141
	v_add_f32_e32 v142, v19, v177
	v_exp_f32_e32 v141, v141
	v_mul_f32_e32 v142, 0xbfb8aa3b, v142
	v_exp_f32_e32 v142, v142
	v_rcp_f32_e32 v159, v140
	v_add_f32_e32 v140, 1.0, v141
	v_rcp_f32_e32 v160, v140
	v_add_f32_e32 v140, 1.0, v142
	v_rcp_f32_e32 v161, v140
	v_add_f32_e32 v140, v8, v174
	v_mul_f32_e32 v140, 0xbfb8aa3b, v140
	v_add_f32_e32 v141, v9, v175
	v_exp_f32_e32 v140, v140
	v_mul_f32_e32 v141, 0xbfb8aa3b, v141
	v_exp_f32_e32 v141, v141
	v_add_f32_e32 v140, 1.0, v140
	global_store_dwordx4 v[162:163], v[154:157], off offset:-3520
	v_add_f32_e32 v142, v11, v177
	v_mul_f32_e32 v142, 0xbfb8aa3b, v142
	v_rcp_f32_e32 v154, v140
	v_add_f32_e32 v140, 1.0, v141
	v_add_f32_e32 v141, v10, v176
	v_mul_f32_e32 v141, 0xbfb8aa3b, v141
	v_exp_f32_e32 v141, v141
	v_exp_f32_e32 v142, v142
	v_rcp_f32_e32 v155, v140
	v_add_f32_e32 v140, 1.0, v141
	v_rcp_f32_e32 v156, v140
	v_add_f32_e32 v140, 1.0, v142
	v_rcp_f32_e32 v157, v140
	v_add_f32_e32 v140, v4, v174
	v_mul_f32_e32 v140, 0xbfb8aa3b, v140
	v_add_f32_e32 v141, v5, v175
	v_exp_f32_e32 v140, v140
	v_mul_f32_e32 v141, 0xbfb8aa3b, v141
	v_exp_f32_e32 v141, v141
	global_store_dwordx4 v[166:167], v[158:161], off offset:-3520
	v_add_f32_e32 v140, 1.0, v140
	global_store_dwordx4 v[164:165], v[154:157], off offset:-3520
	v_add_f32_e32 v142, v7, v177
	v_mul_f32_e32 v142, 0xbfb8aa3b, v142
	v_rcp_f32_e32 v154, v140
	v_add_f32_e32 v140, 1.0, v141
	v_add_f32_e32 v141, v6, v176
	v_mul_f32_e32 v141, 0xbfb8aa3b, v141
	v_exp_f32_e32 v141, v141
	v_exp_f32_e32 v142, v142
	v_rcp_f32_e32 v155, v140
	v_add_f32_e32 v140, 1.0, v141
	v_add_f32_e32 v141, v0, v174
	v_rcp_f32_e32 v156, v140
	v_add_f32_e32 v140, 1.0, v142
	v_mul_f32_e32 v141, 0xbfb8aa3b, v141
	v_add_f32_e32 v142, v1, v175
	v_exp_f32_e32 v141, v141
	v_mul_f32_e32 v142, 0xbfb8aa3b, v142
	v_exp_f32_e32 v142, v142
	v_rcp_f32_e32 v157, v140
	v_add_f32_e32 v140, 1.0, v141
	v_add_f32_e32 v141, v2, v176
	v_rcp_f32_e32 v158, v140
	v_add_f32_e32 v140, 1.0, v142
	v_mul_f32_e32 v141, 0xbfb8aa3b, v141
	v_add_f32_e32 v142, v3, v177
	v_exp_f32_e32 v141, v141
	v_mul_f32_e32 v142, 0xbfb8aa3b, v142
	v_exp_f32_e32 v142, v142
	v_rcp_f32_e32 v159, v140
	v_add_f32_e32 v140, 1.0, v141
	v_rcp_f32_e32 v160, v140
	v_add_f32_e32 v140, 1.0, v142
	v_rcp_f32_e32 v161, v140
	global_store_dwordx4 v[128:129], v[154:157], off offset:-3520
	global_store_dwordx4 v[130:131], v[158:161], off offset:-3520

; #define PG8_STAGE(bufoff, gbase, voff) do { _Pragma("unroll") for (int _i = 0; _i < 2; ++_i) \
;         __builtin_amdgcn_global_load_lds((const unsigned*)((const char*)(gbase) + (voff)[_i]), (LAS unsigned*)(lds + (bufoff) + ldsw + _i * 8192), 16, 0, 0); } while (0)
; #define PG8_LDA(dst, b, h) do { _Pragma("unroll") for (int m = 0; m < 4; ++m) _Pragma("unroll") for (int k = 0; k < 2; ++k) dst[m][k] = *(const LAS bf16x8*)(lds + PG8_SA(b, h) + aoff + m * 2048 + k * 1024); } while (0)
; #define PG8_LDB(dst, b, h) do { _Pragma("unroll") for (int n = 0; n < 2; ++n) _Pragma("unroll") for (int k = 0; k < 2; ++k) dst[n][k] = *(const LAS bf16x8*)(lds + PG8_SB(b, h) + boff + n * 2048 + k * 1024); } while (0)
; #define PG8_MMA(ai, bj, At, Bt) do { __builtin_amdgcn_s_setprio(1); _Pragma("unroll") for (int m = 0; m < 4; ++m) _Pragma("unroll") for (int n = 0; n < 2; ++n) _Pragma("unroll") for (int k = 0; k < 2; ++k) \
;         acc[ai][bj][m][n] = __builtin_amdgcn_mfma_f32_16x16x32_bf16(Bt[n][k], At[m][k], acc[ai][bj][m][n], 0, 0, 0); __builtin_amdgcn_s_setprio(0); } while (0)
; #define PG8_WAIT_V(n) asm volatile("s_waitcnt vmcnt(" #n ")" ::: "memory")
; #define PG8_WAIT_L(n) asm volatile("s_waitcnt lgkmcnt(" #n ")" ::: "memory")
; #define PG8_BAR __builtin_amdgcn_s_barrier()
; #define PG8_SCHED __builtin_amdgcn_sched_barrier(0)
; template <class Epi>
; __device__ __forceinline__ void gemm_phase(LAS unsigned char* lds, const Gemm g, const StaticOrder& S, const Epi& E) {
;     ...
;             PG8_LDB(B0, 0, 0); PG8_SCHED; PG8_LDA(At, 0, 0); PG8_STAGE(PG8_SA(1, 1), a1 + hstepA, voffA);
;             PG8_WAIT_L(8); PG8_BAR; PG8_WAIT_L(0); PG8_MMA(0, 0, At, B0); PG8_BAR; PG8_SCHED;
;             PG8_LDB(B1, 0, 1); PG8_STAGE(PG8_SB(0, 0), b2, voffB);
;             PG8_BAR; PG8_WAIT_L(0); PG8_MMA(0, 1, At, B1); PG8_BAR;
;             PG8_LDA(At, 0, 1); PG8_STAGE(PG8_SA(0, 0), a2, voffA);
;             PG8_BAR; PG8_WAIT_L(0); PG8_MMA(1, 0, At, B0); PG8_BAR; PG8_SCHED;
;             PG8_STAGE(PG8_SB(0, 1), b2 + hstepB, voffB);
;             PG8_WAIT_V(6); PG8_BAR; PG8_MMA(1, 1, At, B1); PG8_BAR;
.LBB0_1089:
	ds_read_b128 v[158:161], v154
	ds_read_b128 v[162:165], v154 offset:1024
	ds_read_b128 v[166:169], v154 offset:2048
	ds_read_b128 v[170:173], v154 offset:3072
	s_add_u32 s36, s30, 0xfff80080
	s_addc_u32 s37, s31, -1
	s_cmp_eq_u32 s71, 28
	s_cselect_b32 s39, s23, s37
	s_cselect_b32 s38, s67, s36
	s_cselect_b32 s37, s21, s70
	s_cselect_b32 s36, s68, s69
	v_lshl_add_u64 v[140:141], s[30:31], 0, v[132:133]
	s_add_i32 m0, s29, 0xc000
	ds_read_b128 v[174:177], v155
	ds_read_b128 v[178:181], v155 offset:1024
	ds_read_b128 v[182:185], v155 offset:2048
	ds_read_b128 v[190:193], v155 offset:3072
	ds_read_b128 v[194:197], v155 offset:4096
	ds_read_b128 v[198:201], v155 offset:5120
	ds_read_b128 v[202:205], v155 offset:6144
	ds_read_b128 v[206:209], v155 offset:7168
	global_load_lds_dwordx4 v[140:141], off
	v_lshl_add_u64 v[140:141], s[30:31], 0, v[134:135]
	s_add_i32 m0, s29, 0xe000
	s_nop 0
	global_load_lds_dwordx4 v[140:141], off
	s_waitcnt lgkmcnt(8)
	s_barrier
	s_setprio 1
	s_waitcnt lgkmcnt(7)
	v_mfma_f32_16x16x32_bf16 v[124:127], v[158:161], v[174:177], v[124:127]
	v_mfma_f32_16x16x32_bf16 v[120:123], v[166:169], v[174:177], v[120:123]
	s_waitcnt lgkmcnt(5)
	v_mfma_f32_16x16x32_bf16 v[112:115], v[158:161], v[182:185], v[112:115]
	v_mfma_f32_16x16x32_bf16 v[104:107], v[166:169], v[182:185], v[104:107]
	s_waitcnt lgkmcnt(3)
	v_mfma_f32_16x16x32_bf16 v[96:99], v[158:161], v[194:197], v[96:99]
	v_mfma_f32_16x16x32_bf16 v[88:91], v[166:169], v[194:197], v[88:91]
	s_waitcnt lgkmcnt(1)
	v_mfma_f32_16x16x32_bf16 v[80:83], v[158:161], v[202:205], v[80:83]
	v_mfma_f32_16x16x32_bf16 v[72:75], v[166:169], v[202:205], v[72:75]
	v_mfma_f32_16x16x32_bf16 v[124:127], v[162:165], v[178:181], v[124:127]
	v_mfma_f32_16x16x32_bf16 v[120:123], v[170:173], v[178:181], v[120:123]
	v_mfma_f32_16x16x32_bf16 v[112:115], v[162:165], v[190:193], v[112:115]
	v_mfma_f32_16x16x32_bf16 v[104:107], v[170:173], v[190:193], v[104:107]
	v_mfma_f32_16x16x32_bf16 v[96:99], v[162:165], v[198:201], v[96:99]
	v_mfma_f32_16x16x32_bf16 v[88:91], v[170:173], v[198:201], v[88:91]
	s_waitcnt lgkmcnt(0)
	v_mfma_f32_16x16x32_bf16 v[80:83], v[162:165], v[206:209], v[80:83]
	v_mfma_f32_16x16x32_bf16 v[72:75], v[170:173], v[206:209], v[72:75]
	s_setprio 0
	s_barrier
	s_add_i32 s72, s64, s45
	v_lshl_add_u64 v[140:141], s[36:37], 0, v[128:129]
	s_mov_b32 m0, s72
	ds_read_b128 v[210:213], v156
	ds_read_b128 v[214:217], v156 offset:1024
	ds_read_b128 v[218:221], v156 offset:2048
	ds_read_b128 v[222:225], v156 offset:3072
	global_load_lds_dwordx4 v[140:141], off
	v_lshl_add_u64 v[186:187], s[36:37], 0, v[130:131]
	s_add_i32 m0, s72, 0x2000
	s_nop 0
	global_load_lds_dwordx4 v[186:187], off
	s_barrier
	s_setprio 1
	s_waitcnt lgkmcnt(3)
	v_mfma_f32_16x16x32_bf16 v[116:119], v[210:213], v[174:177], v[116:119]
	s_waitcnt lgkmcnt(1)
	v_mfma_f32_16x16x32_bf16 v[108:111], v[218:221], v[174:177], v[108:111]
	v_mfma_f32_16x16x32_bf16 v[100:103], v[210:213], v[182:185], v[100:103]
	v_mfma_f32_16x16x32_bf16 v[92:95], v[218:221], v[182:185], v[92:95]
	v_mfma_f32_16x16x32_bf16 v[84:87], v[210:213], v[194:197], v[84:87]
	v_mfma_f32_16x16x32_bf16 v[76:79], v[218:221], v[194:197], v[76:79]
	v_mfma_f32_16x16x32_bf16 v[68:71], v[210:213], v[202:205], v[68:71]
	v_mfma_f32_16x16x32_bf16 v[64:67], v[218:221], v[202:205], v[64:67]
	v_mfma_f32_16x16x32_bf16 v[116:119], v[214:217], v[178:181], v[116:119]
	s_waitcnt lgkmcnt(0)
	v_mfma_f32_16x16x32_bf16 v[108:111], v[222:225], v[178:181], v[108:111]
	v_mfma_f32_16x16x32_bf16 v[100:103], v[214:217], v[190:193], v[100:103]
	v_mfma_f32_16x16x32_bf16 v[92:95], v[222:225], v[190:193], v[92:95]
	v_mfma_f32_16x16x32_bf16 v[84:87], v[214:217], v[198:201], v[84:87]
	v_mfma_f32_16x16x32_bf16 v[76:79], v[222:225], v[198:201], v[76:79]
	v_mfma_f32_16x16x32_bf16 v[68:71], v[214:217], v[206:209], v[68:71]
	v_mfma_f32_16x16x32_bf16 v[64:67], v[222:225], v[206:209], v[64:67]
	s_setprio 0
	s_mov_b32 m0, s29
	v_lshl_add_u64 v[188:189], s[38:39], 0, v[128:129]
	s_barrier
	ds_read_b128 v[174:177], v155 offset:16384
	ds_read_b128 v[178:181], v155 offset:17408
	ds_read_b128 v[182:185], v155 offset:18432
	ds_read_b128 v[190:193], v155 offset:19456
	ds_read_b128 v[194:197], v155 offset:20480
	ds_read_b128 v[198:201], v155 offset:21504
	ds_read_b128 v[202:205], v155 offset:22528
	ds_read_b128 v[206:209], v155 offset:23552
	global_load_lds_dwordx4 v[188:189], off
	v_lshl_add_u64 v[226:227], s[38:39], 0, v[130:131]
	s_mov_b32 m0, s46
	s_nop 0
	global_load_lds_dwordx4 v[226:227], off
	s_barrier
	s_setprio 1
	s_waitcnt lgkmcnt(7)
	v_mfma_f32_16x16x32_bf16 v[60:63], v[158:161], v[174:177], v[60:63]
	v_mfma_f32_16x16x32_bf16 v[56:59], v[166:169], v[174:177], v[56:59]
	s_waitcnt lgkmcnt(5)
	v_mfma_f32_16x16x32_bf16 v[48:51], v[158:161], v[182:185], v[48:51]
	v_mfma_f32_16x16x32_bf16 v[44:47], v[166:169], v[182:185], v[44:47]
	s_waitcnt lgkmcnt(3)
	v_mfma_f32_16x16x32_bf16 v[32:35], v[158:161], v[194:197], v[32:35]
	v_mfma_f32_16x16x32_bf16 v[28:31], v[166:169], v[194:197], v[28:31]
	s_waitcnt lgkmcnt(1)
	v_mfma_f32_16x16x32_bf16 v[16:19], v[158:161], v[202:205], v[16:19]
	v_mfma_f32_16x16x32_bf16 v[12:15], v[166:169], v[202:205], v[12:15]
	v_mfma_f32_16x16x32_bf16 v[60:63], v[162:165], v[178:181], v[60:63]
	v_mfma_f32_16x16x32_bf16 v[56:59], v[170:173], v[178:181], v[56:59]
	v_mfma_f32_16x16x32_bf16 v[48:51], v[162:165], v[190:193], v[48:51]
	v_mfma_f32_16x16x32_bf16 v[44:47], v[170:173], v[190:193], v[44:47]
	v_mfma_f32_16x16x32_bf16 v[32:35], v[162:165], v[198:201], v[32:35]
	v_mfma_f32_16x16x32_bf16 v[28:31], v[170:173], v[198:201], v[28:31]
	s_waitcnt lgkmcnt(0)
	v_mfma_f32_16x16x32_bf16 v[16:19], v[162:165], v[206:209], v[16:19]
	v_mfma_f32_16x16x32_bf16 v[12:15], v[170:173], v[206:209], v[12:15]
	s_setprio 0
	s_barrier
; #define PG8_STAGE(bufoff, gbase, voff) do { _Pragma("unroll") for (int _i = 0; _i < 2; ++_i) \
;         __builtin_amdgcn_global_load_lds((const unsigned*)((const char*)(gbase) + (voff)[_i]), (LAS unsigned*)(lds + (bufoff) + ldsw + _i * 8192), 16, 0, 0); } while (0)
; #define PG8_LDA(dst, b, h) do { _Pragma("unroll") for (int m = 0; m < 4; ++m) _Pragma("unroll") for (int k = 0; k < 2; ++k) dst[m][k] = *(const LAS bf16x8*)(lds + PG8_SA(b, h) + aoff + m * 2048 + k * 1024); } while (0)
; #define PG8_LDB(dst, b, h) do { _Pragma("unroll") for (int n = 0; n < 2; ++n) _Pragma("unroll") for (int k = 0; k < 2; ++k) dst[n][k] = *(const LAS bf16x8*)(lds + PG8_SB(b, h) + boff + n * 2048 + k * 1024); } while (0)
; #define PG8_MMA(ai, bj, At, Bt) do { __builtin_amdgcn_s_setprio(1); _Pragma("unroll") for (int m = 0; m < 4; ++m) _Pragma("unroll") for (int n = 0; n < 2; ++n) _Pragma("unroll") for (int k = 0; k < 2; ++k) \
;         acc[ai][bj][m][n] = __builtin_amdgcn_mfma_f32_16x16x32_bf16(Bt[n][k], At[m][k], acc[ai][bj][m][n], 0, 0, 0); __builtin_amdgcn_s_setprio(0); } while (0)
; #define PG8_WAIT_V(n) asm volatile("s_waitcnt vmcnt(" #n ")" ::: "memory")
; #define PG8_WAIT_L(n) asm volatile("s_waitcnt lgkmcnt(" #n ")" ::: "memory")
; #define PG8_BAR __builtin_amdgcn_s_barrier()
; #define PG8_SCHED __builtin_amdgcn_sched_barrier(0)
; template <class Epi>
; __device__ __forceinline__ void gemm_phase(LAS unsigned char* lds, const Gemm g, const StaticOrder& S, const Epi& E) {
;     ...
;             PG8_WAIT_V(6); PG8_BAR; PG8_MMA(1, 1, At, B1); PG8_BAR;
;             PG8_LDB(B0, 1, 0); PG8_SCHED; PG8_LDA(At, 1, 0); PG8_STAGE(PG8_SA(0, 1), a2 + hstepA, voffA);
;             PG8_WAIT_L(8); PG8_BAR; PG8_WAIT_L(0); PG8_MMA(0, 0, At, B0); PG8_BAR; PG8_SCHED;
;             PG8_LDB(B1, 1, 1); PG8_STAGE(PG8_SB(1, 0), b3, voffB);
;             PG8_BAR; PG8_WAIT_L(0); PG8_MMA(0, 1, At, B1); PG8_BAR;
;             PG8_LDA(At, 1, 1); PG8_STAGE(PG8_SA(1, 0), a3, voffA);
;             PG8_BAR; PG8_WAIT_L(0); PG8_MMA(1, 0, At, B0); PG8_BAR; PG8_SCHED;
	s_add_u32 s72, s36, 0x80000
	s_addc_u32 s73, s37, 0
	s_add_i32 s74, s65, s45
	v_lshl_add_u64 v[158:159], s[72:73], 0, v[128:129]
	s_mov_b32 m0, s74
	s_nop 0
	global_load_lds_dwordx4 v[158:159], off
	v_lshl_add_u64 v[158:159], s[72:73], 0, v[130:131]
	s_add_i32 m0, s74, 0x2000
	s_nop 0
	global_load_lds_dwordx4 v[158:159], off
	s_waitcnt vmcnt(6)
	s_barrier
	s_setprio 1
	v_mfma_f32_16x16x32_bf16 v[52:55], v[210:213], v[174:177], v[52:55]
	v_mfma_f32_16x16x32_bf16 v[40:43], v[218:221], v[174:177], v[40:43]
	v_mfma_f32_16x16x32_bf16 v[36:39], v[210:213], v[182:185], v[36:39]
	v_mfma_f32_16x16x32_bf16 v[24:27], v[218:221], v[182:185], v[24:27]
	v_mfma_f32_16x16x32_bf16 v[20:23], v[210:213], v[194:197], v[20:23]
	v_mfma_f32_16x16x32_bf16 v[8:11], v[218:221], v[194:197], v[8:11]
	v_mfma_f32_16x16x32_bf16 v[4:7], v[210:213], v[202:205], v[4:7]
	v_mfma_f32_16x16x32_bf16 v[0:3], v[218:221], v[202:205], v[0:3]
	v_mfma_f32_16x16x32_bf16 v[52:55], v[214:217], v[178:181], v[52:55]
	v_mfma_f32_16x16x32_bf16 v[40:43], v[222:225], v[178:181], v[40:43]
	v_mfma_f32_16x16x32_bf16 v[36:39], v[214:217], v[190:193], v[36:39]
	v_mfma_f32_16x16x32_bf16 v[24:27], v[222:225], v[190:193], v[24:27]
	v_mfma_f32_16x16x32_bf16 v[20:23], v[214:217], v[198:201], v[20:23]
	v_mfma_f32_16x16x32_bf16 v[8:11], v[222:225], v[198:201], v[8:11]
	v_mfma_f32_16x16x32_bf16 v[4:7], v[214:217], v[206:209], v[4:7]
	v_mfma_f32_16x16x32_bf16 v[0:3], v[222:225], v[206:209], v[0:3]
	s_setprio 0
	s_add_i32 s72, 0, 0x18000
	v_add_u32_e32 v157, s72, v152
	s_barrier
	ds_read_b128 v[158:161], v157
	ds_read_b128 v[162:165], v157 offset:1024
	ds_read_b128 v[166:169], v157 offset:2048
	ds_read_b128 v[170:173], v157 offset:3072
	s_add_u32 s38, s38, 0x80000
	s_addc_u32 s39, s39, 0
	s_mov_b32 m0, s47
	v_lshl_add_u64 v[210:211], s[38:39], 0, v[128:129]
	ds_read_b128 v[174:177], v155 offset:32768
	ds_read_b128 v[178:181], v155 offset:33792
	ds_read_b128 v[182:185], v155 offset:34816
	ds_read_b128 v[190:193], v155 offset:35840
	ds_read_b128 v[194:197], v155 offset:36864
	ds_read_b128 v[198:201], v155 offset:37888
	ds_read_b128 v[202:205], v155 offset:38912
	ds_read_b128 v[206:209], v155 offset:39936
	global_load_lds_dwordx4 v[210:211], off
	v_lshl_add_u64 v[210:211], s[38:39], 0, v[130:131]
	s_mov_b32 m0, s48
	s_nop 0
	global_load_lds_dwordx4 v[210:211], off
	s_waitcnt lgkmcnt(8)
	s_barrier
	s_setprio 1
	s_waitcnt lgkmcnt(7)
	v_mfma_f32_16x16x32_bf16 v[124:127], v[158:161], v[174:177], v[124:127]
	v_mfma_f32_16x16x32_bf16 v[120:123], v[166:169], v[174:177], v[120:123]
	s_waitcnt lgkmcnt(5)
	v_mfma_f32_16x16x32_bf16 v[112:115], v[158:161], v[182:185], v[112:115]
	v_mfma_f32_16x16x32_bf16 v[104:107], v[166:169], v[182:185], v[104:107]
	s_waitcnt lgkmcnt(3)
	v_mfma_f32_16x16x32_bf16 v[96:99], v[158:161], v[194:197], v[96:99]
	v_mfma_f32_16x16x32_bf16 v[88:91], v[166:169], v[194:197], v[88:91]
	s_waitcnt lgkmcnt(1)
	v_mfma_f32_16x16x32_bf16 v[80:83], v[158:161], v[202:205], v[80:83]
	v_mfma_f32_16x16x32_bf16 v[72:75], v[166:169], v[202:205], v[72:75]
	v_mfma_f32_16x16x32_bf16 v[124:127], v[162:165], v[178:181], v[124:127]
	v_mfma_f32_16x16x32_bf16 v[120:123], v[170:173], v[178:181], v[120:123]
	v_mfma_f32_16x16x32_bf16 v[112:115], v[162:165], v[190:193], v[112:115]
	v_mfma_f32_16x16x32_bf16 v[104:107], v[170:173], v[190:193], v[104:107]
	v_mfma_f32_16x16x32_bf16 v[96:99], v[162:165], v[198:201], v[96:99]
	v_mfma_f32_16x16x32_bf16 v[88:91], v[170:173], v[198:201], v[88:91]
	s_waitcnt lgkmcnt(0)
	v_mfma_f32_16x16x32_bf16 v[80:83], v[162:165], v[206:209], v[80:83]
	v_mfma_f32_16x16x32_bf16 v[72:75], v[170:173], v[206:209], v[72:75]
	s_setprio 0
	s_barrier
	s_add_i32 s38, 0, 0x1c000
	s_add_i32 s39, s72, s45
	v_add_u32_e32 v157, s38, v152
	v_lshl_add_u64 v[140:141], v[140:141], 0, s[6:7]
	s_mov_b32 m0, s39
	ds_read_b128 v[210:213], v157
	ds_read_b128 v[214:217], v157 offset:1024
	ds_read_b128 v[218:221], v157 offset:2048
	ds_read_b128 v[222:225], v157 offset:3072
	global_load_lds_dwordx4 v[140:141], off
	v_lshl_add_u64 v[140:141], v[186:187], 0, s[6:7]
	s_add_i32 m0, s39, 0x2000
	s_nop 0
	global_load_lds_dwordx4 v[140:141], off
	s_barrier
	s_setprio 1
	s_waitcnt lgkmcnt(3)
	v_mfma_f32_16x16x32_bf16 v[116:119], v[210:213], v[174:177], v[116:119]
	s_waitcnt lgkmcnt(1)
	v_mfma_f32_16x16x32_bf16 v[108:111], v[218:221], v[174:177], v[108:111]
	v_mfma_f32_16x16x32_bf16 v[100:103], v[210:213], v[182:185], v[100:103]
	v_mfma_f32_16x16x32_bf16 v[92:95], v[218:221], v[182:185], v[92:95]
	v_mfma_f32_16x16x32_bf16 v[84:87], v[210:213], v[194:197], v[84:87]
	v_mfma_f32_16x16x32_bf16 v[76:79], v[218:221], v[194:197], v[76:79]
	v_mfma_f32_16x16x32_bf16 v[68:71], v[210:213], v[202:205], v[68:71]
	v_mfma_f32_16x16x32_bf16 v[64:67], v[218:221], v[202:205], v[64:67]
	v_mfma_f32_16x16x32_bf16 v[116:119], v[214:217], v[178:181], v[116:119]
	s_waitcnt lgkmcnt(0)
	v_mfma_f32_16x16x32_bf16 v[108:111], v[222:225], v[178:181], v[108:111]
	v_mfma_f32_16x16x32_bf16 v[100:103], v[214:217], v[190:193], v[100:103]
	v_mfma_f32_16x16x32_bf16 v[92:95], v[222:225], v[190:193], v[92:95]
	v_mfma_f32_16x16x32_bf16 v[84:87], v[214:217], v[198:201], v[84:87]
	v_mfma_f32_16x16x32_bf16 v[76:79], v[222:225], v[198:201], v[76:79]
	v_mfma_f32_16x16x32_bf16 v[68:71], v[214:217], v[206:209], v[68:71]
	v_mfma_f32_16x16x32_bf16 v[64:67], v[222:225], v[206:209], v[64:67]
	s_setprio 0
	s_mov_b32 m0, s50
	v_lshl_add_u64 v[140:141], v[188:189], 0, s[6:7]
	s_barrier
; #define PG8_STAGE(bufoff, gbase, voff) do { _Pragma("unroll") for (int _i = 0; _i < 2; ++_i) \
;         __builtin_amdgcn_global_load_lds((const unsigned*)((const char*)(gbase) + (voff)[_i]), (LAS unsigned*)(lds + (bufoff) + ldsw + _i * 8192), 16, 0, 0); } while (0)
; #define PG8_MMA(ai, bj, At, Bt) do { __builtin_amdgcn_s_setprio(1); _Pragma("unroll") for (int m = 0; m < 4; ++m) _Pragma("unroll") for (int n = 0; n < 2; ++n) _Pragma("unroll") for (int k = 0; k < 2; ++k) \
;         acc[ai][bj][m][n] = __builtin_amdgcn_mfma_f32_16x16x32_bf16(Bt[n][k], At[m][k], acc[ai][bj][m][n], 0, 0, 0); __builtin_amdgcn_s_setprio(0); } while (0)
; #define PG8_WAIT_V(n) asm volatile("s_waitcnt vmcnt(" #n ")" ::: "memory")
; #define PG8_WAIT_L(n) asm volatile("s_waitcnt lgkmcnt(" #n ")" ::: "memory")
; #define PG8_BAR __builtin_amdgcn_s_barrier()
; #define PG8_SCHED __builtin_amdgcn_sched_barrier(0)
; template <class Epi>
; __device__ __forceinline__ void gemm_phase(LAS unsigned char* lds, const Gemm g, const StaticOrder& S, const Epi& E) {
;     ...
;             PG8_BAR; PG8_WAIT_L(0); PG8_MMA(1, 0, At, B0); PG8_BAR; PG8_SCHED;
;             PG8_STAGE(PG8_SB(1, 1), b3 + hstepB, voffB);
;             PG8_WAIT_V(6); PG8_BAR; PG8_MMA(1, 1, At, B1); PG8_BAR;
;     __device__ __forceinline__ void operator()(const AccT& acc, const Unit& u, int wr, int wc, int fr, int fq) const {
;         const int row0 = u.pm * 256 + wr * 64 + fr, col0 = u.pn * 256 + wc * 32 + 4 * fq;
; #pragma unroll
;         for (int ai = 0; ai < 2; ++ai)
; #pragma unroll
;             for (int m = 0; m < 4; ++m) { const size_t ro = (size_t)(row0 + ai * 128 + m * 16) * DM + col0;
; #pragma unroll
;                 for (int bj = 0; bj < 2; ++bj)
; #pragma unroll
;                     for (int n = 0; n < 2; ++n) { const size_t o = ro + bj * 128 + n * 16; *(f32x4*)(H + o) = acc[ai][bj][m][n] + *(const f32x4*)(X + o); } asm volatile("" ::: "memory"); }
	ds_read_b128 v[174:177], v155 offset:49152
	ds_read_b128 v[178:181], v155 offset:50176
	ds_read_b128 v[182:185], v155 offset:51200
	ds_read_b128 v[190:193], v155 offset:52224
	ds_read_b128 v[194:197], v155 offset:53248
	ds_read_b128 v[198:201], v155 offset:54272
	ds_read_b128 v[202:205], v155 offset:55296
	ds_read_b128 v[206:209], v155 offset:56320
	global_load_lds_dwordx4 v[140:141], off
	v_lshl_add_u64 v[140:141], v[226:227], 0, s[6:7]
	s_mov_b32 m0, s51
	s_nop 0
	global_load_lds_dwordx4 v[140:141], off
	s_barrier
	s_setprio 1
	s_waitcnt lgkmcnt(7)
	v_mfma_f32_16x16x32_bf16 v[60:63], v[158:161], v[174:177], v[60:63]
	v_mfma_f32_16x16x32_bf16 v[56:59], v[166:169], v[174:177], v[56:59]
	s_waitcnt lgkmcnt(5)
	v_mfma_f32_16x16x32_bf16 v[48:51], v[158:161], v[182:185], v[48:51]
	v_mfma_f32_16x16x32_bf16 v[44:47], v[166:169], v[182:185], v[44:47]
	s_waitcnt lgkmcnt(3)
	v_mfma_f32_16x16x32_bf16 v[32:35], v[158:161], v[194:197], v[32:35]
	v_mfma_f32_16x16x32_bf16 v[28:31], v[166:169], v[194:197], v[28:31]
	s_waitcnt lgkmcnt(1)
	v_mfma_f32_16x16x32_bf16 v[16:19], v[158:161], v[202:205], v[16:19]
	v_mfma_f32_16x16x32_bf16 v[12:15], v[166:169], v[202:205], v[12:15]
	v_mfma_f32_16x16x32_bf16 v[60:63], v[162:165], v[178:181], v[60:63]
	v_mfma_f32_16x16x32_bf16 v[56:59], v[170:173], v[178:181], v[56:59]
	v_mfma_f32_16x16x32_bf16 v[48:51], v[162:165], v[190:193], v[48:51]
	v_mfma_f32_16x16x32_bf16 v[44:47], v[170:173], v[190:193], v[44:47]
	v_mfma_f32_16x16x32_bf16 v[32:35], v[162:165], v[198:201], v[32:35]
	v_mfma_f32_16x16x32_bf16 v[28:31], v[170:173], v[198:201], v[28:31]
	s_waitcnt lgkmcnt(0)
	v_mfma_f32_16x16x32_bf16 v[16:19], v[162:165], v[206:209], v[16:19]
	v_mfma_f32_16x16x32_bf16 v[12:15], v[170:173], v[206:209], v[12:15]
	s_setprio 0
	s_barrier
	s_add_u32 s36, s36, 0x80080
	s_addc_u32 s37, s37, 0
	s_add_i32 s38, s38, s45
	v_lshl_add_u64 v[140:141], s[36:37], 0, v[128:129]
	s_mov_b32 m0, s38
	s_nop 0
	global_load_lds_dwordx4 v[140:141], off
	v_lshl_add_u64 v[140:141], s[36:37], 0, v[130:131]
	s_add_i32 m0, s38, 0x2000
	s_nop 0
	global_load_lds_dwordx4 v[140:141], off
	s_waitcnt vmcnt(6)
	s_barrier
	s_setprio 1
	v_mfma_f32_16x16x32_bf16 v[52:55], v[210:213], v[174:177], v[52:55]
	v_mfma_f32_16x16x32_bf16 v[40:43], v[218:221], v[174:177], v[40:43]
	v_mfma_f32_16x16x32_bf16 v[36:39], v[210:213], v[182:185], v[36:39]
	v_mfma_f32_16x16x32_bf16 v[24:27], v[218:221], v[182:185], v[24:27]
	v_mfma_f32_16x16x32_bf16 v[20:23], v[210:213], v[194:197], v[20:23]
	v_mfma_f32_16x16x32_bf16 v[8:11], v[218:221], v[194:197], v[8:11]
	v_mfma_f32_16x16x32_bf16 v[4:7], v[210:213], v[202:205], v[4:7]
	v_mfma_f32_16x16x32_bf16 v[0:3], v[218:221], v[202:205], v[0:3]
	v_mfma_f32_16x16x32_bf16 v[52:55], v[214:217], v[178:181], v[52:55]
	v_mfma_f32_16x16x32_bf16 v[40:43], v[222:225], v[178:181], v[40:43]
	v_mfma_f32_16x16x32_bf16 v[36:39], v[214:217], v[190:193], v[36:39]
	v_mfma_f32_16x16x32_bf16 v[24:27], v[222:225], v[190:193], v[24:27]
	v_mfma_f32_16x16x32_bf16 v[20:23], v[214:217], v[198:201], v[20:23]
	v_mfma_f32_16x16x32_bf16 v[8:11], v[222:225], v[198:201], v[8:11]
	v_mfma_f32_16x16x32_bf16 v[4:7], v[214:217], v[206:209], v[4:7]
	v_mfma_f32_16x16x32_bf16 v[0:3], v[222:225], v[206:209], v[0:3]
	s_setprio 0
	s_add_i32 s71, s71, 2
	s_add_u32 s30, s30, 0x100
	s_addc_u32 s31, s31, 0
	s_add_u32 s69, s69, 0x100
	s_addc_u32 s70, s70, 0
	s_cmp_gt_u32 s71, 29
	s_barrier
	s_cbranch_scc0 .LBB0_1089
	v_lshl_add_u32 v162, s28, 8, v151
	v_lshl_or_b32 v164, s66, 8, v153
	v_ashrrev_i32_e32 v163, 31, v162
	v_ashrrev_i32_e32 v165, 31, v164
	v_lshlrev_b64 v[140:141], 11, v[162:163]
	v_lshl_add_u64 v[140:141], v[140:141], 0, v[164:165]
	v_lshlrev_b64 v[140:141], 2, v[140:141]
	v_lshl_add_u64 v[166:167], s[12:13], 0, v[140:141]
	global_load_dwordx4 v[158:161], v[166:167], off
	v_lshl_add_u64 v[168:169], s[54:55], 0, v[140:141]
	s_and_b64 vcc, exec, s[4:5]
	s_mov_b32 s66, s20
	s_mov_b32 s28, s22
	s_mov_b64 s[36:37], s[26:27]
	s_mov_b64 s[30:31], s[24:25]
	s_waitcnt vmcnt(0)
	v_pk_add_f32 v[126:127], v[126:127], v[160:161]
	v_pk_add_f32 v[124:125], v[124:125], v[158:159]
	global_store_dwordx4 v[168:169], v[124:127], off
	global_load_dwordx4 v[124:127], v[166:167], off offset:64
	s_waitcnt vmcnt(0)
	v_pk_add_f32 v[122:123], v[122:123], v[126:127]
	v_pk_add_f32 v[120:121], v[120:121], v[124:125]
	global_store_dwordx4 v[168:169], v[120:123], off offset:64
	global_load_dwordx4 v[120:123], v[166:167], off offset:512
	s_waitcnt vmcnt(0)
	v_pk_add_f32 v[118:119], v[118:119], v[122:123]
	v_pk_add_f32 v[116:117], v[116:117], v[120:121]
	global_store_dwordx4 v[168:169], v[116:119], off offset:512
	global_load_dwordx4 v[116:119], v[166:167], off offset:576
	v_or_b32_e32 v120, 16, v162
	v_ashrrev_i32_e32 v121, 31, v120
	v_lshlrev_b64 v[120:121], 11, v[120:121]
	v_lshl_add_u64 v[120:121], v[120:121], 0, v[164:165]
	v_lshlrev_b64 v[120:121], 2, v[120:121]
	v_lshl_add_u64 v[122:123], s[12:13], 0, v[120:121]
	s_waitcnt vmcnt(0)
	v_pk_add_f32 v[110:111], v[110:111], v[118:119]
	v_pk_add_f32 v[108:109], v[108:109], v[116:117]
	global_store_dwordx4 v[168:169], v[108:111], off offset:576
	global_load_dwordx4 v[108:111], v[122:123], off
	v_lshl_add_u64 v[116:117], s[54:55], 0, v[120:121]
	s_waitcnt vmcnt(0)
	v_pk_add_f32 v[110:111], v[114:115], v[110:111]
	v_pk_add_f32 v[108:109], v[112:113], v[108:109]
	global_store_dwordx4 v[116:117], v[108:111], off
	global_load_dwordx4 v[108:111], v[122:123], off offset:64
	s_waitcnt vmcnt(0)
	v_pk_add_f32 v[106:107], v[106:107], v[110:111]
	v_pk_add_f32 v[104:105], v[104:105], v[108:109]
	global_store_dwordx4 v[116:117], v[104:107], off offset:64
	global_load_dwordx4 v[104:107], v[122:123], off offset:512
	s_waitcnt vmcnt(0)
; #define PG8_WAIT_V(n) asm volatile("s_waitcnt vmcnt(" #n ")" ::: "memory")
; #define PG8_BAR __builtin_amdgcn_s_barrier()
; template <class Epi>
; __device__ __forceinline__ void gemm_phase(LAS unsigned char* lds, const Gemm g, const StaticOrder& S, const Epi& E) {
;     ...
;     PG8_WAIT_V(0);
;     if (wr == 0) PG8_BAR;
;     PG8_BAR;
;     __device__ __forceinline__ void operator()(const AccT& acc, const Unit& u, int wr, int wc, int fr, int fq) const {
;         const int row0 = u.pm * 256 + wr * 64 + fr, col0 = u.pn * 256 + wc * 32 + 4 * fq;
; #pragma unroll
;         for (int ai = 0; ai < 2; ++ai)
; #pragma unroll
;             for (int m = 0; m < 4; ++m) { const size_t ro = (size_t)(row0 + ai * 128 + m * 16) * DM + col0;
; #pragma unroll
;                 for (int bj = 0; bj < 2; ++bj)
; #pragma unroll
;                     for (int n = 0; n < 2; ++n) { const size_t o = ro + bj * 128 + n * 16; *(f32x4*)(H + o) = acc[ai][bj][m][n] + *(const f32x4*)(X + o); } asm volatile("" ::: "memory"); }
	v_pk_add_f32 v[102:103], v[102:103], v[106:107]
	v_pk_add_f32 v[100:101], v[100:101], v[104:105]
	global_store_dwordx4 v[116:117], v[100:103], off offset:512
	global_load_dwordx4 v[100:103], v[122:123], off offset:576
	v_or_b32_e32 v104, 32, v162
	v_ashrrev_i32_e32 v105, 31, v104
	v_lshlrev_b64 v[104:105], 11, v[104:105]
	v_lshl_add_u64 v[104:105], v[104:105], 0, v[164:165]
	v_lshlrev_b64 v[104:105], 2, v[104:105]
	v_lshl_add_u64 v[106:107], s[12:13], 0, v[104:105]
	s_waitcnt vmcnt(0)
	v_pk_add_f32 v[94:95], v[94:95], v[102:103]
	v_pk_add_f32 v[92:93], v[92:93], v[100:101]
	global_store_dwordx4 v[116:117], v[92:95], off offset:576
	global_load_dwordx4 v[92:95], v[106:107], off
	v_lshl_add_u64 v[100:101], s[54:55], 0, v[104:105]
	s_waitcnt vmcnt(0)
	v_pk_add_f32 v[94:95], v[98:99], v[94:95]
	v_pk_add_f32 v[92:93], v[96:97], v[92:93]
	global_store_dwordx4 v[100:101], v[92:95], off
	global_load_dwordx4 v[92:95], v[106:107], off offset:64
	s_waitcnt vmcnt(0)
	v_pk_add_f32 v[90:91], v[90:91], v[94:95]
	v_pk_add_f32 v[88:89], v[88:89], v[92:93]
	global_store_dwordx4 v[100:101], v[88:91], off offset:64
	global_load_dwordx4 v[88:91], v[106:107], off offset:512
	s_waitcnt vmcnt(0)
	v_pk_add_f32 v[86:87], v[86:87], v[90:91]
	v_pk_add_f32 v[84:85], v[84:85], v[88:89]
	global_store_dwordx4 v[100:101], v[84:87], off offset:512
	global_load_dwordx4 v[84:87], v[106:107], off offset:576
	v_or_b32_e32 v88, 48, v162
	v_ashrrev_i32_e32 v89, 31, v88
	v_lshlrev_b64 v[88:89], 11, v[88:89]
	v_lshl_add_u64 v[88:89], v[88:89], 0, v[164:165]
	v_lshlrev_b64 v[88:89], 2, v[88:89]
	v_lshl_add_u64 v[90:91], s[12:13], 0, v[88:89]
	s_waitcnt vmcnt(0)
	v_pk_add_f32 v[78:79], v[78:79], v[86:87]
	v_pk_add_f32 v[76:77], v[76:77], v[84:85]
	global_store_dwordx4 v[100:101], v[76:79], off offset:576
	global_load_dwordx4 v[76:79], v[90:91], off
	v_lshl_add_u64 v[84:85], s[54:55], 0, v[88:89]
	s_waitcnt vmcnt(0)
	v_pk_add_f32 v[78:79], v[82:83], v[78:79]
	v_pk_add_f32 v[76:77], v[80:81], v[76:77]
	global_store_dwordx4 v[84:85], v[76:79], off
	global_load_dwordx4 v[76:79], v[90:91], off offset:64
	s_waitcnt vmcnt(0)
	v_pk_add_f32 v[74:75], v[74:75], v[78:79]
	v_pk_add_f32 v[72:73], v[72:73], v[76:77]
	global_store_dwordx4 v[84:85], v[72:75], off offset:64
	global_load_dwordx4 v[72:75], v[90:91], off offset:512
	s_waitcnt vmcnt(0)
	v_pk_add_f32 v[70:71], v[70:71], v[74:75]
	v_pk_add_f32 v[68:69], v[68:69], v[72:73]
	global_store_dwordx4 v[84:85], v[68:71], off offset:512
	global_load_dwordx4 v[68:71], v[90:91], off offset:576
	v_lshl_add_u64 v[72:73], v[140:141], 0, s[8:9]
	v_lshl_add_u64 v[74:75], s[12:13], 0, v[72:73]
	s_waitcnt vmcnt(0)
	v_pk_add_f32 v[66:67], v[66:67], v[70:71]
	v_pk_add_f32 v[64:65], v[64:65], v[68:69]
	global_store_dwordx4 v[84:85], v[64:67], off offset:576
	global_load_dwordx4 v[64:67], v[74:75], off
	v_lshl_add_u64 v[68:69], s[54:55], 0, v[72:73]
	s_waitcnt vmcnt(0)
	v_pk_add_f32 v[62:63], v[62:63], v[66:67]
	v_pk_add_f32 v[60:61], v[60:61], v[64:65]
	global_store_dwordx4 v[68:69], v[60:63], off
	global_load_dwordx4 v[60:63], v[74:75], off offset:64
	s_waitcnt vmcnt(0)
	v_pk_add_f32 v[58:59], v[58:59], v[62:63]
	v_pk_add_f32 v[56:57], v[56:57], v[60:61]
	global_store_dwordx4 v[68:69], v[56:59], off offset:64
	global_load_dwordx4 v[56:59], v[74:75], off offset:512
	s_waitcnt vmcnt(0)
	v_pk_add_f32 v[54:55], v[54:55], v[58:59]
	v_pk_add_f32 v[52:53], v[52:53], v[56:57]
	global_store_dwordx4 v[68:69], v[52:55], off offset:512
	global_load_dwordx4 v[52:55], v[74:75], off offset:576
	v_lshl_add_u64 v[56:57], v[140:141], 0, s[14:15]
	v_lshl_add_u64 v[58:59], s[12:13], 0, v[56:57]
	s_waitcnt vmcnt(0)
	v_pk_add_f32 v[42:43], v[42:43], v[54:55]
	v_pk_add_f32 v[40:41], v[40:41], v[52:53]
	global_store_dwordx4 v[68:69], v[40:43], off offset:576
	global_load_dwordx4 v[40:43], v[58:59], off
	v_lshl_add_u64 v[52:53], s[54:55], 0, v[56:57]
	s_waitcnt vmcnt(0)
	v_pk_add_f32 v[42:43], v[50:51], v[42:43]
	v_pk_add_f32 v[40:41], v[48:49], v[40:41]
	global_store_dwordx4 v[52:53], v[40:43], off
	global_load_dwordx4 v[40:43], v[58:59], off offset:64
	s_waitcnt vmcnt(0)
	v_pk_add_f32 v[42:43], v[46:47], v[42:43]
	v_pk_add_f32 v[40:41], v[44:45], v[40:41]
	global_store_dwordx4 v[52:53], v[40:43], off offset:64
	global_load_dwordx4 v[40:43], v[58:59], off offset:512
	s_waitcnt vmcnt(0)
	v_pk_add_f32 v[38:39], v[38:39], v[42:43]
	v_pk_add_f32 v[36:37], v[36:37], v[40:41]
	global_store_dwordx4 v[52:53], v[36:39], off offset:512
	global_load_dwordx4 v[36:39], v[58:59], off offset:576
	v_lshl_add_u64 v[40:41], v[140:141], 0, s[16:17]
	v_lshl_add_u64 v[42:43], s[12:13], 0, v[40:41]
	s_waitcnt vmcnt(0)
	v_pk_add_f32 v[26:27], v[26:27], v[38:39]
	v_pk_add_f32 v[24:25], v[24:25], v[36:37]
	global_store_dwordx4 v[52:53], v[24:27], off offset:576
	global_load_dwordx4 v[24:27], v[42:43], off
	v_lshl_add_u64 v[36:37], s[54:55], 0, v[40:41]
	s_waitcnt vmcnt(0)
	v_pk_add_f32 v[26:27], v[34:35], v[26:27]
	v_pk_add_f32 v[24:25], v[32:33], v[24:25]
	global_store_dwordx4 v[36:37], v[24:27], off
	global_load_dwordx4 v[24:27], v[42:43], off offset:64
	s_waitcnt vmcnt(0)
	v_pk_add_f32 v[26:27], v[30:31], v[26:27]
	v_pk_add_f32 v[24:25], v[28:29], v[24:25]
	global_store_dwordx4 v[36:37], v[24:27], off offset:64
	global_load_dwordx4 v[24:27], v[42:43], off offset:512
	s_waitcnt vmcnt(0)
	v_pk_add_f32 v[22:23], v[22:23], v[26:27]
	v_pk_add_f32 v[20:21], v[20:21], v[24:25]
	global_store_dwordx4 v[36:37], v[20:23], off offset:512
	global_load_dwordx4 v[20:23], v[42:43], off offset:576
	v_lshl_add_u64 v[24:25], v[140:141], 0, s[18:19]
	v_lshl_add_u64 v[26:27], s[12:13], 0, v[24:25]
	s_waitcnt vmcnt(0)
	v_pk_add_f32 v[10:11], v[10:11], v[22:23]
	v_pk_add_f32 v[8:9], v[8:9], v[20:21]
	global_store_dwordx4 v[36:37], v[8:11], off offset:576
	global_load_dwordx4 v[8:11], v[26:27], off
	v_lshl_add_u64 v[20:21], s[54:55], 0, v[24:25]
	s_waitcnt vmcnt(0)
	v_pk_add_f32 v[10:11], v[18:19], v[10:11]
	v_pk_add_f32 v[8:9], v[16:17], v[8:9]
	global_store_dwordx4 v[20:21], v[8:11], off
	global_load_dwordx4 v[8:11], v[26:27], off offset:64
	s_waitcnt vmcnt(0)
	v_pk_add_f32 v[10:11], v[14:15], v[10:11]
	v_pk_add_f32 v[8:9], v[12:13], v[8:9]
	global_store_dwordx4 v[20:21], v[8:11], off offset:64
	global_load_dwordx4 v[8:11], v[26:27], off offset:512
	s_waitcnt vmcnt(0)
	v_pk_add_f32 v[6:7], v[6:7], v[10:11]
	v_pk_add_f32 v[4:5], v[4:5], v[8:9]
	global_store_dwordx4 v[20:21], v[4:7], off offset:512
	global_load_dwordx4 v[4:7], v[26:27], off offset:576
	s_waitcnt vmcnt(0)
	v_pk_add_f32 v[2:3], v[2:3], v[6:7]
	v_pk_add_f32 v[0:1], v[0:1], v[4:5]
	global_store_dwordx4 v[20:21], v[0:3], off offset:576
	s_cbranch_vccz .LBB0_1082
	s_waitcnt vmcnt(0)
	s_cmpk_gt_u32 s3, 0xff
	s_cbranch_scc1 .LBB0_1093
	s_barrier

; #define PG8_STAGE(bufoff, gbase, voff) do { _Pragma("unroll") for (int _i = 0; _i < 2; ++_i) \
;         __builtin_amdgcn_global_load_lds((const unsigned*)((const char*)(gbase) + (voff)[_i]), (LAS unsigned*)(lds + (bufoff) + ldsw + _i * 8192), 16, 0, 0); } while (0)
; #define PG8_LDA(dst, b, h) do { _Pragma("unroll") for (int m = 0; m < 4; ++m) _Pragma("unroll") for (int k = 0; k < 2; ++k) dst[m][k] = *(const LAS bf16x8*)(lds + PG8_SA(b, h) + aoff + m * 2048 + k * 1024); } while (0)
; #define PG8_LDB(dst, b, h) do { _Pragma("unroll") for (int n = 0; n < 2; ++n) _Pragma("unroll") for (int k = 0; k < 2; ++k) dst[n][k] = *(const LAS bf16x8*)(lds + PG8_SB(b, h) + boff + n * 2048 + k * 1024); } while (0)
; #define PG8_MMA(ai, bj, At, Bt) do { __builtin_amdgcn_s_setprio(1); _Pragma("unroll") for (int m = 0; m < 4; ++m) _Pragma("unroll") for (int n = 0; n < 2; ++n) _Pragma("unroll") for (int k = 0; k < 2; ++k) \
;         acc[ai][bj][m][n] = __builtin_amdgcn_mfma_f32_16x16x32_bf16(Bt[n][k], At[m][k], acc[ai][bj][m][n], 0, 0, 0); __builtin_amdgcn_s_setprio(0); } while (0)
; #define PG8_WAIT_L(n) asm volatile("s_waitcnt lgkmcnt(" #n ")" ::: "memory")
; template <class Epi>
; __device__ __forceinline__ void gemm_phase(LAS unsigned char* lds, const Gemm g, const StaticOrder& S, const Epi& E) {
;     ...
;         const bool has_next = S.next(ui + 1, nxt);
;         const char* nA = has_next ? (const char*)g.A + (size_t)nxt.pm * tstepA : cA; const char* nB = has_next ? (const char*)g.Bt + (size_t)nxt.pn * tstepB : cB;
;         for (int t = 0; t < nt; t += 2) {
;             const bool last = (t == nt - 2);
;             const char* a1 = cA + (size_t)(t + 1) * kstep;
;             const char* a2 = last ? nA : cA + (size_t)(t + 2) * kstep; const char* b2 = last ? nB : cB + (size_t)(t + 2) * kstep;
;             const char* a3 = a2 + kstep; const char* b3 = b2 + kstep;
;             PG8_LDB(B0, 0, 0); PG8_SCHED; PG8_LDA(At, 0, 0); PG8_STAGE(PG8_SA(1, 1), a1 + hstepA, voffA);
;             PG8_WAIT_L(8); PG8_BAR; PG8_WAIT_L(0); PG8_MMA(0, 0, At, B0); PG8_BAR; PG8_SCHED;
;             PG8_LDB(B1, 0, 1); PG8_STAGE(PG8_SB(0, 0), b2, voffB);
;             PG8_BAR; PG8_WAIT_L(0); PG8_MMA(0, 1, At, B1); PG8_BAR;
;             PG8_LDA(At, 0, 1); PG8_STAGE(PG8_SA(0, 0), a2, voffA);
;             PG8_BAR; PG8_WAIT_L(0); PG8_MMA(1, 0, At, B0); PG8_BAR; PG8_SCHED;
.LBB0_1103:
	s_ashr_i32 s27, s26, 31
	s_lshl_b64 s[28:29], s[26:27], 17
	s_add_u32 s28, s47, s28
	v_cmp_lt_i64_e32 vcc, s[22:23], v[48:49]
	s_addc_u32 s29, s48, s29
	ds_read_b128 v[0:3], v57
	ds_read_b128 v[4:7], v57 offset:1024
	ds_read_b128 v[8:11], v57 offset:2048
	ds_read_b128 v[12:15], v57 offset:3072
	s_and_b64 s[30:31], vcc, exec
	s_cselect_b32 s45, s29, s39
	s_cselect_b32 s44, s28, s38
	s_ashr_i32 s25, s24, 31
	s_lshl_b64 s[30:31], s[24:25], 17
	s_add_u32 s30, s49, s30
	s_addc_u32 s31, s50, s31
	s_and_b64 s[42:43], vcc, exec
	s_cselect_b32 s43, s31, s41
	s_cselect_b32 s42, s30, s40
	s_add_u32 s78, s38, 0x10080
	s_addc_u32 s79, s39, 0
	s_add_i32 s80, s37, 0xc000
	v_lshl_add_u64 v[52:53], s[78:79], 0, v[40:41]
	s_mov_b32 m0, s80
	s_add_i32 s3, s37, 0xe000
	ds_read_b128 v[16:19], v58
	ds_read_b128 v[20:23], v58 offset:1024
	ds_read_b128 v[24:27], v58 offset:2048
	ds_read_b128 v[28:31], v58 offset:3072
	ds_read_b128 v[32:35], v58 offset:4096
	ds_read_b128 v[36:39], v58 offset:5120
	ds_read_b128 v[60:63], v58 offset:6144
	ds_read_b128 v[64:67], v58 offset:7168
	global_load_lds_dwordx4 v[52:53], off
	v_lshl_add_u64 v[52:53], s[78:79], 0, v[44:45]
	s_mov_b32 m0, s3
	s_nop 0
	global_load_lds_dwordx4 v[52:53], off
	s_waitcnt lgkmcnt(8)
	s_barrier
	s_setprio 1
	s_waitcnt lgkmcnt(7)
	v_mfma_f32_16x16x32_bf16 v[68:71], v[0:3], v[16:19], 0
	v_mfma_f32_16x16x32_bf16 v[72:75], v[8:11], v[16:19], 0
	s_waitcnt lgkmcnt(5)
	v_mfma_f32_16x16x32_bf16 v[76:79], v[0:3], v[24:27], 0
	v_mfma_f32_16x16x32_bf16 v[80:83], v[8:11], v[24:27], 0
	s_waitcnt lgkmcnt(3)
	v_mfma_f32_16x16x32_bf16 v[84:87], v[0:3], v[32:35], 0
	v_mfma_f32_16x16x32_bf16 v[88:91], v[8:11], v[32:35], 0
	s_waitcnt lgkmcnt(1)
	v_mfma_f32_16x16x32_bf16 v[92:95], v[0:3], v[60:63], 0
	v_mfma_f32_16x16x32_bf16 v[96:99], v[8:11], v[60:63], 0
	v_mfma_f32_16x16x32_bf16 v[68:71], v[4:7], v[20:23], v[68:71]
	v_mfma_f32_16x16x32_bf16 v[72:75], v[12:15], v[20:23], v[72:75]
	v_mfma_f32_16x16x32_bf16 v[76:79], v[4:7], v[28:31], v[76:79]
	v_mfma_f32_16x16x32_bf16 v[80:83], v[12:15], v[28:31], v[80:83]
	v_mfma_f32_16x16x32_bf16 v[84:87], v[4:7], v[36:39], v[84:87]
	v_mfma_f32_16x16x32_bf16 v[88:91], v[12:15], v[36:39], v[88:91]
	s_waitcnt lgkmcnt(0)
	v_mfma_f32_16x16x32_bf16 v[92:95], v[4:7], v[64:67], v[92:95]
	v_mfma_f32_16x16x32_bf16 v[96:99], v[12:15], v[64:67], v[96:99]
	s_setprio 0
	s_barrier
	v_lshl_add_u64 v[52:53], s[40:41], 0, v[42:43]
	s_add_i32 s77, s70, s51
	v_lshl_add_u64 v[116:117], v[52:53], 0, s[8:9]
	s_mov_b32 m0, s77
	v_lshl_add_u64 v[186:187], s[40:41], 0, v[46:47]
	s_add_i32 s25, s77, 0x2000
	ds_read_b128 v[100:103], v59
	ds_read_b128 v[104:107], v59 offset:1024
	ds_read_b128 v[108:111], v59 offset:2048
	ds_read_b128 v[112:115], v59 offset:3072
	global_load_lds_dwordx4 v[116:117], off
	v_lshl_add_u64 v[116:117], v[186:187], 0, s[8:9]
	s_mov_b32 m0, s25
	s_nop 0
	global_load_lds_dwordx4 v[116:117], off
	s_barrier
	s_setprio 1
	s_waitcnt lgkmcnt(3)
	v_mfma_f32_16x16x32_bf16 v[116:119], v[100:103], v[16:19], 0
	s_waitcnt lgkmcnt(1)
	v_mfma_f32_16x16x32_bf16 v[16:19], v[108:111], v[16:19], 0
	v_mfma_f32_16x16x32_bf16 v[116:119], v[104:107], v[20:23], v[116:119]
	s_waitcnt lgkmcnt(0)
	v_mfma_f32_16x16x32_bf16 v[16:19], v[112:115], v[20:23], v[16:19]
	v_mfma_f32_16x16x32_bf16 v[20:23], v[100:103], v[24:27], 0
	v_mfma_f32_16x16x32_bf16 v[24:27], v[108:111], v[24:27], 0
	v_mfma_f32_16x16x32_bf16 v[20:23], v[104:107], v[28:31], v[20:23]
	v_mfma_f32_16x16x32_bf16 v[24:27], v[112:115], v[28:31], v[24:27]
	v_mfma_f32_16x16x32_bf16 v[28:31], v[100:103], v[32:35], 0
	v_mfma_f32_16x16x32_bf16 v[32:35], v[108:111], v[32:35], 0
	v_mfma_f32_16x16x32_bf16 v[28:31], v[104:107], v[36:39], v[28:31]
	v_mfma_f32_16x16x32_bf16 v[32:35], v[112:115], v[36:39], v[32:35]
	v_mfma_f32_16x16x32_bf16 v[36:39], v[100:103], v[60:63], 0
	v_mfma_f32_16x16x32_bf16 v[60:63], v[108:111], v[60:63], 0
	v_mfma_f32_16x16x32_bf16 v[36:39], v[104:107], v[64:67], v[36:39]
	v_mfma_f32_16x16x32_bf16 v[60:63], v[112:115], v[64:67], v[60:63]
	s_setprio 0
	v_lshl_add_u64 v[188:189], s[38:39], 0, v[40:41]
	s_mov_b32 m0, s37
	v_lshl_add_u64 v[150:151], v[188:189], 0, s[8:9]
	v_lshl_add_u64 v[218:219], s[38:39], 0, v[44:45]
	s_barrier
	ds_read_b128 v[64:67], v58 offset:16384
	ds_read_b128 v[120:123], v58 offset:17408
	ds_read_b128 v[124:127], v58 offset:18432
	ds_read_b128 v[128:131], v58 offset:19456
	ds_read_b128 v[132:135], v58 offset:20480
	ds_read_b128 v[136:139], v58 offset:21504
	ds_read_b128 v[140:143], v58 offset:22528
	ds_read_b128 v[144:147], v58 offset:23552
	global_load_lds_dwordx4 v[150:151], off
	v_lshl_add_u64 v[150:151], v[218:219], 0, s[8:9]
	s_mov_b32 m0, s60
	s_nop 0
	global_load_lds_dwordx4 v[150:151], off
	s_barrier
	s_setprio 1
	s_waitcnt lgkmcnt(7)
	v_mfma_f32_16x16x32_bf16 v[150:153], v[0:3], v[64:67], 0
	s_waitcnt lgkmcnt(5)
	v_mfma_f32_16x16x32_bf16 v[158:161], v[0:3], v[124:127], 0
	s_waitcnt lgkmcnt(3)
	v_mfma_f32_16x16x32_bf16 v[166:169], v[0:3], v[132:135], 0
	s_waitcnt lgkmcnt(1)
	v_mfma_f32_16x16x32_bf16 v[0:3], v[0:3], v[140:143], 0
	v_mfma_f32_16x16x32_bf16 v[150:153], v[4:7], v[120:123], v[150:153]
	v_mfma_f32_16x16x32_bf16 v[154:157], v[8:11], v[64:67], 0
	v_mfma_f32_16x16x32_bf16 v[158:161], v[4:7], v[128:131], v[158:161]
	v_mfma_f32_16x16x32_bf16 v[162:165], v[8:11], v[124:127], 0
	v_mfma_f32_16x16x32_bf16 v[166:169], v[4:7], v[136:139], v[166:169]
	v_mfma_f32_16x16x32_bf16 v[170:173], v[8:11], v[132:135], 0
	s_waitcnt lgkmcnt(0)
	v_mfma_f32_16x16x32_bf16 v[0:3], v[4:7], v[144:147], v[0:3]
	v_mfma_f32_16x16x32_bf16 v[4:7], v[8:11], v[140:143], 0
	v_mfma_f32_16x16x32_bf16 v[154:157], v[12:15], v[120:123], v[154:157]
	v_mfma_f32_16x16x32_bf16 v[162:165], v[12:15], v[128:131], v[162:165]
	v_mfma_f32_16x16x32_bf16 v[170:173], v[12:15], v[136:139], v[170:173]
	v_mfma_f32_16x16x32_bf16 v[4:7], v[12:15], v[144:147], v[4:7]
	s_setprio 0
	s_barrier
; #define PG8_STAGE(bufoff, gbase, voff) do { _Pragma("unroll") for (int _i = 0; _i < 2; ++_i) \
;         __builtin_amdgcn_global_load_lds((const unsigned*)((const char*)(gbase) + (voff)[_i]), (LAS unsigned*)(lds + (bufoff) + ldsw + _i * 8192), 16, 0, 0); } while (0)
; #define PG8_LDA(dst, b, h) do { _Pragma("unroll") for (int m = 0; m < 4; ++m) _Pragma("unroll") for (int k = 0; k < 2; ++k) dst[m][k] = *(const LAS bf16x8*)(lds + PG8_SA(b, h) + aoff + m * 2048 + k * 1024); } while (0)
; #define PG8_LDB(dst, b, h) do { _Pragma("unroll") for (int n = 0; n < 2; ++n) _Pragma("unroll") for (int k = 0; k < 2; ++k) dst[n][k] = *(const LAS bf16x8*)(lds + PG8_SB(b, h) + boff + n * 2048 + k * 1024); } while (0)
; #define PG8_MMA(ai, bj, At, Bt) do { __builtin_amdgcn_s_setprio(1); _Pragma("unroll") for (int m = 0; m < 4; ++m) _Pragma("unroll") for (int n = 0; n < 2; ++n) _Pragma("unroll") for (int k = 0; k < 2; ++k) \
;         acc[ai][bj][m][n] = __builtin_amdgcn_mfma_f32_16x16x32_bf16(Bt[n][k], At[m][k], acc[ai][bj][m][n], 0, 0, 0); __builtin_amdgcn_s_setprio(0); } while (0)
; #define PG8_WAIT_V(n) asm volatile("s_waitcnt vmcnt(" #n ")" ::: "memory")
; #define PG8_WAIT_L(n) asm volatile("s_waitcnt lgkmcnt(" #n ")" ::: "memory")
; #define PG8_BAR __builtin_amdgcn_s_barrier()
; #define PG8_SCHED __builtin_amdgcn_sched_barrier(0)
; template <class Epi>
; __device__ __forceinline__ void gemm_phase(LAS unsigned char* lds, const Gemm g, const StaticOrder& S, const Epi& E) {
;     ...
;             PG8_STAGE(PG8_SB(0, 1), b2 + hstepB, voffB);
;             PG8_WAIT_V(6); PG8_BAR; PG8_MMA(1, 1, At, B1); PG8_BAR;
;             PG8_LDB(B0, 1, 0); PG8_SCHED; PG8_LDA(At, 1, 0); PG8_STAGE(PG8_SA(0, 1), a2 + hstepA, voffA);
;             PG8_WAIT_L(8); PG8_BAR; PG8_WAIT_L(0); PG8_MMA(0, 0, At, B0); PG8_BAR; PG8_SCHED;
;             PG8_LDB(B1, 1, 1); PG8_STAGE(PG8_SB(1, 0), b3, voffB);
;             PG8_BAR; PG8_WAIT_L(0); PG8_MMA(0, 1, At, B1); PG8_BAR;
;             PG8_LDA(At, 1, 1); PG8_STAGE(PG8_SA(1, 0), a3, voffA);
;             PG8_BAR; PG8_WAIT_L(0); PG8_MMA(1, 0, At, B0); PG8_BAR; PG8_SCHED;
	s_add_u32 s82, s40, 0x10100
	s_addc_u32 s83, s41, 0
	s_add_i32 s78, s71, s51
	v_lshl_add_u64 v[8:9], s[82:83], 0, v[42:43]
	s_mov_b32 m0, s78
	s_add_i32 s27, s78, 0x2000
	global_load_lds_dwordx4 v[8:9], off
	v_lshl_add_u64 v[8:9], s[82:83], 0, v[46:47]
	s_mov_b32 m0, s27
	s_nop 0
	global_load_lds_dwordx4 v[8:9], off
	s_waitcnt vmcnt(6)
	s_barrier
	s_setprio 1
	v_mfma_f32_16x16x32_bf16 v[8:11], v[100:103], v[64:67], 0
	v_mfma_f32_16x16x32_bf16 v[12:15], v[108:111], v[64:67], 0
	v_mfma_f32_16x16x32_bf16 v[8:11], v[104:107], v[120:123], v[8:11]
	v_mfma_f32_16x16x32_bf16 v[12:15], v[112:115], v[120:123], v[12:15]
	v_mfma_f32_16x16x32_bf16 v[64:67], v[100:103], v[124:127], 0
	v_mfma_f32_16x16x32_bf16 v[120:123], v[108:111], v[124:127], 0
	v_mfma_f32_16x16x32_bf16 v[124:127], v[100:103], v[132:135], 0
	v_mfma_f32_16x16x32_bf16 v[100:103], v[100:103], v[140:143], 0
	v_mfma_f32_16x16x32_bf16 v[64:67], v[104:107], v[128:131], v[64:67]
	v_mfma_f32_16x16x32_bf16 v[120:123], v[112:115], v[128:131], v[120:123]
	v_mfma_f32_16x16x32_bf16 v[124:127], v[104:107], v[136:139], v[124:127]
	v_mfma_f32_16x16x32_bf16 v[128:131], v[108:111], v[132:135], 0
	v_mfma_f32_16x16x32_bf16 v[100:103], v[104:107], v[144:147], v[100:103]
	v_mfma_f32_16x16x32_bf16 v[104:107], v[108:111], v[140:143], 0
	v_mfma_f32_16x16x32_bf16 v[128:131], v[112:115], v[136:139], v[128:131]
	v_mfma_f32_16x16x32_bf16 v[104:107], v[112:115], v[144:147], v[104:107]
	s_setprio 0
	s_add_i32 s81, 0, 0x18000
	v_add_u32_e32 v149, s81, v55
	s_barrier
	ds_read_b128 v[108:111], v149
	ds_read_b128 v[112:115], v149 offset:1024
	ds_read_b128 v[132:135], v149 offset:2048
	ds_read_b128 v[136:139], v149 offset:3072
	s_add_u32 s82, s38, 0x10100
	s_addc_u32 s83, s39, 0
	s_mov_b32 m0, s61
	v_lshl_add_u64 v[202:203], s[82:83], 0, v[40:41]
	ds_read_b128 v[140:143], v58 offset:32768
	ds_read_b128 v[144:147], v58 offset:33792
	ds_read_b128 v[174:177], v58 offset:34816
	ds_read_b128 v[178:181], v58 offset:35840
	ds_read_b128 v[182:185], v58 offset:36864
	ds_read_b128 v[190:193], v58 offset:37888
	ds_read_b128 v[194:197], v58 offset:38912
	ds_read_b128 v[198:201], v58 offset:39936
	global_load_lds_dwordx4 v[202:203], off
	v_lshl_add_u64 v[202:203], s[82:83], 0, v[44:45]
	s_mov_b32 m0, s64
	s_nop 0
	global_load_lds_dwordx4 v[202:203], off
	s_waitcnt lgkmcnt(8)
	s_barrier
	s_setprio 1
	s_waitcnt lgkmcnt(7)
	v_mfma_f32_16x16x32_bf16 v[68:71], v[108:111], v[140:143], v[68:71]
	v_mfma_f32_16x16x32_bf16 v[72:75], v[132:135], v[140:143], v[72:75]
	s_waitcnt lgkmcnt(5)
	v_mfma_f32_16x16x32_bf16 v[76:79], v[108:111], v[174:177], v[76:79]
	v_mfma_f32_16x16x32_bf16 v[80:83], v[132:135], v[174:177], v[80:83]
	s_waitcnt lgkmcnt(3)
	v_mfma_f32_16x16x32_bf16 v[84:87], v[108:111], v[182:185], v[84:87]
	v_mfma_f32_16x16x32_bf16 v[88:91], v[132:135], v[182:185], v[88:91]
	s_waitcnt lgkmcnt(1)
	v_mfma_f32_16x16x32_bf16 v[92:95], v[108:111], v[194:197], v[92:95]
	v_mfma_f32_16x16x32_bf16 v[96:99], v[132:135], v[194:197], v[96:99]
	v_mfma_f32_16x16x32_bf16 v[68:71], v[112:115], v[144:147], v[68:71]
	v_mfma_f32_16x16x32_bf16 v[72:75], v[136:139], v[144:147], v[72:75]
	v_mfma_f32_16x16x32_bf16 v[76:79], v[112:115], v[178:181], v[76:79]
	v_mfma_f32_16x16x32_bf16 v[80:83], v[136:139], v[178:181], v[80:83]
	v_mfma_f32_16x16x32_bf16 v[84:87], v[112:115], v[190:193], v[84:87]
	v_mfma_f32_16x16x32_bf16 v[88:91], v[136:139], v[190:193], v[88:91]
	s_waitcnt lgkmcnt(0)
	v_mfma_f32_16x16x32_bf16 v[92:95], v[112:115], v[198:201], v[92:95]
	v_mfma_f32_16x16x32_bf16 v[96:99], v[136:139], v[198:201], v[96:99]
	s_setprio 0
	s_barrier
	s_add_i32 s84, 0, 0x1c000
	s_add_i32 s81, s81, s51
	v_add_u32_e32 v220, s84, v55
	v_lshl_add_u64 v[52:53], v[52:53], 0, s[12:13]
	s_mov_b32 m0, s81
	s_add_i32 s79, s81, 0x2000
	ds_read_b128 v[202:205], v220
	ds_read_b128 v[206:209], v220 offset:1024
	ds_read_b128 v[210:213], v220 offset:2048
	ds_read_b128 v[214:217], v220 offset:3072
	global_load_lds_dwordx4 v[52:53], off
	v_lshl_add_u64 v[52:53], v[186:187], 0, s[12:13]
	s_mov_b32 m0, s79
	s_nop 0
	global_load_lds_dwordx4 v[52:53], off
	s_barrier
	s_setprio 1
	s_waitcnt lgkmcnt(3)
	v_mfma_f32_16x16x32_bf16 v[116:119], v[202:205], v[140:143], v[116:119]
	s_waitcnt lgkmcnt(1)
	v_mfma_f32_16x16x32_bf16 v[16:19], v[210:213], v[140:143], v[16:19]
	v_mfma_f32_16x16x32_bf16 v[20:23], v[202:205], v[174:177], v[20:23]
	v_mfma_f32_16x16x32_bf16 v[24:27], v[210:213], v[174:177], v[24:27]
	v_mfma_f32_16x16x32_bf16 v[28:31], v[202:205], v[182:185], v[28:31]
	v_mfma_f32_16x16x32_bf16 v[32:35], v[210:213], v[182:185], v[32:35]
	v_mfma_f32_16x16x32_bf16 v[36:39], v[202:205], v[194:197], v[36:39]
	v_mfma_f32_16x16x32_bf16 v[60:63], v[210:213], v[194:197], v[60:63]
	v_mfma_f32_16x16x32_bf16 v[116:119], v[206:209], v[144:147], v[116:119]
	s_waitcnt lgkmcnt(0)
	v_mfma_f32_16x16x32_bf16 v[16:19], v[214:217], v[144:147], v[16:19]
	v_mfma_f32_16x16x32_bf16 v[20:23], v[206:209], v[178:181], v[20:23]
	v_mfma_f32_16x16x32_bf16 v[24:27], v[214:217], v[178:181], v[24:27]
	v_mfma_f32_16x16x32_bf16 v[28:31], v[206:209], v[190:193], v[28:31]
	v_mfma_f32_16x16x32_bf16 v[32:35], v[214:217], v[190:193], v[32:35]
	v_mfma_f32_16x16x32_bf16 v[36:39], v[206:209], v[198:201], v[36:39]
	v_mfma_f32_16x16x32_bf16 v[60:63], v[214:217], v[198:201], v[60:63]
	s_setprio 0
	s_mov_b32 m0, s65
	v_lshl_add_u64 v[52:53], v[188:189], 0, s[12:13]
	s_barrier
	ds_read_b128 v[140:143], v58 offset:49152
	ds_read_b128 v[144:147], v58 offset:50176
	ds_read_b128 v[174:177], v58 offset:51200
	ds_read_b128 v[178:181], v58 offset:52224
	ds_read_b128 v[182:185], v58 offset:53248
	ds_read_b128 v[190:193], v58 offset:54272
	ds_read_b128 v[194:197], v58 offset:55296
	ds_read_b128 v[198:201], v58 offset:56320
	global_load_lds_dwordx4 v[52:53], off
	v_lshl_add_u64 v[52:53], v[218:219], 0, s[12:13]
	s_mov_b32 m0, s66
	s_nop 0
	global_load_lds_dwordx4 v[52:53], off
	s_barrier
; #define PG8_STAGE(bufoff, gbase, voff) do { _Pragma("unroll") for (int _i = 0; _i < 2; ++_i) \
;         __builtin_amdgcn_global_load_lds((const unsigned*)((const char*)(gbase) + (voff)[_i]), (LAS unsigned*)(lds + (bufoff) + ldsw + _i * 8192), 16, 0, 0); } while (0)
; #define PG8_LDA(dst, b, h) do { _Pragma("unroll") for (int m = 0; m < 4; ++m) _Pragma("unroll") for (int k = 0; k < 2; ++k) dst[m][k] = *(const LAS bf16x8*)(lds + PG8_SA(b, h) + aoff + m * 2048 + k * 1024); } while (0)
; #define PG8_LDB(dst, b, h) do { _Pragma("unroll") for (int n = 0; n < 2; ++n) _Pragma("unroll") for (int k = 0; k < 2; ++k) dst[n][k] = *(const LAS bf16x8*)(lds + PG8_SB(b, h) + boff + n * 2048 + k * 1024); } while (0)
; #define PG8_MMA(ai, bj, At, Bt) do { __builtin_amdgcn_s_setprio(1); _Pragma("unroll") for (int m = 0; m < 4; ++m) _Pragma("unroll") for (int n = 0; n < 2; ++n) _Pragma("unroll") for (int k = 0; k < 2; ++k) \
;         acc[ai][bj][m][n] = __builtin_amdgcn_mfma_f32_16x16x32_bf16(Bt[n][k], At[m][k], acc[ai][bj][m][n], 0, 0, 0); __builtin_amdgcn_s_setprio(0); } while (0)
; #define PG8_WAIT_V(n) asm volatile("s_waitcnt vmcnt(" #n ")" ::: "memory")
; #define PG8_WAIT_L(n) asm volatile("s_waitcnt lgkmcnt(" #n ")" ::: "memory")
; #define PG8_BAR __builtin_amdgcn_s_barrier()
; #define PG8_SCHED __builtin_amdgcn_sched_barrier(0)
; template <class Epi>
; __device__ __forceinline__ void gemm_phase(LAS unsigned char* lds, const Gemm g, const StaticOrder& S, const Epi& E) {
;     ...
;             PG8_LDB(B0, 0, 0); PG8_SCHED; PG8_LDA(At, 0, 0); PG8_STAGE(PG8_SA(1, 1), a1 + hstepA, voffA);
;             PG8_WAIT_L(8); PG8_BAR; PG8_WAIT_L(0); PG8_MMA(0, 0, At, B0); PG8_BAR; PG8_SCHED;
;             PG8_LDB(B1, 0, 1); PG8_STAGE(PG8_SB(0, 0), b2, voffB);
;             PG8_BAR; PG8_WAIT_L(0); PG8_MMA(0, 1, At, B1); PG8_BAR;
;             PG8_LDA(At, 0, 1); PG8_STAGE(PG8_SA(0, 0), a2, voffA);
;             PG8_BAR; PG8_WAIT_L(0); PG8_MMA(1, 0, At, B0); PG8_BAR; PG8_SCHED;
;     ...
;             PG8_BAR; PG8_WAIT_L(0); PG8_MMA(1, 0, At, B0); PG8_BAR; PG8_SCHED;
;             PG8_STAGE(PG8_SB(1, 1), b3 + hstepB, voffB);
;             PG8_WAIT_V(6); PG8_BAR; PG8_MMA(1, 1, At, B1); PG8_BAR;
	s_setprio 1
	s_waitcnt lgkmcnt(7)
	v_mfma_f32_16x16x32_bf16 v[150:153], v[108:111], v[140:143], v[150:153]
	v_mfma_f32_16x16x32_bf16 v[154:157], v[132:135], v[140:143], v[154:157]
	s_waitcnt lgkmcnt(5)
	v_mfma_f32_16x16x32_bf16 v[158:161], v[108:111], v[174:177], v[158:161]
	v_mfma_f32_16x16x32_bf16 v[162:165], v[132:135], v[174:177], v[162:165]
	s_waitcnt lgkmcnt(3)
	v_mfma_f32_16x16x32_bf16 v[166:169], v[108:111], v[182:185], v[166:169]
	v_mfma_f32_16x16x32_bf16 v[170:173], v[132:135], v[182:185], v[170:173]
	s_waitcnt lgkmcnt(1)
	v_mfma_f32_16x16x32_bf16 v[0:3], v[108:111], v[194:197], v[0:3]
	v_mfma_f32_16x16x32_bf16 v[4:7], v[132:135], v[194:197], v[4:7]
	v_mfma_f32_16x16x32_bf16 v[150:153], v[112:115], v[144:147], v[150:153]
	v_mfma_f32_16x16x32_bf16 v[154:157], v[136:139], v[144:147], v[154:157]
	v_mfma_f32_16x16x32_bf16 v[158:161], v[112:115], v[178:181], v[158:161]
	v_mfma_f32_16x16x32_bf16 v[162:165], v[136:139], v[178:181], v[162:165]
	v_mfma_f32_16x16x32_bf16 v[166:169], v[112:115], v[190:193], v[166:169]
	v_mfma_f32_16x16x32_bf16 v[170:173], v[136:139], v[190:193], v[170:173]
	s_waitcnt lgkmcnt(0)
	v_mfma_f32_16x16x32_bf16 v[0:3], v[112:115], v[198:201], v[0:3]
	v_mfma_f32_16x16x32_bf16 v[4:7], v[136:139], v[198:201], v[4:7]
	s_setprio 0
	s_barrier
	s_add_u32 s82, s40, 0x10180
	s_addc_u32 s83, s41, 0
	s_add_i32 s41, s84, s51
	v_lshl_add_u64 v[52:53], s[82:83], 0, v[42:43]
	s_mov_b32 m0, s41
	s_add_i32 s40, s41, 0x2000
	global_load_lds_dwordx4 v[52:53], off
	v_lshl_add_u64 v[52:53], s[82:83], 0, v[46:47]
	s_mov_b32 m0, s40
	s_nop 0
	global_load_lds_dwordx4 v[52:53], off
	s_waitcnt vmcnt(6)
	s_barrier
	s_setprio 1
	v_mfma_f32_16x16x32_bf16 v[8:11], v[202:205], v[140:143], v[8:11]
	v_mfma_f32_16x16x32_bf16 v[12:15], v[210:213], v[140:143], v[12:15]
	v_mfma_f32_16x16x32_bf16 v[64:67], v[202:205], v[174:177], v[64:67]
	v_mfma_f32_16x16x32_bf16 v[108:111], v[210:213], v[174:177], v[120:123]
	v_mfma_f32_16x16x32_bf16 v[112:115], v[202:205], v[182:185], v[124:127]
	v_mfma_f32_16x16x32_bf16 v[120:123], v[210:213], v[182:185], v[128:131]
	v_mfma_f32_16x16x32_bf16 v[100:103], v[202:205], v[194:197], v[100:103]
	v_mfma_f32_16x16x32_bf16 v[104:107], v[210:213], v[194:197], v[104:107]
	v_mfma_f32_16x16x32_bf16 v[8:11], v[206:209], v[144:147], v[8:11]
	v_mfma_f32_16x16x32_bf16 v[12:15], v[214:217], v[144:147], v[12:15]
	v_mfma_f32_16x16x32_bf16 v[64:67], v[206:209], v[178:181], v[64:67]
	v_mfma_f32_16x16x32_bf16 v[108:111], v[214:217], v[178:181], v[108:111]
	v_mfma_f32_16x16x32_bf16 v[112:115], v[206:209], v[190:193], v[112:115]
	v_mfma_f32_16x16x32_bf16 v[120:123], v[214:217], v[190:193], v[120:123]
	v_mfma_f32_16x16x32_bf16 v[100:103], v[206:209], v[198:201], v[100:103]
	v_mfma_f32_16x16x32_bf16 v[104:107], v[214:217], v[198:201], v[104:107]
	s_setprio 0
	s_barrier
	ds_read_b128 v[124:127], v57
	ds_read_b128 v[128:131], v57 offset:1024
	ds_read_b128 v[132:135], v57 offset:2048
	ds_read_b128 v[136:139], v57 offset:3072
	s_add_u32 s38, s38, 0x10180
	s_addc_u32 s39, s39, 0
	s_mov_b32 m0, s80
	v_lshl_add_u64 v[52:53], s[38:39], 0, v[40:41]
	ds_read_b128 v[140:143], v58
	ds_read_b128 v[144:147], v58 offset:1024
	ds_read_b128 v[174:177], v58 offset:2048
	ds_read_b128 v[178:181], v58 offset:3072
	ds_read_b128 v[182:185], v58 offset:4096
	ds_read_b128 v[190:193], v58 offset:5120
	ds_read_b128 v[194:197], v58 offset:6144
	ds_read_b128 v[198:201], v58 offset:7168
	global_load_lds_dwordx4 v[52:53], off
	v_lshl_add_u64 v[52:53], s[38:39], 0, v[44:45]
	s_mov_b32 m0, s3
	s_nop 0
	global_load_lds_dwordx4 v[52:53], off
	s_waitcnt lgkmcnt(8)
	s_barrier
	s_setprio 1
	s_waitcnt lgkmcnt(7)
	v_mfma_f32_16x16x32_bf16 v[68:71], v[124:127], v[140:143], v[68:71]
	v_mfma_f32_16x16x32_bf16 v[72:75], v[132:135], v[140:143], v[72:75]
	s_waitcnt lgkmcnt(5)
	v_mfma_f32_16x16x32_bf16 v[76:79], v[124:127], v[174:177], v[76:79]
	v_mfma_f32_16x16x32_bf16 v[80:83], v[132:135], v[174:177], v[80:83]
	s_waitcnt lgkmcnt(3)
	v_mfma_f32_16x16x32_bf16 v[84:87], v[124:127], v[182:185], v[84:87]
	v_mfma_f32_16x16x32_bf16 v[88:91], v[132:135], v[182:185], v[88:91]
	s_waitcnt lgkmcnt(1)
	v_mfma_f32_16x16x32_bf16 v[92:95], v[124:127], v[194:197], v[92:95]
	v_mfma_f32_16x16x32_bf16 v[96:99], v[132:135], v[194:197], v[96:99]
	v_mfma_f32_16x16x32_bf16 v[68:71], v[128:131], v[144:147], v[68:71]
	v_mfma_f32_16x16x32_bf16 v[72:75], v[136:139], v[144:147], v[72:75]
	v_mfma_f32_16x16x32_bf16 v[76:79], v[128:131], v[178:181], v[76:79]
	v_mfma_f32_16x16x32_bf16 v[80:83], v[136:139], v[178:181], v[80:83]
	v_mfma_f32_16x16x32_bf16 v[84:87], v[128:131], v[190:193], v[84:87]
	v_mfma_f32_16x16x32_bf16 v[88:91], v[136:139], v[190:193], v[88:91]
	s_waitcnt lgkmcnt(0)
	v_mfma_f32_16x16x32_bf16 v[92:95], v[128:131], v[198:201], v[92:95]
	v_mfma_f32_16x16x32_bf16 v[96:99], v[136:139], v[198:201], v[96:99]
	s_setprio 0
	s_barrier
	s_mov_b32 m0, s77
	v_lshl_add_u64 v[52:53], s[42:43], 0, v[42:43]
	ds_read_b128 v[202:205], v59
	ds_read_b128 v[206:209], v59 offset:1024
	ds_read_b128 v[210:213], v59 offset:2048
	ds_read_b128 v[214:217], v59 offset:3072
	global_load_lds_dwordx4 v[52:53], off
	v_lshl_add_u64 v[186:187], s[42:43], 0, v[46:47]
	s_mov_b32 m0, s25
	s_nop 0
	global_load_lds_dwordx4 v[186:187], off
	s_barrier
; #define PG8_STAGE(bufoff, gbase, voff) do { _Pragma("unroll") for (int _i = 0; _i < 2; ++_i) \
;         __builtin_amdgcn_global_load_lds((const unsigned*)((const char*)(gbase) + (voff)[_i]), (LAS unsigned*)(lds + (bufoff) + ldsw + _i * 8192), 16, 0, 0); } while (0)
; #define PG8_LDA(dst, b, h) do { _Pragma("unroll") for (int m = 0; m < 4; ++m) _Pragma("unroll") for (int k = 0; k < 2; ++k) dst[m][k] = *(const LAS bf16x8*)(lds + PG8_SA(b, h) + aoff + m * 2048 + k * 1024); } while (0)
; #define PG8_LDB(dst, b, h) do { _Pragma("unroll") for (int n = 0; n < 2; ++n) _Pragma("unroll") for (int k = 0; k < 2; ++k) dst[n][k] = *(const LAS bf16x8*)(lds + PG8_SB(b, h) + boff + n * 2048 + k * 1024); } while (0)
; #define PG8_MMA(ai, bj, At, Bt) do { __builtin_amdgcn_s_setprio(1); _Pragma("unroll") for (int m = 0; m < 4; ++m) _Pragma("unroll") for (int n = 0; n < 2; ++n) _Pragma("unroll") for (int k = 0; k < 2; ++k) \
;         acc[ai][bj][m][n] = __builtin_amdgcn_mfma_f32_16x16x32_bf16(Bt[n][k], At[m][k], acc[ai][bj][m][n], 0, 0, 0); __builtin_amdgcn_s_setprio(0); } while (0)
; #define PG8_WAIT_V(n) asm volatile("s_waitcnt vmcnt(" #n ")" ::: "memory")
; #define PG8_WAIT_L(n) asm volatile("s_waitcnt lgkmcnt(" #n ")" ::: "memory")
; #define PG8_BAR __builtin_amdgcn_s_barrier()
; #define PG8_SCHED __builtin_amdgcn_sched_barrier(0)
; template <class Epi>
; __device__ __forceinline__ void gemm_phase(LAS unsigned char* lds, const Gemm g, const StaticOrder& S, const Epi& E) {
;     ...
;             PG8_BAR; PG8_WAIT_L(0); PG8_MMA(0, 1, At, B1); PG8_BAR;
;             PG8_LDA(At, 0, 1); PG8_STAGE(PG8_SA(0, 0), a2, voffA);
;             PG8_BAR; PG8_WAIT_L(0); PG8_MMA(1, 0, At, B0); PG8_BAR; PG8_SCHED;
;             PG8_STAGE(PG8_SB(0, 1), b2 + hstepB, voffB);
;             PG8_WAIT_V(6); PG8_BAR; PG8_MMA(1, 1, At, B1); PG8_BAR;
;             PG8_LDB(B0, 1, 0); PG8_SCHED; PG8_LDA(At, 1, 0); PG8_STAGE(PG8_SA(0, 1), a2 + hstepA, voffA);
;             PG8_WAIT_L(8); PG8_BAR; PG8_WAIT_L(0); PG8_MMA(0, 0, At, B0); PG8_BAR; PG8_SCHED;
;             PG8_LDB(B1, 1, 1); PG8_STAGE(PG8_SB(1, 0), b3, voffB);
;             PG8_BAR; PG8_WAIT_L(0); PG8_MMA(0, 1, At, B1); PG8_BAR;
	s_setprio 1
	s_waitcnt lgkmcnt(3)
	v_mfma_f32_16x16x32_bf16 v[116:119], v[202:205], v[140:143], v[116:119]
	s_waitcnt lgkmcnt(1)
	v_mfma_f32_16x16x32_bf16 v[16:19], v[210:213], v[140:143], v[16:19]
	v_mfma_f32_16x16x32_bf16 v[20:23], v[202:205], v[174:177], v[20:23]
	v_mfma_f32_16x16x32_bf16 v[24:27], v[210:213], v[174:177], v[24:27]
	v_mfma_f32_16x16x32_bf16 v[28:31], v[202:205], v[182:185], v[28:31]
	v_mfma_f32_16x16x32_bf16 v[32:35], v[210:213], v[182:185], v[32:35]
	v_mfma_f32_16x16x32_bf16 v[36:39], v[202:205], v[194:197], v[36:39]
	v_mfma_f32_16x16x32_bf16 v[60:63], v[210:213], v[194:197], v[60:63]
	v_mfma_f32_16x16x32_bf16 v[116:119], v[206:209], v[144:147], v[116:119]
	s_waitcnt lgkmcnt(0)
	v_mfma_f32_16x16x32_bf16 v[16:19], v[214:217], v[144:147], v[16:19]
	v_mfma_f32_16x16x32_bf16 v[20:23], v[206:209], v[178:181], v[20:23]
	v_mfma_f32_16x16x32_bf16 v[24:27], v[214:217], v[178:181], v[24:27]
	v_mfma_f32_16x16x32_bf16 v[28:31], v[206:209], v[190:193], v[28:31]
	v_mfma_f32_16x16x32_bf16 v[32:35], v[214:217], v[190:193], v[32:35]
	v_mfma_f32_16x16x32_bf16 v[36:39], v[206:209], v[198:201], v[36:39]
	v_mfma_f32_16x16x32_bf16 v[60:63], v[214:217], v[198:201], v[60:63]
	s_setprio 0
	s_mov_b32 m0, s37
	v_lshl_add_u64 v[188:189], s[44:45], 0, v[40:41]
	s_barrier
	ds_read_b128 v[140:143], v58 offset:16384
	ds_read_b128 v[144:147], v58 offset:17408
	ds_read_b128 v[174:177], v58 offset:18432
	ds_read_b128 v[178:181], v58 offset:19456
	ds_read_b128 v[182:185], v58 offset:20480
	ds_read_b128 v[190:193], v58 offset:21504
	ds_read_b128 v[194:197], v58 offset:22528
	ds_read_b128 v[198:201], v58 offset:23552
	global_load_lds_dwordx4 v[188:189], off
	v_lshl_add_u64 v[234:235], s[44:45], 0, v[44:45]
	s_mov_b32 m0, s60
	s_nop 0
	global_load_lds_dwordx4 v[234:235], off
	s_barrier
	s_setprio 1
	s_waitcnt lgkmcnt(7)
	v_mfma_f32_16x16x32_bf16 v[150:153], v[124:127], v[140:143], v[150:153]
	v_mfma_f32_16x16x32_bf16 v[154:157], v[132:135], v[140:143], v[154:157]
	s_waitcnt lgkmcnt(5)
	v_mfma_f32_16x16x32_bf16 v[158:161], v[124:127], v[174:177], v[158:161]
	v_mfma_f32_16x16x32_bf16 v[162:165], v[132:135], v[174:177], v[162:165]
	s_waitcnt lgkmcnt(3)
	v_mfma_f32_16x16x32_bf16 v[166:169], v[124:127], v[182:185], v[166:169]
	v_mfma_f32_16x16x32_bf16 v[170:173], v[132:135], v[182:185], v[170:173]
	s_waitcnt lgkmcnt(1)
	v_mfma_f32_16x16x32_bf16 v[0:3], v[124:127], v[194:197], v[0:3]
	v_mfma_f32_16x16x32_bf16 v[4:7], v[132:135], v[194:197], v[4:7]
	v_mfma_f32_16x16x32_bf16 v[150:153], v[128:131], v[144:147], v[150:153]
	v_mfma_f32_16x16x32_bf16 v[154:157], v[136:139], v[144:147], v[154:157]
	v_mfma_f32_16x16x32_bf16 v[158:161], v[128:131], v[178:181], v[158:161]
	v_mfma_f32_16x16x32_bf16 v[162:165], v[136:139], v[178:181], v[162:165]
	v_mfma_f32_16x16x32_bf16 v[166:169], v[128:131], v[190:193], v[166:169]
	v_mfma_f32_16x16x32_bf16 v[170:173], v[136:139], v[190:193], v[170:173]
	s_waitcnt lgkmcnt(0)
	v_mfma_f32_16x16x32_bf16 v[0:3], v[128:131], v[198:201], v[0:3]
	v_mfma_f32_16x16x32_bf16 v[124:127], v[136:139], v[198:201], v[4:7]
	s_setprio 0
	s_barrier
	s_add_u32 s38, s42, 0x10000
	s_addc_u32 s39, s43, 0
	s_mov_b32 m0, s78
	v_lshl_add_u64 v[4:5], s[38:39], 0, v[42:43]
	global_load_lds_dwordx4 v[4:5], off
	v_lshl_add_u64 v[4:5], s[38:39], 0, v[46:47]
	s_mov_b32 m0, s27
	s_nop 0
	global_load_lds_dwordx4 v[4:5], off
	s_waitcnt vmcnt(6)
	s_barrier
	s_setprio 1
	v_mfma_f32_16x16x32_bf16 v[4:7], v[202:205], v[140:143], v[8:11]
	v_mfma_f32_16x16x32_bf16 v[8:11], v[206:209], v[144:147], v[4:7]
	v_mfma_f32_16x16x32_bf16 v[4:7], v[210:213], v[140:143], v[12:15]
	v_mfma_f32_16x16x32_bf16 v[12:15], v[214:217], v[144:147], v[4:7]
	v_mfma_f32_16x16x32_bf16 v[4:7], v[202:205], v[174:177], v[64:67]
	v_mfma_f32_16x16x32_bf16 v[64:67], v[206:209], v[178:181], v[4:7]
	v_mfma_f32_16x16x32_bf16 v[4:7], v[210:213], v[174:177], v[108:111]
	v_mfma_f32_16x16x32_bf16 v[108:111], v[214:217], v[178:181], v[4:7]
	v_mfma_f32_16x16x32_bf16 v[4:7], v[202:205], v[182:185], v[112:115]
	v_mfma_f32_16x16x32_bf16 v[112:115], v[206:209], v[190:193], v[4:7]
	v_mfma_f32_16x16x32_bf16 v[4:7], v[210:213], v[182:185], v[120:123]
	v_mfma_f32_16x16x32_bf16 v[120:123], v[214:217], v[190:193], v[4:7]
	v_mfma_f32_16x16x32_bf16 v[4:7], v[202:205], v[194:197], v[100:103]
	v_mfma_f32_16x16x32_bf16 v[100:103], v[206:209], v[198:201], v[4:7]
	v_mfma_f32_16x16x32_bf16 v[4:7], v[210:213], v[194:197], v[104:107]
	v_mfma_f32_16x16x32_bf16 v[104:107], v[214:217], v[198:201], v[4:7]
	s_setprio 0
	s_barrier
	s_nop 4
	ds_read_b128 v[4:7], v149
	ds_read_b128 v[128:131], v149 offset:1024
	ds_read_b128 v[132:135], v149 offset:2048
	ds_read_b128 v[136:139], v149 offset:3072
	s_add_u32 s38, s44, 0x10000
	s_addc_u32 s39, s45, 0
	s_mov_b32 m0, s61
	v_lshl_add_u64 v[202:203], s[38:39], 0, v[40:41]
	ds_read_b128 v[140:143], v58 offset:32768
	ds_read_b128 v[144:147], v58 offset:33792
	ds_read_b128 v[174:177], v58 offset:34816
	ds_read_b128 v[178:181], v58 offset:35840
	ds_read_b128 v[182:185], v58 offset:36864
	ds_read_b128 v[190:193], v58 offset:37888
	ds_read_b128 v[194:197], v58 offset:38912
	ds_read_b128 v[198:201], v58 offset:39936
	global_load_lds_dwordx4 v[202:203], off
	v_lshl_add_u64 v[202:203], s[38:39], 0, v[44:45]
	s_mov_b32 m0, s64
	s_nop 0
	global_load_lds_dwordx4 v[202:203], off
	s_waitcnt lgkmcnt(8)
	s_barrier
; #define PG8_STAGE(bufoff, gbase, voff) do { _Pragma("unroll") for (int _i = 0; _i < 2; ++_i) \
;         __builtin_amdgcn_global_load_lds((const unsigned*)((const char*)(gbase) + (voff)[_i]), (LAS unsigned*)(lds + (bufoff) + ldsw + _i * 8192), 16, 0, 0); } while (0)
; #define PG8_LDA(dst, b, h) do { _Pragma("unroll") for (int m = 0; m < 4; ++m) _Pragma("unroll") for (int k = 0; k < 2; ++k) dst[m][k] = *(const LAS bf16x8*)(lds + PG8_SA(b, h) + aoff + m * 2048 + k * 1024); } while (0)
; #define PG8_LDB(dst, b, h) do { _Pragma("unroll") for (int n = 0; n < 2; ++n) _Pragma("unroll") for (int k = 0; k < 2; ++k) dst[n][k] = *(const LAS bf16x8*)(lds + PG8_SB(b, h) + boff + n * 2048 + k * 1024); } while (0)
; #define PG8_MMA(ai, bj, At, Bt) do { __builtin_amdgcn_s_setprio(1); _Pragma("unroll") for (int m = 0; m < 4; ++m) _Pragma("unroll") for (int n = 0; n < 2; ++n) _Pragma("unroll") for (int k = 0; k < 2; ++k) \
;         acc[ai][bj][m][n] = __builtin_amdgcn_mfma_f32_16x16x32_bf16(Bt[n][k], At[m][k], acc[ai][bj][m][n], 0, 0, 0); __builtin_amdgcn_s_setprio(0); } while (0)
; #define PG8_WAIT_V(n) asm volatile("s_waitcnt vmcnt(" #n ")" ::: "memory")
; #define PG8_WAIT_L(n) asm volatile("s_waitcnt lgkmcnt(" #n ")" ::: "memory")
; #define PG8_BAR __builtin_amdgcn_s_barrier()
; #define PG8_SCHED __builtin_amdgcn_sched_barrier(0)
; template <class Epi>
; __device__ __forceinline__ void gemm_phase(LAS unsigned char* lds, const Gemm g, const StaticOrder& S, const Epi& E) {
;     ...
;             PG8_WAIT_L(8); PG8_BAR; PG8_WAIT_L(0); PG8_MMA(0, 0, At, B0); PG8_BAR; PG8_SCHED;
;             PG8_LDB(B1, 1, 1); PG8_STAGE(PG8_SB(1, 0), b3, voffB);
;             PG8_BAR; PG8_WAIT_L(0); PG8_MMA(0, 1, At, B1); PG8_BAR;
;             PG8_LDA(At, 1, 1); PG8_STAGE(PG8_SA(1, 0), a3, voffA);
;             PG8_BAR; PG8_WAIT_L(0); PG8_MMA(1, 0, At, B0); PG8_BAR; PG8_SCHED;
;             PG8_STAGE(PG8_SB(1, 1), b3 + hstepB, voffB);
;             PG8_WAIT_V(6); PG8_BAR; PG8_MMA(1, 1, At, B1); PG8_BAR;
	s_setprio 1
	s_waitcnt lgkmcnt(7)
	v_mfma_f32_16x16x32_bf16 v[68:71], v[4:7], v[140:143], v[68:71]
	v_mfma_f32_16x16x32_bf16 v[72:75], v[132:135], v[140:143], v[72:75]
	s_waitcnt lgkmcnt(5)
	v_mfma_f32_16x16x32_bf16 v[76:79], v[4:7], v[174:177], v[76:79]
	v_mfma_f32_16x16x32_bf16 v[80:83], v[132:135], v[174:177], v[80:83]
	s_waitcnt lgkmcnt(3)
	v_mfma_f32_16x16x32_bf16 v[84:87], v[4:7], v[182:185], v[84:87]
	v_mfma_f32_16x16x32_bf16 v[88:91], v[132:135], v[182:185], v[88:91]
	s_waitcnt lgkmcnt(1)
	v_mfma_f32_16x16x32_bf16 v[92:95], v[4:7], v[194:197], v[92:95]
	v_mfma_f32_16x16x32_bf16 v[96:99], v[132:135], v[194:197], v[96:99]
	v_mfma_f32_16x16x32_bf16 v[68:71], v[128:131], v[144:147], v[68:71]
	v_mfma_f32_16x16x32_bf16 v[72:75], v[136:139], v[144:147], v[72:75]
	v_mfma_f32_16x16x32_bf16 v[76:79], v[128:131], v[178:181], v[76:79]
	v_mfma_f32_16x16x32_bf16 v[80:83], v[136:139], v[178:181], v[80:83]
	v_mfma_f32_16x16x32_bf16 v[84:87], v[128:131], v[190:193], v[84:87]
	v_mfma_f32_16x16x32_bf16 v[88:91], v[136:139], v[190:193], v[88:91]
	s_waitcnt lgkmcnt(0)
	v_mfma_f32_16x16x32_bf16 v[92:95], v[128:131], v[198:201], v[92:95]
	v_mfma_f32_16x16x32_bf16 v[96:99], v[136:139], v[198:201], v[96:99]
	s_setprio 0
	s_barrier
	s_mov_b32 m0, s81
	v_lshl_add_u64 v[52:53], v[52:53], 0, s[6:7]
	ds_read_b128 v[202:205], v220
	ds_read_b128 v[206:209], v220 offset:1024
	ds_read_b128 v[210:213], v220 offset:2048
	ds_read_b128 v[214:217], v220 offset:3072
	global_load_lds_dwordx4 v[52:53], off
	v_lshl_add_u64 v[52:53], v[186:187], 0, s[6:7]
	s_mov_b32 m0, s79
	s_nop 0
	global_load_lds_dwordx4 v[52:53], off
	s_barrier
	s_setprio 1
	s_waitcnt lgkmcnt(1)
	v_mfma_f32_16x16x32_bf16 v[16:19], v[210:213], v[140:143], v[16:19]
	v_mfma_f32_16x16x32_bf16 v[116:119], v[202:205], v[140:143], v[116:119]
	s_waitcnt lgkmcnt(0)
	v_mfma_f32_16x16x32_bf16 v[140:143], v[214:217], v[144:147], v[16:19]
	v_mfma_f32_16x16x32_bf16 v[16:19], v[202:205], v[174:177], v[20:23]
	v_mfma_f32_16x16x32_bf16 v[116:119], v[206:209], v[144:147], v[116:119]
	v_mfma_f32_16x16x32_bf16 v[144:147], v[206:209], v[178:181], v[16:19]
	v_mfma_f32_16x16x32_bf16 v[16:19], v[210:213], v[174:177], v[24:27]
	v_mfma_f32_16x16x32_bf16 v[174:177], v[214:217], v[178:181], v[16:19]
	v_mfma_f32_16x16x32_bf16 v[16:19], v[202:205], v[182:185], v[28:31]
	v_mfma_f32_16x16x32_bf16 v[178:181], v[206:209], v[190:193], v[16:19]
	v_mfma_f32_16x16x32_bf16 v[16:19], v[210:213], v[182:185], v[32:35]
	v_mfma_f32_16x16x32_bf16 v[182:185], v[214:217], v[190:193], v[16:19]
	v_mfma_f32_16x16x32_bf16 v[16:19], v[202:205], v[194:197], v[36:39]
	v_mfma_f32_16x16x32_bf16 v[190:193], v[206:209], v[198:201], v[16:19]
	v_mfma_f32_16x16x32_bf16 v[16:19], v[210:213], v[194:197], v[60:63]
	v_mfma_f32_16x16x32_bf16 v[60:63], v[214:217], v[198:201], v[16:19]
	s_setprio 0
	s_mov_b32 m0, s65
	s_nop 4
	v_lshl_add_u64 v[16:17], v[188:189], 0, s[6:7]
	s_barrier
	ds_read_b128 v[24:27], v58 offset:49152
	ds_read_b128 v[28:31], v58 offset:50176
	ds_read_b128 v[194:197], v58 offset:51200
	ds_read_b128 v[198:201], v58 offset:52224
	ds_read_b128 v[218:221], v58 offset:53248
	ds_read_b128 v[222:225], v58 offset:54272
	ds_read_b128 v[226:229], v58 offset:55296
	ds_read_b128 v[230:233], v58 offset:56320
	global_load_lds_dwordx4 v[16:17], off
	v_lshl_add_u64 v[16:17], v[234:235], 0, s[6:7]
	s_mov_b32 m0, s66
	s_nop 0
	global_load_lds_dwordx4 v[16:17], off
	s_barrier
	s_setprio 1
	s_waitcnt lgkmcnt(7)
	v_mfma_f32_16x16x32_bf16 v[16:19], v[4:7], v[24:27], v[150:153]
	s_waitcnt lgkmcnt(6)
	v_mfma_f32_16x16x32_bf16 v[150:153], v[128:131], v[28:31], v[16:19]
	v_mfma_f32_16x16x32_bf16 v[16:19], v[132:135], v[24:27], v[154:157]
	v_mfma_f32_16x16x32_bf16 v[154:157], v[136:139], v[28:31], v[16:19]
	s_waitcnt lgkmcnt(5)
	v_mfma_f32_16x16x32_bf16 v[16:19], v[4:7], v[194:197], v[158:161]
	s_waitcnt lgkmcnt(4)
	v_mfma_f32_16x16x32_bf16 v[36:39], v[128:131], v[198:201], v[16:19]
	v_mfma_f32_16x16x32_bf16 v[16:19], v[132:135], v[194:197], v[162:165]
	v_mfma_f32_16x16x32_bf16 v[32:35], v[136:139], v[198:201], v[16:19]
	s_waitcnt lgkmcnt(3)
	v_mfma_f32_16x16x32_bf16 v[16:19], v[4:7], v[218:221], v[166:169]
	s_waitcnt lgkmcnt(1)
	v_mfma_f32_16x16x32_bf16 v[0:3], v[4:7], v[226:229], v[0:3]
	v_mfma_f32_16x16x32_bf16 v[20:23], v[128:131], v[222:225], v[16:19]
	v_mfma_f32_16x16x32_bf16 v[16:19], v[132:135], v[218:221], v[170:173]
	s_waitcnt lgkmcnt(0)
	v_mfma_f32_16x16x32_bf16 v[4:7], v[128:131], v[230:233], v[0:3]
	v_mfma_f32_16x16x32_bf16 v[0:3], v[132:135], v[226:229], v[124:127]
	v_mfma_f32_16x16x32_bf16 v[16:19], v[136:139], v[222:225], v[16:19]
	v_mfma_f32_16x16x32_bf16 v[0:3], v[136:139], v[230:233], v[0:3]
	s_setprio 0
	s_barrier
	s_add_u32 s38, s42, 0x10080
	s_addc_u32 s39, s43, 0
	s_mov_b32 m0, s41
	v_lshl_add_u64 v[52:53], s[38:39], 0, v[42:43]
	global_load_lds_dwordx4 v[52:53], off
	v_lshl_add_u64 v[52:53], s[38:39], 0, v[46:47]
	s_mov_b32 m0, s40
	s_nop 0
	global_load_lds_dwordx4 v[52:53], off
	s_waitcnt vmcnt(6)
	s_barrier
; __device__ __forceinline__ unsigned cvt_pk_bf16(float lo, float hi) { unsigned r; asm volatile("v_cvt_pk_bf16_f32 %0, %1, %2" : "=v"(r) : "v"(lo), "v"(hi)); return r; }
; #define PG8_MMA(ai, bj, At, Bt) do { __builtin_amdgcn_s_setprio(1); _Pragma("unroll") for (int m = 0; m < 4; ++m) _Pragma("unroll") for (int n = 0; n < 2; ++n) _Pragma("unroll") for (int k = 0; k < 2; ++k) \
;         acc[ai][bj][m][n] = __builtin_amdgcn_mfma_f32_16x16x32_bf16(Bt[n][k], At[m][k], acc[ai][bj][m][n], 0, 0, 0); __builtin_amdgcn_s_setprio(0); } while (0)
; #define PG8_WAIT_V(n) asm volatile("s_waitcnt vmcnt(" #n ")" ::: "memory")
; #define PG8_BAR __builtin_amdgcn_s_barrier()
; template <class Epi>
; __device__ __forceinline__ void gemm_phase(LAS unsigned char* lds, const Gemm g, const StaticOrder& S, const Epi& E) {
;     ...
;             PG8_WAIT_V(6); PG8_BAR; PG8_MMA(1, 1, At, B1); PG8_BAR;
;     __device__ __forceinline__ void operator()(const AccT& acc, const Unit& u, int wr, int wc, int fr, int fq) const {
;         const int row0 = u.pm * 256 + wr * 64 + fr, col0 = u.pn * 256 + wc * 32 + 8 * fq;
; #pragma unroll
;         for (int ai = 0; ai < 2; ++ai)
; #pragma unroll
;             for (int m = 0; m < 4; ++m) { u16* rowp = O + (size_t)(row0 + ai * 128 + m * 16) * ld + col0;
; #pragma unroll
;                 for (int bj = 0; bj < 2; ++bj) { const f32x4 v0 = acc[ai][bj][m][0], v1 = acc[ai][bj][m][1];
;                     u32x4 w; w.x = cvt_pk_bf16(v0[0], v0[1]); w.y = cvt_pk_bf16(v0[2], v0[3]); w.z = cvt_pk_bf16(v1[0], v1[1]); w.w = cvt_pk_bf16(v1[2], v1[3]);
;                     *(u32x4*)(rowp + bj * 128) = w; } }
	s_setprio 1
	v_mfma_f32_16x16x32_bf16 v[8:11], v[202:205], v[24:27], v[8:11]
	v_mfma_f32_16x16x32_bf16 v[124:127], v[206:209], v[28:31], v[8:11]
	v_mfma_f32_16x16x32_bf16 v[8:11], v[210:213], v[24:27], v[12:15]
	v_mfma_f32_16x16x32_bf16 v[128:131], v[214:217], v[28:31], v[8:11]
	v_mfma_f32_16x16x32_bf16 v[8:11], v[202:205], v[194:197], v[64:67]
	v_mfma_f32_16x16x32_bf16 v[64:67], v[206:209], v[198:201], v[8:11]
	v_mfma_f32_16x16x32_bf16 v[8:11], v[210:213], v[194:197], v[108:111]
	v_mfma_f32_16x16x32_bf16 v[108:111], v[214:217], v[198:201], v[8:11]
	v_mfma_f32_16x16x32_bf16 v[8:11], v[202:205], v[218:221], v[112:115]
	v_mfma_f32_16x16x32_bf16 v[28:31], v[206:209], v[222:225], v[8:11]
	v_mfma_f32_16x16x32_bf16 v[8:11], v[210:213], v[218:221], v[120:123]
	v_mfma_f32_16x16x32_bf16 v[24:27], v[214:217], v[222:225], v[8:11]
	v_mfma_f32_16x16x32_bf16 v[8:11], v[202:205], v[226:229], v[100:103]
	v_mfma_f32_16x16x32_bf16 v[12:15], v[206:209], v[230:233], v[8:11]
	v_mfma_f32_16x16x32_bf16 v[8:11], v[210:213], v[226:229], v[104:107]
	v_mfma_f32_16x16x32_bf16 v[8:11], v[214:217], v[230:233], v[8:11]
	s_setprio 0
	v_lshl_add_u32 v100, s36, 8, v54
	v_lshl_or_b32 v52, s76, 8, v56
	v_ashrrev_i32_e32 v101, 31, v100
	v_ashrrev_i32_e32 v53, 31, v52
	v_lshlrev_b64 v[102:103], 12, v[100:101]
	v_lshl_add_u64 v[102:103], s[0:1], 0, v[102:103]
	v_lshlrev_b64 v[104:105], 1, v[52:53]
	s_barrier
	v_lshl_add_u64 v[52:53], v[102:103], 0, v[104:105]
	v_cvt_pk_bf16_f32 v68, v68, v69
	v_cvt_pk_bf16_f32 v69, v70, v71
	v_cvt_pk_bf16_f32 v70, v72, v73
	v_cvt_pk_bf16_f32 v71, v74, v75
	global_store_dwordx4 v[52:53], v[68:71], off
	s_add_i32 s69, s69, s96
	s_mov_b32 s76, s24
	v_cvt_pk_bf16_f32 v68, v116, v117
	v_cvt_pk_bf16_f32 v69, v118, v119
	v_cvt_pk_bf16_f32 v70, v140, v141
	v_cvt_pk_bf16_f32 v71, v142, v143
	global_store_dwordx4 v[52:53], v[68:71], off offset:256
	s_mov_b32 s36, s26
	s_mov_b64 s[40:41], s[30:31]
	v_or_b32_e32 v68, 16, v100
	v_ashrrev_i32_e32 v69, 31, v68
	v_lshlrev_b64 v[68:69], 12, v[68:69]
	v_lshl_add_u64 v[68:69], s[0:1], 0, v[68:69]
	v_lshl_add_u64 v[72:73], v[68:69], 0, v[104:105]
	v_cvt_pk_bf16_f32 v68, v76, v77
	v_cvt_pk_bf16_f32 v69, v78, v79
	v_cvt_pk_bf16_f32 v70, v80, v81
	v_cvt_pk_bf16_f32 v71, v82, v83
	global_store_dwordx4 v[72:73], v[68:71], off
	s_mov_b64 s[38:39], s[28:29]
	s_nop 0
	v_cvt_pk_bf16_f32 v68, v144, v145
	v_cvt_pk_bf16_f32 v69, v146, v147
	v_cvt_pk_bf16_f32 v70, v174, v175
	v_cvt_pk_bf16_f32 v71, v176, v177
	global_store_dwordx4 v[72:73], v[68:71], off offset:256
	s_nop 1
	v_or_b32_e32 v68, 32, v100
	v_ashrrev_i32_e32 v69, 31, v68
	v_lshlrev_b64 v[68:69], 12, v[68:69]
	v_lshl_add_u64 v[68:69], s[0:1], 0, v[68:69]
	v_lshl_add_u64 v[72:73], v[68:69], 0, v[104:105]
	v_cvt_pk_bf16_f32 v68, v84, v85
	v_cvt_pk_bf16_f32 v69, v86, v87
	v_cvt_pk_bf16_f32 v70, v88, v89
	v_cvt_pk_bf16_f32 v71, v90, v91
	global_store_dwordx4 v[72:73], v[68:71], off
	s_nop 1
	v_cvt_pk_bf16_f32 v68, v178, v179
	v_cvt_pk_bf16_f32 v69, v180, v181
	v_cvt_pk_bf16_f32 v70, v182, v183
	v_cvt_pk_bf16_f32 v71, v184, v185
	global_store_dwordx4 v[72:73], v[68:71], off offset:256
	s_nop 1
	v_or_b32_e32 v68, 48, v100
	v_ashrrev_i32_e32 v69, 31, v68
	v_lshlrev_b64 v[68:69], 12, v[68:69]
	v_lshl_add_u64 v[68:69], s[0:1], 0, v[68:69]
	v_lshl_add_u64 v[72:73], v[68:69], 0, v[104:105]
	v_cvt_pk_bf16_f32 v68, v92, v93
	v_cvt_pk_bf16_f32 v69, v94, v95
	v_cvt_pk_bf16_f32 v70, v96, v97
	v_cvt_pk_bf16_f32 v71, v98, v99
	global_store_dwordx4 v[72:73], v[68:71], off
	s_nop 1
	v_cvt_pk_bf16_f32 v68, v190, v191
	v_cvt_pk_bf16_f32 v69, v192, v193
	v_cvt_pk_bf16_f32 v70, v60, v61
	v_cvt_pk_bf16_f32 v71, v62, v63
	global_store_dwordx4 v[72:73], v[68:71], off offset:256
	v_cvt_pk_bf16_f32 v60, v150, v151
	v_cvt_pk_bf16_f32 v61, v152, v153
	v_cvt_pk_bf16_f32 v62, v154, v155
	v_cvt_pk_bf16_f32 v63, v156, v157
	s_nop 1
	v_add_co_u32_e32 v70, vcc, s72, v52
	v_lshl_add_u64 v[68:69], v[52:53], 0, s[14:15]
	s_nop 0
	v_addc_co_u32_e32 v71, vcc, 0, v53, vcc
	global_store_dwordx4 v[70:71], v[60:63], off
	s_nop 1
	v_cvt_pk_bf16_f32 v60, v124, v125
	v_cvt_pk_bf16_f32 v61, v126, v127
	v_cvt_pk_bf16_f32 v62, v128, v129
	v_cvt_pk_bf16_f32 v63, v130, v131
	global_store_dwordx4 v[68:69], v[60:63], off offset:256
	v_cvt_pk_bf16_f32 v36, v36, v37
	v_cvt_pk_bf16_f32 v37, v38, v39
	v_cvt_pk_bf16_f32 v38, v32, v33
	v_add_co_u32_e32 v32, vcc, s73, v52
	s_nop 0
	v_lshl_add_u64 v[60:61], v[52:53], 0, s[16:17]
	v_addc_co_u32_e32 v33, vcc, 0, v53, vcc
	v_cvt_pk_bf16_f32 v39, v34, v35
	global_store_dwordx4 v[32:33], v[36:39], off
	v_cvt_pk_bf16_f32 v32, v64, v65
	v_cvt_pk_bf16_f32 v33, v66, v67
	v_cvt_pk_bf16_f32 v34, v108, v109
	v_cvt_pk_bf16_f32 v35, v110, v111
	global_store_dwordx4 v[60:61], v[32:35], off offset:256
	v_cvt_pk_bf16_f32 v20, v20, v21
	v_cvt_pk_bf16_f32 v21, v22, v23
	v_cvt_pk_bf16_f32 v22, v16, v17
	v_add_co_u32_e32 v16, vcc, s74, v52
	s_nop 0
	v_lshl_add_u64 v[32:33], v[52:53], 0, s[18:19]
	v_addc_co_u32_e32 v17, vcc, 0, v53, vcc
	v_cvt_pk_bf16_f32 v23, v18, v19
	global_store_dwordx4 v[16:17], v[20:23], off
	v_cvt_pk_bf16_f32 v16, v28, v29
	v_cvt_pk_bf16_f32 v17, v30, v31
	v_cvt_pk_bf16_f32 v18, v24, v25
	v_cvt_pk_bf16_f32 v19, v26, v27
	global_store_dwordx4 v[32:33], v[16:19], off offset:256
	v_cvt_pk_bf16_f32 v4, v4, v5
	v_cvt_pk_bf16_f32 v5, v6, v7
	v_cvt_pk_bf16_f32 v6, v0, v1
	v_add_co_u32_e32 v0, vcc, s75, v52
	s_nop 0
	v_lshl_add_u64 v[16:17], v[52:53], 0, s[20:21]
	v_addc_co_u32_e32 v1, vcc, 0, v53, vcc
	s_andn2_b64 vcc, exec, s[4:5]
	v_cvt_pk_bf16_f32 v7, v2, v3
	global_store_dwordx4 v[0:1], v[4:7], off
	v_cvt_pk_bf16_f32 v0, v12, v13
	v_cvt_pk_bf16_f32 v1, v14, v15
	v_cvt_pk_bf16_f32 v2, v8, v9
	v_cvt_pk_bf16_f32 v3, v10, v11
	global_store_dwordx4 v[16:17], v[0:3], off offset:256
	s_cbranch_vccz .LBB0_1109

; #define PG8_STAGE(bufoff, gbase, voff) do { _Pragma("unroll") for (int _i = 0; _i < 2; ++_i) \
;         __builtin_amdgcn_global_load_lds((const unsigned*)((const char*)(gbase) + (voff)[_i]), (LAS unsigned*)(lds + (bufoff) + ldsw + _i * 8192), 16, 0, 0); } while (0)
; #define PG8_LDA(dst, b, h) do { _Pragma("unroll") for (int m = 0; m < 4; ++m) _Pragma("unroll") for (int k = 0; k < 2; ++k) dst[m][k] = *(const LAS bf16x8*)(lds + PG8_SA(b, h) + aoff + m * 2048 + k * 1024); } while (0)
; #define PG8_LDB(dst, b, h) do { _Pragma("unroll") for (int n = 0; n < 2; ++n) _Pragma("unroll") for (int k = 0; k < 2; ++k) dst[n][k] = *(const LAS bf16x8*)(lds + PG8_SB(b, h) + boff + n * 2048 + k * 1024); } while (0)
; #define PG8_MMA(ai, bj, At, Bt) do { __builtin_amdgcn_s_setprio(1); _Pragma("unroll") for (int m = 0; m < 4; ++m) _Pragma("unroll") for (int n = 0; n < 2; ++n) _Pragma("unroll") for (int k = 0; k < 2; ++k) \
;         acc[ai][bj][m][n] = __builtin_amdgcn_mfma_f32_16x16x32_bf16(Bt[n][k], At[m][k], acc[ai][bj][m][n], 0, 0, 0); __builtin_amdgcn_s_setprio(0); } while (0)
; #define PG8_WAIT_L(n) asm volatile("s_waitcnt lgkmcnt(" #n ")" ::: "memory")
; #define PG8_BAR __builtin_amdgcn_s_barrier()
; #define PG8_SCHED __builtin_amdgcn_sched_barrier(0)
; template <class Epi>
; __device__ __forceinline__ void gemm_phase(LAS unsigned char* lds, const Gemm g, const StaticOrder& S, const Epi& E) {
;     ...
;             PG8_LDB(B0, 0, 0); PG8_SCHED; PG8_LDA(At, 0, 0); PG8_STAGE(PG8_SA(1, 1), a1 + hstepA, voffA);
;             PG8_WAIT_L(8); PG8_BAR; PG8_WAIT_L(0); PG8_MMA(0, 0, At, B0); PG8_BAR; PG8_SCHED;
;             PG8_LDB(B1, 0, 1); PG8_STAGE(PG8_SB(0, 0), b2, voffB);
;             PG8_BAR; PG8_WAIT_L(0); PG8_MMA(0, 1, At, B1); PG8_BAR;
;             PG8_LDA(At, 0, 1); PG8_STAGE(PG8_SA(0, 0), a2, voffA);
;             PG8_BAR; PG8_WAIT_L(0); PG8_MMA(1, 0, At, B0); PG8_BAR; PG8_SCHED;
.LBB0_1240:
	ds_read_b128 v[140:143], v152
	ds_read_b128 v[144:147], v152 offset:1024
	ds_read_b128 v[156:159], v152 offset:2048
	ds_read_b128 v[160:163], v152 offset:3072
	s_add_u32 s30, s28, 0xfff80080
	s_addc_u32 s31, s29, -1
	s_cmp_eq_u32 s67, 28
	s_cselect_b32 s37, s21, s31
	s_cselect_b32 s36, s63, s30
	s_cselect_b32 s31, s19, s66
	s_cselect_b32 s30, s64, s65
	v_lshl_add_u64 v[188:189], s[28:29], 0, v[132:133]
	s_add_i32 m0, s27, 0xc000
	ds_read_b128 v[164:167], v153
	ds_read_b128 v[168:171], v153 offset:1024
	ds_read_b128 v[172:175], v153 offset:2048
	ds_read_b128 v[176:179], v153 offset:3072
	ds_read_b128 v[180:183], v153 offset:4096
	ds_read_b128 v[184:187], v153 offset:5120
	ds_read_b128 v[190:193], v153 offset:6144
	ds_read_b128 v[194:197], v153 offset:7168
	global_load_lds_dwordx4 v[188:189], off
	v_lshl_add_u64 v[188:189], s[28:29], 0, v[134:135]
	s_add_i32 m0, s27, 0xe000
	s_nop 0
	global_load_lds_dwordx4 v[188:189], off
	s_waitcnt lgkmcnt(8)
	s_barrier
	s_setprio 1
	s_waitcnt lgkmcnt(7)
	v_mfma_f32_16x16x32_bf16 v[124:127], v[140:143], v[164:167], v[124:127]
	v_mfma_f32_16x16x32_bf16 v[120:123], v[156:159], v[164:167], v[120:123]
	s_waitcnt lgkmcnt(5)
	v_mfma_f32_16x16x32_bf16 v[108:111], v[140:143], v[172:175], v[108:111]
	v_mfma_f32_16x16x32_bf16 v[104:107], v[156:159], v[172:175], v[104:107]
	s_waitcnt lgkmcnt(3)
	v_mfma_f32_16x16x32_bf16 v[92:95], v[140:143], v[180:183], v[92:95]
	v_mfma_f32_16x16x32_bf16 v[88:91], v[156:159], v[180:183], v[88:91]
	s_waitcnt lgkmcnt(1)
	v_mfma_f32_16x16x32_bf16 v[76:79], v[140:143], v[190:193], v[76:79]
	v_mfma_f32_16x16x32_bf16 v[72:75], v[156:159], v[190:193], v[72:75]
	v_mfma_f32_16x16x32_bf16 v[124:127], v[144:147], v[168:171], v[124:127]
	v_mfma_f32_16x16x32_bf16 v[120:123], v[160:163], v[168:171], v[120:123]
	v_mfma_f32_16x16x32_bf16 v[108:111], v[144:147], v[176:179], v[108:111]
	v_mfma_f32_16x16x32_bf16 v[104:107], v[160:163], v[176:179], v[104:107]
	v_mfma_f32_16x16x32_bf16 v[92:95], v[144:147], v[184:187], v[92:95]
	v_mfma_f32_16x16x32_bf16 v[88:91], v[160:163], v[184:187], v[88:91]
	s_waitcnt lgkmcnt(0)
	v_mfma_f32_16x16x32_bf16 v[76:79], v[144:147], v[194:197], v[76:79]
	v_mfma_f32_16x16x32_bf16 v[72:75], v[160:163], v[194:197], v[72:75]
	s_setprio 0
	s_barrier
	s_add_i32 s68, s60, s43
	v_lshl_add_u64 v[188:189], s[30:31], 0, v[128:129]
	s_mov_b32 m0, s68
	ds_read_b128 v[198:201], v154
	ds_read_b128 v[202:205], v154 offset:1024
	ds_read_b128 v[206:209], v154 offset:2048
	ds_read_b128 v[210:213], v154 offset:3072
	global_load_lds_dwordx4 v[188:189], off
	v_lshl_add_u64 v[214:215], s[30:31], 0, v[130:131]
	s_add_i32 m0, s68, 0x2000
	s_nop 0
	global_load_lds_dwordx4 v[214:215], off
	s_barrier
	s_setprio 1
	s_waitcnt lgkmcnt(3)
	v_mfma_f32_16x16x32_bf16 v[116:119], v[198:201], v[164:167], v[116:119]
	s_waitcnt lgkmcnt(1)
	v_mfma_f32_16x16x32_bf16 v[112:115], v[206:209], v[164:167], v[112:115]
	v_mfma_f32_16x16x32_bf16 v[100:103], v[198:201], v[172:175], v[100:103]
	v_mfma_f32_16x16x32_bf16 v[96:99], v[206:209], v[172:175], v[96:99]
	v_mfma_f32_16x16x32_bf16 v[84:87], v[198:201], v[180:183], v[84:87]
	v_mfma_f32_16x16x32_bf16 v[80:83], v[206:209], v[180:183], v[80:83]
	v_mfma_f32_16x16x32_bf16 v[68:71], v[198:201], v[190:193], v[68:71]
	v_mfma_f32_16x16x32_bf16 v[64:67], v[206:209], v[190:193], v[64:67]
	v_mfma_f32_16x16x32_bf16 v[116:119], v[202:205], v[168:171], v[116:119]
	s_waitcnt lgkmcnt(0)
	v_mfma_f32_16x16x32_bf16 v[112:115], v[210:213], v[168:171], v[112:115]
	v_mfma_f32_16x16x32_bf16 v[100:103], v[202:205], v[176:179], v[100:103]
	v_mfma_f32_16x16x32_bf16 v[96:99], v[210:213], v[176:179], v[96:99]
	v_mfma_f32_16x16x32_bf16 v[84:87], v[202:205], v[184:187], v[84:87]
	v_mfma_f32_16x16x32_bf16 v[80:83], v[210:213], v[184:187], v[80:83]
	v_mfma_f32_16x16x32_bf16 v[68:71], v[202:205], v[194:197], v[68:71]
	v_mfma_f32_16x16x32_bf16 v[64:67], v[210:213], v[194:197], v[64:67]
	s_setprio 0
	s_mov_b32 m0, s27
	v_lshl_add_u64 v[216:217], s[36:37], 0, v[128:129]
	s_barrier
	ds_read_b128 v[164:167], v153 offset:16384
	ds_read_b128 v[168:171], v153 offset:17408
	ds_read_b128 v[172:175], v153 offset:18432
	ds_read_b128 v[176:179], v153 offset:19456
	ds_read_b128 v[180:183], v153 offset:20480
	ds_read_b128 v[184:187], v153 offset:21504
	ds_read_b128 v[190:193], v153 offset:22528
	ds_read_b128 v[194:197], v153 offset:23552
	global_load_lds_dwordx4 v[216:217], off
	v_lshl_add_u64 v[218:219], s[36:37], 0, v[130:131]
	s_mov_b32 m0, s44
	s_nop 0
	global_load_lds_dwordx4 v[218:219], off
	s_barrier
	s_setprio 1
	s_waitcnt lgkmcnt(7)
	v_mfma_f32_16x16x32_bf16 v[60:63], v[140:143], v[164:167], v[60:63]
	v_mfma_f32_16x16x32_bf16 v[56:59], v[156:159], v[164:167], v[56:59]
	s_waitcnt lgkmcnt(5)
	v_mfma_f32_16x16x32_bf16 v[44:47], v[140:143], v[172:175], v[44:47]
	v_mfma_f32_16x16x32_bf16 v[40:43], v[156:159], v[172:175], v[40:43]
	s_waitcnt lgkmcnt(3)
	v_mfma_f32_16x16x32_bf16 v[28:31], v[140:143], v[180:183], v[28:31]
	v_mfma_f32_16x16x32_bf16 v[24:27], v[156:159], v[180:183], v[24:27]
	s_waitcnt lgkmcnt(1)
	v_mfma_f32_16x16x32_bf16 v[12:15], v[140:143], v[190:193], v[12:15]
	v_mfma_f32_16x16x32_bf16 v[8:11], v[156:159], v[190:193], v[8:11]
	v_mfma_f32_16x16x32_bf16 v[60:63], v[144:147], v[168:171], v[60:63]
	v_mfma_f32_16x16x32_bf16 v[56:59], v[160:163], v[168:171], v[56:59]
	v_mfma_f32_16x16x32_bf16 v[44:47], v[144:147], v[176:179], v[44:47]
	v_mfma_f32_16x16x32_bf16 v[40:43], v[160:163], v[176:179], v[40:43]
	v_mfma_f32_16x16x32_bf16 v[28:31], v[144:147], v[184:187], v[28:31]
	v_mfma_f32_16x16x32_bf16 v[24:27], v[160:163], v[184:187], v[24:27]
	s_waitcnt lgkmcnt(0)
	v_mfma_f32_16x16x32_bf16 v[12:15], v[144:147], v[194:197], v[12:15]
	v_mfma_f32_16x16x32_bf16 v[8:11], v[160:163], v[194:197], v[8:11]
	s_setprio 0
	s_barrier
; #define PG8_STAGE(bufoff, gbase, voff) do { _Pragma("unroll") for (int _i = 0; _i < 2; ++_i) \
;         __builtin_amdgcn_global_load_lds((const unsigned*)((const char*)(gbase) + (voff)[_i]), (LAS unsigned*)(lds + (bufoff) + ldsw + _i * 8192), 16, 0, 0); } while (0)
; #define PG8_LDA(dst, b, h) do { _Pragma("unroll") for (int m = 0; m < 4; ++m) _Pragma("unroll") for (int k = 0; k < 2; ++k) dst[m][k] = *(const LAS bf16x8*)(lds + PG8_SA(b, h) + aoff + m * 2048 + k * 1024); } while (0)
; #define PG8_LDB(dst, b, h) do { _Pragma("unroll") for (int n = 0; n < 2; ++n) _Pragma("unroll") for (int k = 0; k < 2; ++k) dst[n][k] = *(const LAS bf16x8*)(lds + PG8_SB(b, h) + boff + n * 2048 + k * 1024); } while (0)
; #define PG8_MMA(ai, bj, At, Bt) do { __builtin_amdgcn_s_setprio(1); _Pragma("unroll") for (int m = 0; m < 4; ++m) _Pragma("unroll") for (int n = 0; n < 2; ++n) _Pragma("unroll") for (int k = 0; k < 2; ++k) \
;         acc[ai][bj][m][n] = __builtin_amdgcn_mfma_f32_16x16x32_bf16(Bt[n][k], At[m][k], acc[ai][bj][m][n], 0, 0, 0); __builtin_amdgcn_s_setprio(0); } while (0)
; #define PG8_WAIT_V(n) asm volatile("s_waitcnt vmcnt(" #n ")" ::: "memory")
; #define PG8_WAIT_L(n) asm volatile("s_waitcnt lgkmcnt(" #n ")" ::: "memory")
; #define PG8_BAR __builtin_amdgcn_s_barrier()
; #define PG8_SCHED __builtin_amdgcn_sched_barrier(0)
; template <class Epi>
; __device__ __forceinline__ void gemm_phase(LAS unsigned char* lds, const Gemm g, const StaticOrder& S, const Epi& E) {
;     ...
;             PG8_STAGE(PG8_SB(0, 1), b2 + hstepB, voffB);
;             PG8_WAIT_V(6); PG8_BAR; PG8_MMA(1, 1, At, B1); PG8_BAR;
;             PG8_LDB(B0, 1, 0); PG8_SCHED; PG8_LDA(At, 1, 0); PG8_STAGE(PG8_SA(0, 1), a2 + hstepA, voffA);
;             PG8_WAIT_L(8); PG8_BAR; PG8_WAIT_L(0); PG8_MMA(0, 0, At, B0); PG8_BAR; PG8_SCHED;
;             PG8_LDB(B1, 1, 1); PG8_STAGE(PG8_SB(1, 0), b3, voffB);
;             PG8_BAR; PG8_WAIT_L(0); PG8_MMA(0, 1, At, B1); PG8_BAR;
	s_add_u32 s68, s30, 0x80000
	s_addc_u32 s69, s31, 0
	s_add_i32 s70, s61, s43
	v_lshl_add_u64 v[140:141], s[68:69], 0, v[128:129]
	s_mov_b32 m0, s70
	s_nop 0
	global_load_lds_dwordx4 v[140:141], off
	v_lshl_add_u64 v[140:141], s[68:69], 0, v[130:131]
	s_add_i32 m0, s70, 0x2000
	s_nop 0
	global_load_lds_dwordx4 v[140:141], off
	s_waitcnt vmcnt(6)
	s_barrier
	s_setprio 1
	v_mfma_f32_16x16x32_bf16 v[52:55], v[198:201], v[164:167], v[52:55]
	v_mfma_f32_16x16x32_bf16 v[48:51], v[206:209], v[164:167], v[48:51]
	v_mfma_f32_16x16x32_bf16 v[36:39], v[198:201], v[172:175], v[36:39]
	v_mfma_f32_16x16x32_bf16 v[32:35], v[206:209], v[172:175], v[32:35]
	v_mfma_f32_16x16x32_bf16 v[20:23], v[198:201], v[180:183], v[20:23]
	v_mfma_f32_16x16x32_bf16 v[16:19], v[206:209], v[180:183], v[16:19]
	v_mfma_f32_16x16x32_bf16 v[4:7], v[198:201], v[190:193], v[4:7]
	v_mfma_f32_16x16x32_bf16 v[0:3], v[206:209], v[190:193], v[0:3]
	v_mfma_f32_16x16x32_bf16 v[52:55], v[202:205], v[168:171], v[52:55]
	v_mfma_f32_16x16x32_bf16 v[48:51], v[210:213], v[168:171], v[48:51]
	v_mfma_f32_16x16x32_bf16 v[36:39], v[202:205], v[176:179], v[36:39]
	v_mfma_f32_16x16x32_bf16 v[32:35], v[210:213], v[176:179], v[32:35]
	v_mfma_f32_16x16x32_bf16 v[20:23], v[202:205], v[184:187], v[20:23]
	v_mfma_f32_16x16x32_bf16 v[16:19], v[210:213], v[184:187], v[16:19]
	v_mfma_f32_16x16x32_bf16 v[4:7], v[202:205], v[194:197], v[4:7]
	v_mfma_f32_16x16x32_bf16 v[0:3], v[210:213], v[194:197], v[0:3]
	s_setprio 0
	s_add_i32 s68, 0, 0x18000
	v_add_u32_e32 v155, s68, v150
	s_barrier
	ds_read_b128 v[140:143], v155
	ds_read_b128 v[144:147], v155 offset:1024
	ds_read_b128 v[156:159], v155 offset:2048
	ds_read_b128 v[160:163], v155 offset:3072
	s_add_u32 s36, s36, 0x80000
	s_addc_u32 s37, s37, 0
	s_mov_b32 m0, s45
	v_lshl_add_u64 v[198:199], s[36:37], 0, v[128:129]
	ds_read_b128 v[164:167], v153 offset:32768
	ds_read_b128 v[168:171], v153 offset:33792
	ds_read_b128 v[172:175], v153 offset:34816
	ds_read_b128 v[176:179], v153 offset:35840
	ds_read_b128 v[180:183], v153 offset:36864
	ds_read_b128 v[184:187], v153 offset:37888
	ds_read_b128 v[190:193], v153 offset:38912
	ds_read_b128 v[194:197], v153 offset:39936
	global_load_lds_dwordx4 v[198:199], off
	v_lshl_add_u64 v[198:199], s[36:37], 0, v[130:131]
	s_mov_b32 m0, s46
	s_nop 0
	global_load_lds_dwordx4 v[198:199], off
	s_waitcnt lgkmcnt(8)
	s_barrier
	s_setprio 1
	s_waitcnt lgkmcnt(7)
	v_mfma_f32_16x16x32_bf16 v[124:127], v[140:143], v[164:167], v[124:127]
	v_mfma_f32_16x16x32_bf16 v[120:123], v[156:159], v[164:167], v[120:123]
	s_waitcnt lgkmcnt(5)
	v_mfma_f32_16x16x32_bf16 v[108:111], v[140:143], v[172:175], v[108:111]
	v_mfma_f32_16x16x32_bf16 v[104:107], v[156:159], v[172:175], v[104:107]
	s_waitcnt lgkmcnt(3)
	v_mfma_f32_16x16x32_bf16 v[92:95], v[140:143], v[180:183], v[92:95]
	v_mfma_f32_16x16x32_bf16 v[88:91], v[156:159], v[180:183], v[88:91]
	s_waitcnt lgkmcnt(1)
	v_mfma_f32_16x16x32_bf16 v[76:79], v[140:143], v[190:193], v[76:79]
	v_mfma_f32_16x16x32_bf16 v[72:75], v[156:159], v[190:193], v[72:75]
	v_mfma_f32_16x16x32_bf16 v[124:127], v[144:147], v[168:171], v[124:127]
	v_mfma_f32_16x16x32_bf16 v[120:123], v[160:163], v[168:171], v[120:123]
	v_mfma_f32_16x16x32_bf16 v[108:111], v[144:147], v[176:179], v[108:111]
	v_mfma_f32_16x16x32_bf16 v[104:107], v[160:163], v[176:179], v[104:107]
	v_mfma_f32_16x16x32_bf16 v[92:95], v[144:147], v[184:187], v[92:95]
	v_mfma_f32_16x16x32_bf16 v[88:91], v[160:163], v[184:187], v[88:91]
	s_waitcnt lgkmcnt(0)
	v_mfma_f32_16x16x32_bf16 v[76:79], v[144:147], v[194:197], v[76:79]
	v_mfma_f32_16x16x32_bf16 v[72:75], v[160:163], v[194:197], v[72:75]
	s_setprio 0
	s_barrier
	s_add_i32 s36, 0, 0x1c000
	s_add_i32 s37, s68, s43
	v_add_u32_e32 v155, s36, v150
	v_lshl_add_u64 v[188:189], v[188:189], 0, s[6:7]
	s_mov_b32 m0, s37
	ds_read_b128 v[198:201], v155
	ds_read_b128 v[202:205], v155 offset:1024
	ds_read_b128 v[206:209], v155 offset:2048
	ds_read_b128 v[210:213], v155 offset:3072
	global_load_lds_dwordx4 v[188:189], off
	v_lshl_add_u64 v[188:189], v[214:215], 0, s[6:7]
	s_add_i32 m0, s37, 0x2000
	s_nop 0
	global_load_lds_dwordx4 v[188:189], off
	s_barrier
	s_setprio 1
	s_waitcnt lgkmcnt(3)
	v_mfma_f32_16x16x32_bf16 v[116:119], v[198:201], v[164:167], v[116:119]
	s_waitcnt lgkmcnt(1)
	v_mfma_f32_16x16x32_bf16 v[112:115], v[206:209], v[164:167], v[112:115]
	v_mfma_f32_16x16x32_bf16 v[100:103], v[198:201], v[172:175], v[100:103]
	v_mfma_f32_16x16x32_bf16 v[96:99], v[206:209], v[172:175], v[96:99]
	v_mfma_f32_16x16x32_bf16 v[84:87], v[198:201], v[180:183], v[84:87]
	v_mfma_f32_16x16x32_bf16 v[80:83], v[206:209], v[180:183], v[80:83]
	v_mfma_f32_16x16x32_bf16 v[68:71], v[198:201], v[190:193], v[68:71]
	v_mfma_f32_16x16x32_bf16 v[64:67], v[206:209], v[190:193], v[64:67]
	v_mfma_f32_16x16x32_bf16 v[116:119], v[202:205], v[168:171], v[116:119]
	s_waitcnt lgkmcnt(0)
	v_mfma_f32_16x16x32_bf16 v[112:115], v[210:213], v[168:171], v[112:115]
	v_mfma_f32_16x16x32_bf16 v[100:103], v[202:205], v[176:179], v[100:103]
	v_mfma_f32_16x16x32_bf16 v[96:99], v[210:213], v[176:179], v[96:99]
	v_mfma_f32_16x16x32_bf16 v[84:87], v[202:205], v[184:187], v[84:87]
	v_mfma_f32_16x16x32_bf16 v[80:83], v[210:213], v[184:187], v[80:83]
	v_mfma_f32_16x16x32_bf16 v[68:71], v[202:205], v[194:197], v[68:71]
	v_mfma_f32_16x16x32_bf16 v[64:67], v[210:213], v[194:197], v[64:67]
	s_setprio 0
	s_mov_b32 m0, s48
	v_lshl_add_u64 v[188:189], v[216:217], 0, s[6:7]
	s_barrier
; __device__ __forceinline__ float bflo(unsigned w) { return __uint_as_float(w << 16); }
; __device__ __forceinline__ float bfhi(unsigned w) { return __uint_as_float(w & 0xffff0000u); }
; __device__ __forceinline__ float sigmoidf_(float x) { return __builtin_amdgcn_rcpf(1.0f + __expf(-x)); }
; #define PG8_STAGE(bufoff, gbase, voff) do { _Pragma("unroll") for (int _i = 0; _i < 2; ++_i) \
;         __builtin_amdgcn_global_load_lds((const unsigned*)((const char*)(gbase) + (voff)[_i]), (LAS unsigned*)(lds + (bufoff) + ldsw + _i * 8192), 16, 0, 0); } while (0)
; #define PG8_LDA(dst, b, h) do { _Pragma("unroll") for (int m = 0; m < 4; ++m) _Pragma("unroll") for (int k = 0; k < 2; ++k) dst[m][k] = *(const LAS bf16x8*)(lds + PG8_SA(b, h) + aoff + m * 2048 + k * 1024); } while (0)
; #define PG8_WAIT_V(n) asm volatile("s_waitcnt vmcnt(" #n ")" ::: "memory")
; #define PG8_WAIT_L(n) asm volatile("s_waitcnt lgkmcnt(" #n ")" ::: "memory")
; template <class Epi>
; __device__ __forceinline__ void gemm_phase(LAS unsigned char* lds, const Gemm g, const StaticOrder& S, const Epi& E) {
;     ...
;             PG8_LDA(At, 1, 1); PG8_STAGE(PG8_SA(1, 0), a3, voffA);
;             PG8_BAR; PG8_WAIT_L(0); PG8_MMA(1, 0, At, B0); PG8_BAR; PG8_SCHED;
;             PG8_STAGE(PG8_SB(1, 1), b3 + hstepB, voffB);
;             PG8_WAIT_V(6); PG8_BAR; PG8_MMA(1, 1, At, B1); PG8_BAR;
;         }
;     __device__ __forceinline__ void operator()(const AccT& acc, const Unit& u, int wr, int wc, int fr, int fq) const {
;         const int row0 = u.pm * 256 + wr * 64 + fr, col0 = u.pn * 256 + wc * 32 + 4 * fq;
; #pragma unroll
;         for (int ai = 0; ai < 2; ++ai)
; #pragma unroll
;             for (int m = 0; m < 4; ++m) { const size_t ro = (size_t)(row0 + ai * 128 + m * 16) * DM + col0;
; #pragma unroll
;                 for (int bj = 0; bj < 2; ++bj)
; #pragma unroll
;                     for (int n = 0; n < 2; ++n) { const size_t o = ro + bj * 128 + n * 16; const f32x4 h = *(const f32x4*)(H + o); const u32x2 pw = *(const u32x2*)(PP + o);
;                         const f32x4 a = acc[ai][bj][m][n]; f32x4 r;
;                         r[0] = h[0] + bflo(pw.x) * sigmoidf_(a[0]); r[1] = h[1] + bfhi(pw.x) * sigmoidf_(a[1]); r[2] = h[2] + bflo(pw.y) * sigmoidf_(a[2]); r[3] = h[3] + bfhi(pw.y) * sigmoidf_(a[3]);
;                         *(f32x4*)(H + o) = r; asm volatile("" ::: "memory"); } }
	ds_read_b128 v[164:167], v153 offset:49152
	ds_read_b128 v[168:171], v153 offset:50176
	ds_read_b128 v[172:175], v153 offset:51200
	ds_read_b128 v[176:179], v153 offset:52224
	ds_read_b128 v[180:183], v153 offset:53248
	ds_read_b128 v[184:187], v153 offset:54272
	ds_read_b128 v[190:193], v153 offset:55296
	ds_read_b128 v[194:197], v153 offset:56320
	global_load_lds_dwordx4 v[188:189], off
	v_lshl_add_u64 v[188:189], v[218:219], 0, s[6:7]
	s_mov_b32 m0, s49
	s_nop 0
	global_load_lds_dwordx4 v[188:189], off
	s_barrier
	s_setprio 1
	s_waitcnt lgkmcnt(7)
	v_mfma_f32_16x16x32_bf16 v[60:63], v[140:143], v[164:167], v[60:63]
	v_mfma_f32_16x16x32_bf16 v[56:59], v[156:159], v[164:167], v[56:59]
	s_waitcnt lgkmcnt(5)
	v_mfma_f32_16x16x32_bf16 v[44:47], v[140:143], v[172:175], v[44:47]
	v_mfma_f32_16x16x32_bf16 v[40:43], v[156:159], v[172:175], v[40:43]
	s_waitcnt lgkmcnt(3)
	v_mfma_f32_16x16x32_bf16 v[28:31], v[140:143], v[180:183], v[28:31]
	v_mfma_f32_16x16x32_bf16 v[24:27], v[156:159], v[180:183], v[24:27]
	s_waitcnt lgkmcnt(1)
	v_mfma_f32_16x16x32_bf16 v[12:15], v[140:143], v[190:193], v[12:15]
	v_mfma_f32_16x16x32_bf16 v[8:11], v[156:159], v[190:193], v[8:11]
	v_mfma_f32_16x16x32_bf16 v[60:63], v[144:147], v[168:171], v[60:63]
	v_mfma_f32_16x16x32_bf16 v[56:59], v[160:163], v[168:171], v[56:59]
	v_mfma_f32_16x16x32_bf16 v[44:47], v[144:147], v[176:179], v[44:47]
	v_mfma_f32_16x16x32_bf16 v[40:43], v[160:163], v[176:179], v[40:43]
	v_mfma_f32_16x16x32_bf16 v[28:31], v[144:147], v[184:187], v[28:31]
	v_mfma_f32_16x16x32_bf16 v[24:27], v[160:163], v[184:187], v[24:27]
	s_waitcnt lgkmcnt(0)
	v_mfma_f32_16x16x32_bf16 v[12:15], v[144:147], v[194:197], v[12:15]
	v_mfma_f32_16x16x32_bf16 v[8:11], v[160:163], v[194:197], v[8:11]
	s_setprio 0
	s_barrier
	s_add_u32 s30, s30, 0x80080
	s_addc_u32 s31, s31, 0
	s_add_i32 s36, s36, s43
	v_lshl_add_u64 v[140:141], s[30:31], 0, v[128:129]
	s_mov_b32 m0, s36
	s_nop 0
	global_load_lds_dwordx4 v[140:141], off
	v_lshl_add_u64 v[140:141], s[30:31], 0, v[130:131]
	s_add_i32 m0, s36, 0x2000
	s_nop 0
	global_load_lds_dwordx4 v[140:141], off
	s_waitcnt vmcnt(6)
	s_barrier
	s_setprio 1
	v_mfma_f32_16x16x32_bf16 v[52:55], v[198:201], v[164:167], v[52:55]
	v_mfma_f32_16x16x32_bf16 v[48:51], v[206:209], v[164:167], v[48:51]
	v_mfma_f32_16x16x32_bf16 v[36:39], v[198:201], v[172:175], v[36:39]
	v_mfma_f32_16x16x32_bf16 v[32:35], v[206:209], v[172:175], v[32:35]
	v_mfma_f32_16x16x32_bf16 v[20:23], v[198:201], v[180:183], v[20:23]
	v_mfma_f32_16x16x32_bf16 v[16:19], v[206:209], v[180:183], v[16:19]
	v_mfma_f32_16x16x32_bf16 v[4:7], v[198:201], v[190:193], v[4:7]
	v_mfma_f32_16x16x32_bf16 v[0:3], v[206:209], v[190:193], v[0:3]
	v_mfma_f32_16x16x32_bf16 v[52:55], v[202:205], v[168:171], v[52:55]
	v_mfma_f32_16x16x32_bf16 v[48:51], v[210:213], v[168:171], v[48:51]
	v_mfma_f32_16x16x32_bf16 v[36:39], v[202:205], v[176:179], v[36:39]
	v_mfma_f32_16x16x32_bf16 v[32:35], v[210:213], v[176:179], v[32:35]
	v_mfma_f32_16x16x32_bf16 v[20:23], v[202:205], v[184:187], v[20:23]
	v_mfma_f32_16x16x32_bf16 v[16:19], v[210:213], v[184:187], v[16:19]
	v_mfma_f32_16x16x32_bf16 v[4:7], v[202:205], v[194:197], v[4:7]
	v_mfma_f32_16x16x32_bf16 v[0:3], v[210:213], v[194:197], v[0:3]
	s_setprio 0
	s_add_i32 s67, s67, 2
	s_add_u32 s28, s28, 0x100
	s_addc_u32 s29, s29, 0
	s_add_u32 s65, s65, 0x100
	s_addc_u32 s66, s66, 0
	s_cmp_gt_u32 s67, 29
	s_barrier
	s_cbranch_scc0 .LBB0_1240
	v_lshl_add_u32 v144, s26, 8, v149
	v_lshl_or_b32 v142, s62, 8, v151
	v_ashrrev_i32_e32 v145, 31, v144
	v_ashrrev_i32_e32 v143, 31, v142
	v_lshlrev_b64 v[140:141], 11, v[144:145]
	v_lshl_add_u64 v[140:141], v[140:141], 0, v[142:143]
	v_lshlrev_b64 v[160:161], 1, v[140:141]
	v_lshl_add_u64 v[146:147], s[0:1], 0, v[160:161]
	global_load_dwordx2 v[162:163], v[146:147], off
	v_lshl_add_u64 v[146:147], v[140:141], 2, s[54:55]
	global_load_dwordx4 v[156:159], v[146:147], off
	v_mul_f32_e32 v124, 0xbfb8aa3b, v124
	v_mul_f32_e32 v125, 0xbfb8aa3b, v125
	v_mul_f32_e32 v126, 0xbfb8aa3b, v126
	v_mul_f32_e32 v127, 0xbfb8aa3b, v127
	v_exp_f32_e32 v124, v124
	v_exp_f32_e32 v125, v125
	v_exp_f32_e32 v126, v126
	v_exp_f32_e32 v127, v127
	v_add_f32_e32 v145, 1.0, v124
	v_add_f32_e32 v155, 1.0, v125
	v_add_f32_e32 v164, 1.0, v126
	v_add_f32_e32 v165, 1.0, v127
	v_rcp_f32_e32 v126, v145
	v_rcp_f32_e32 v127, v155
	v_rcp_f32_e32 v164, v164
	v_rcp_f32_e32 v165, v165
	v_or_b32_e32 v124, 32, v160
	v_mov_b32_e32 v125, v161
	v_lshl_add_u64 v[166:167], s[0:1], 0, v[124:125]
	v_mul_f32_e32 v120, 0xbfb8aa3b, v120
	v_mul_f32_e32 v121, 0xbfb8aa3b, v121
	v_mul_f32_e32 v122, 0xbfb8aa3b, v122
	v_mul_f32_e32 v123, 0xbfb8aa3b, v123
	v_exp_f32_e32 v120, v120
	v_exp_f32_e32 v121, v121
	v_exp_f32_e32 v122, v122
	v_exp_f32_e32 v123, v123
	v_add_f32_e32 v145, 1.0, v120
	v_add_f32_e32 v155, 1.0, v121
	v_or_b32_e32 v120, 0x100, v160
	v_mov_b32_e32 v121, v161
	v_mul_f32_e32 v116, 0xbfb8aa3b, v116
	v_mul_f32_e32 v117, 0xbfb8aa3b, v117
	v_mul_f32_e32 v118, 0xbfb8aa3b, v118
	v_mul_f32_e32 v119, 0xbfb8aa3b, v119
	v_exp_f32_e32 v116, v116
	v_exp_f32_e32 v117, v117
	v_exp_f32_e32 v118, v118
	v_exp_f32_e32 v119, v119
	v_add_f32_e32 v116, 1.0, v116
	v_add_f32_e32 v117, 1.0, v117
	v_add_f32_e32 v118, 1.0, v118
	v_add_f32_e32 v119, 1.0, v119
	v_rcp_f32_e32 v116, v116
	v_rcp_f32_e32 v117, v117
	v_rcp_f32_e32 v118, v118
	v_rcp_f32_e32 v119, v119
	v_or_b32_e32 v160, 0x120, v160
	v_mul_f32_e32 v112, 0xbfb8aa3b, v112
	v_mul_f32_e32 v113, 0xbfb8aa3b, v113
	v_mul_f32_e32 v114, 0xbfb8aa3b, v114
	v_mul_f32_e32 v115, 0xbfb8aa3b, v115
	v_exp_f32_e32 v114, v114
	v_exp_f32_e32 v115, v115
	v_mul_f32_e32 v108, 0xbfb8aa3b, v108
	v_mul_f32_e32 v109, 0xbfb8aa3b, v109
	v_add_f32_e32 v114, 1.0, v114
	v_add_f32_e32 v115, 1.0, v115
	v_rcp_f32_e32 v114, v114
	v_rcp_f32_e32 v115, v115
	v_mul_f32_e32 v110, 0xbfb8aa3b, v110
	v_mul_f32_e32 v111, 0xbfb8aa3b, v111
	v_exp_f32_e32 v108, v108
	v_exp_f32_e32 v109, v109
	v_exp_f32_e32 v110, v110
	v_exp_f32_e32 v111, v111
	v_add_f32_e32 v108, 1.0, v108
	v_add_f32_e32 v109, 1.0, v109
	v_add_f32_e32 v110, 1.0, v110
	v_add_f32_e32 v111, 1.0, v111
	v_rcp_f32_e32 v108, v108
	v_rcp_f32_e32 v109, v109
	v_rcp_f32_e32 v110, v110
	v_rcp_f32_e32 v111, v111
	v_mul_f32_e32 v104, 0xbfb8aa3b, v104
	v_mul_f32_e32 v105, 0xbfb8aa3b, v105
	v_mul_f32_e32 v106, 0xbfb8aa3b, v106
	s_waitcnt vmcnt(0)
; __device__ __forceinline__ float bflo(unsigned w) { return __uint_as_float(w << 16); }
; __device__ __forceinline__ float bfhi(unsigned w) { return __uint_as_float(w & 0xffff0000u); }
; __device__ __forceinline__ float sigmoidf_(float x) { return __builtin_amdgcn_rcpf(1.0f + __expf(-x)); }
;     __device__ __forceinline__ void operator()(const AccT& acc, const Unit& u, int wr, int wc, int fr, int fq) const {
;     ...
;                     for (int n = 0; n < 2; ++n) { const size_t o = ro + bj * 128 + n * 16; const f32x4 h = *(const f32x4*)(H + o); const u32x2 pw = *(const u32x2*)(PP + o);
;                         const f32x4 a = acc[ai][bj][m][n]; f32x4 r;
;                         r[0] = h[0] + bflo(pw.x) * sigmoidf_(a[0]); r[1] = h[1] + bfhi(pw.x) * sigmoidf_(a[1]); r[2] = h[2] + bflo(pw.y) * sigmoidf_(a[2]); r[3] = h[3] + bfhi(pw.y) * sigmoidf_(a[3]);
;                         *(f32x4*)(H + o) = r; asm volatile("" ::: "memory"); } }
	v_lshlrev_b32_e32 v124, 16, v162
	v_and_b32_e32 v125, 0xffff0000, v162
	v_lshlrev_b32_e32 v162, 16, v163
	v_and_b32_e32 v163, 0xffff0000, v163
	v_pk_fma_f32 v[124:125], v[126:127], v[124:125], v[156:157]
	v_pk_fma_f32 v[126:127], v[164:165], v[162:163], v[158:159]
	global_store_dwordx4 v[146:147], v[124:127], off
	global_load_dwordx2 v[156:157], v[166:167], off
	global_load_dwordx4 v[124:127], v[146:147], off offset:64
	v_add_f32_e32 v158, 1.0, v122
	v_add_f32_e32 v159, 1.0, v123
	v_rcp_f32_e32 v122, v145
	v_rcp_f32_e32 v123, v155
	v_rcp_f32_e32 v158, v158
	v_rcp_f32_e32 v159, v159
	v_lshl_add_u64 v[162:163], s[0:1], 0, v[120:121]
	v_mul_f32_e32 v107, 0xbfb8aa3b, v107
	v_exp_f32_e32 v104, v104
	v_exp_f32_e32 v105, v105
	v_exp_f32_e32 v106, v106
	v_exp_f32_e32 v107, v107
	v_add_f32_e32 v104, 1.0, v104
	v_add_f32_e32 v105, 1.0, v105
	v_add_f32_e32 v106, 1.0, v106
	v_add_f32_e32 v107, 1.0, v107
	v_rcp_f32_e32 v104, v104
	v_rcp_f32_e32 v105, v105
	v_rcp_f32_e32 v106, v106
	v_rcp_f32_e32 v107, v107
	v_mul_f32_e32 v100, 0xbfb8aa3b, v100
	v_mul_f32_e32 v101, 0xbfb8aa3b, v101
	v_mul_f32_e32 v102, 0xbfb8aa3b, v102
	v_mul_f32_e32 v103, 0xbfb8aa3b, v103
	v_exp_f32_e32 v100, v100
	v_exp_f32_e32 v101, v101
	v_exp_f32_e32 v102, v102
	v_exp_f32_e32 v103, v103
	v_add_f32_e32 v100, 1.0, v100
	v_add_f32_e32 v101, 1.0, v101
	v_add_f32_e32 v102, 1.0, v102
	v_add_f32_e32 v103, 1.0, v103
	v_rcp_f32_e32 v100, v100
	v_rcp_f32_e32 v101, v101
	v_rcp_f32_e32 v102, v102
	v_rcp_f32_e32 v103, v103
	v_mul_f32_e32 v96, 0xbfb8aa3b, v96
	v_mul_f32_e32 v97, 0xbfb8aa3b, v97
	v_mul_f32_e32 v98, 0xbfb8aa3b, v98
	v_mul_f32_e32 v99, 0xbfb8aa3b, v99
	v_exp_f32_e32 v98, v98
	v_exp_f32_e32 v99, v99
	v_mul_f32_e32 v92, 0xbfb8aa3b, v92
	v_mul_f32_e32 v93, 0xbfb8aa3b, v93
	v_add_f32_e32 v98, 1.0, v98
	v_add_f32_e32 v99, 1.0, v99
	v_rcp_f32_e32 v98, v98
	v_rcp_f32_e32 v99, v99
	v_mul_f32_e32 v94, 0xbfb8aa3b, v94
	v_mul_f32_e32 v95, 0xbfb8aa3b, v95
	v_exp_f32_e32 v92, v92
	v_exp_f32_e32 v93, v93
	v_exp_f32_e32 v94, v94
	v_exp_f32_e32 v95, v95
	v_add_f32_e32 v92, 1.0, v92
	v_add_f32_e32 v93, 1.0, v93
	v_add_f32_e32 v94, 1.0, v94
	v_add_f32_e32 v95, 1.0, v95
	v_rcp_f32_e32 v92, v92
	v_rcp_f32_e32 v93, v93
	v_rcp_f32_e32 v94, v94
	v_rcp_f32_e32 v95, v95
	v_mul_f32_e32 v88, 0xbfb8aa3b, v88
	v_mul_f32_e32 v89, 0xbfb8aa3b, v89
	v_mul_f32_e32 v90, 0xbfb8aa3b, v90
	v_mul_f32_e32 v91, 0xbfb8aa3b, v91
	v_exp_f32_e32 v88, v88
	v_exp_f32_e32 v89, v89
	v_exp_f32_e32 v90, v90
	v_exp_f32_e32 v91, v91
	v_add_f32_e32 v88, 1.0, v88
	v_add_f32_e32 v89, 1.0, v89
	v_add_f32_e32 v90, 1.0, v90
	v_add_f32_e32 v91, 1.0, v91
	v_rcp_f32_e32 v88, v88
	v_rcp_f32_e32 v89, v89
	v_rcp_f32_e32 v90, v90
	v_rcp_f32_e32 v91, v91
	s_waitcnt vmcnt(0)
	v_lshlrev_b32_e32 v120, 16, v156
	v_and_b32_e32 v121, 0xffff0000, v156
	v_lshlrev_b32_e32 v156, 16, v157
	v_and_b32_e32 v157, 0xffff0000, v157
	v_pk_fma_f32 v[120:121], v[122:123], v[120:121], v[124:125]
	v_pk_fma_f32 v[122:123], v[158:159], v[156:157], v[126:127]
	global_store_dwordx4 v[146:147], v[120:123], off offset:64
	global_load_dwordx2 v[124:125], v[162:163], off
	global_load_dwordx4 v[120:123], v[146:147], off offset:512
	v_lshl_add_u64 v[126:127], s[0:1], 0, v[160:161]
	v_mul_f32_e32 v84, 0xbfb8aa3b, v84
	v_mul_f32_e32 v85, 0xbfb8aa3b, v85
	v_mul_f32_e32 v86, 0xbfb8aa3b, v86
	v_mul_f32_e32 v87, 0xbfb8aa3b, v87
	v_exp_f32_e32 v84, v84
	v_exp_f32_e32 v85, v85
	v_exp_f32_e32 v86, v86
	v_exp_f32_e32 v87, v87
	v_add_f32_e32 v84, 1.0, v84
	v_add_f32_e32 v85, 1.0, v85
	v_add_f32_e32 v86, 1.0, v86
	v_add_f32_e32 v87, 1.0, v87
	v_rcp_f32_e32 v84, v84
	v_rcp_f32_e32 v85, v85
	v_rcp_f32_e32 v86, v86
	v_rcp_f32_e32 v87, v87
	v_mul_f32_e32 v80, 0xbfb8aa3b, v80
	v_mul_f32_e32 v81, 0xbfb8aa3b, v81
	v_mul_f32_e32 v82, 0xbfb8aa3b, v82
	v_mul_f32_e32 v83, 0xbfb8aa3b, v83
	v_exp_f32_e32 v82, v82
	v_exp_f32_e32 v83, v83
	v_mul_f32_e32 v76, 0xbfb8aa3b, v76
	v_mul_f32_e32 v77, 0xbfb8aa3b, v77
	v_add_f32_e32 v82, 1.0, v82
	v_add_f32_e32 v83, 1.0, v83
	v_rcp_f32_e32 v82, v82
	v_rcp_f32_e32 v83, v83
	v_mul_f32_e32 v78, 0xbfb8aa3b, v78
	v_mul_f32_e32 v79, 0xbfb8aa3b, v79
	v_exp_f32_e32 v76, v76
	v_exp_f32_e32 v77, v77
	v_exp_f32_e32 v78, v78
	v_exp_f32_e32 v79, v79
	v_add_f32_e32 v76, 1.0, v76
	v_add_f32_e32 v77, 1.0, v77
	v_add_f32_e32 v78, 1.0, v78
	v_add_f32_e32 v79, 1.0, v79
	v_rcp_f32_e32 v76, v76
	v_rcp_f32_e32 v77, v77
	v_rcp_f32_e32 v78, v78
	v_rcp_f32_e32 v79, v79
	v_mul_f32_e32 v72, 0xbfb8aa3b, v72
	v_mul_f32_e32 v73, 0xbfb8aa3b, v73
	v_mul_f32_e32 v74, 0xbfb8aa3b, v74
	v_mul_f32_e32 v75, 0xbfb8aa3b, v75
	v_exp_f32_e32 v72, v72
	v_exp_f32_e32 v73, v73
	v_exp_f32_e32 v74, v74
	v_exp_f32_e32 v75, v75
	v_add_f32_e32 v72, 1.0, v72
	v_add_f32_e32 v73, 1.0, v73
	v_add_f32_e32 v74, 1.0, v74
	v_add_f32_e32 v75, 1.0, v75
	v_rcp_f32_e32 v72, v72
	v_rcp_f32_e32 v73, v73
	v_rcp_f32_e32 v74, v74
	v_rcp_f32_e32 v75, v75
	v_mul_f32_e32 v68, 0xbfb8aa3b, v68
	v_mul_f32_e32 v69, 0xbfb8aa3b, v69
	v_mul_f32_e32 v70, 0xbfb8aa3b, v70
	v_mul_f32_e32 v71, 0xbfb8aa3b, v71
	v_exp_f32_e32 v68, v68
	v_exp_f32_e32 v69, v69
	v_exp_f32_e32 v70, v70
	v_exp_f32_e32 v71, v71
	v_add_f32_e32 v68, 1.0, v68
	v_add_f32_e32 v69, 1.0, v69
	v_add_f32_e32 v70, 1.0, v70
	v_add_f32_e32 v71, 1.0, v71
	v_rcp_f32_e32 v68, v68
	v_rcp_f32_e32 v69, v69
	v_rcp_f32_e32 v70, v70
	v_rcp_f32_e32 v71, v71
	v_mul_f32_e32 v64, 0xbfb8aa3b, v64
	v_mul_f32_e32 v65, 0xbfb8aa3b, v65
	v_mul_f32_e32 v66, 0xbfb8aa3b, v66
	s_waitcnt vmcnt(0)
; __device__ __forceinline__ float bflo(unsigned w) { return __uint_as_float(w << 16); }
; __device__ __forceinline__ float bfhi(unsigned w) { return __uint_as_float(w & 0xffff0000u); }
; __device__ __forceinline__ float sigmoidf_(float x) { return __builtin_amdgcn_rcpf(1.0f + __expf(-x)); }
;     __device__ __forceinline__ void operator()(const AccT& acc, const Unit& u, int wr, int wc, int fr, int fq) const {
;     ...
;                     for (int n = 0; n < 2; ++n) { const size_t o = ro + bj * 128 + n * 16; const f32x4 h = *(const f32x4*)(H + o); const u32x2 pw = *(const u32x2*)(PP + o);
;                         const f32x4 a = acc[ai][bj][m][n]; f32x4 r;
;                         r[0] = h[0] + bflo(pw.x) * sigmoidf_(a[0]); r[1] = h[1] + bfhi(pw.x) * sigmoidf_(a[1]); r[2] = h[2] + bflo(pw.y) * sigmoidf_(a[2]); r[3] = h[3] + bfhi(pw.y) * sigmoidf_(a[3]);
;                         *(f32x4*)(H + o) = r; asm volatile("" ::: "memory"); } }
	v_lshlrev_b32_e32 v156, 16, v124
	v_and_b32_e32 v157, 0xffff0000, v124
	v_lshlrev_b32_e32 v124, 16, v125
	v_and_b32_e32 v125, 0xffff0000, v125
	v_pk_fma_f32 v[116:117], v[116:117], v[156:157], v[120:121]
	v_pk_fma_f32 v[118:119], v[118:119], v[124:125], v[122:123]
	global_store_dwordx4 v[146:147], v[116:119], off offset:512
	global_load_dwordx2 v[120:121], v[126:127], off
	global_load_dwordx4 v[116:119], v[146:147], off offset:576
	v_exp_f32_e32 v124, v112
	v_exp_f32_e32 v125, v113
	v_or_b32_e32 v112, 16, v144
	v_ashrrev_i32_e32 v113, 31, v112
	v_lshlrev_b64 v[112:113], 11, v[112:113]
	v_lshl_add_u64 v[122:123], v[112:113], 0, v[142:143]
	v_add_f32_e32 v112, 1.0, v124
	v_add_f32_e32 v113, 1.0, v125
	v_rcp_f32_e32 v112, v112
	v_rcp_f32_e32 v113, v113
	v_lshlrev_b64 v[124:125], 1, v[122:123]
	v_lshl_add_u64 v[126:127], s[0:1], 0, v[124:125]
	v_mul_f32_e32 v67, 0xbfb8aa3b, v67
	v_exp_f32_e32 v64, v64
	v_exp_f32_e32 v65, v65
	v_exp_f32_e32 v66, v66
	v_exp_f32_e32 v67, v67
	v_add_f32_e32 v64, 1.0, v64
	v_add_f32_e32 v65, 1.0, v65
	v_add_f32_e32 v66, 1.0, v66
	v_add_f32_e32 v67, 1.0, v67
	v_rcp_f32_e32 v64, v64
	v_rcp_f32_e32 v65, v65
	v_rcp_f32_e32 v66, v66
	v_rcp_f32_e32 v67, v67
	v_mul_f32_e32 v60, 0xbfb8aa3b, v60
	v_mul_f32_e32 v61, 0xbfb8aa3b, v61
	v_mul_f32_e32 v62, 0xbfb8aa3b, v62
	v_mul_f32_e32 v63, 0xbfb8aa3b, v63
	v_exp_f32_e32 v60, v60
	v_exp_f32_e32 v61, v61
	v_exp_f32_e32 v62, v62
	v_exp_f32_e32 v63, v63
	v_add_f32_e32 v60, 1.0, v60
	v_add_f32_e32 v61, 1.0, v61
	v_add_f32_e32 v62, 1.0, v62
	v_add_f32_e32 v63, 1.0, v63
	v_rcp_f32_e32 v60, v60
	v_rcp_f32_e32 v61, v61
	v_rcp_f32_e32 v62, v62
	v_rcp_f32_e32 v63, v63
	v_mul_f32_e32 v56, 0xbfb8aa3b, v56
	v_mul_f32_e32 v57, 0xbfb8aa3b, v57
	v_mul_f32_e32 v58, 0xbfb8aa3b, v58
	v_mul_f32_e32 v59, 0xbfb8aa3b, v59
	v_exp_f32_e32 v56, v56
	v_exp_f32_e32 v57, v57
	v_exp_f32_e32 v58, v58
	v_exp_f32_e32 v59, v59
	v_add_f32_e32 v56, 1.0, v56
	v_add_f32_e32 v57, 1.0, v57
	v_add_f32_e32 v58, 1.0, v58
	v_add_f32_e32 v59, 1.0, v59
	v_rcp_f32_e32 v56, v56
	v_rcp_f32_e32 v57, v57
	v_rcp_f32_e32 v58, v58
	v_rcp_f32_e32 v59, v59
	v_mul_f32_e32 v52, 0xbfb8aa3b, v52
	v_mul_f32_e32 v53, 0xbfb8aa3b, v53
	v_mul_f32_e32 v54, 0xbfb8aa3b, v54
	v_mul_f32_e32 v55, 0xbfb8aa3b, v55
	v_exp_f32_e32 v52, v52
	v_exp_f32_e32 v53, v53
	v_exp_f32_e32 v54, v54
	v_exp_f32_e32 v55, v55
	v_add_f32_e32 v52, 1.0, v52
	v_add_f32_e32 v53, 1.0, v53
	v_add_f32_e32 v54, 1.0, v54
	v_add_f32_e32 v55, 1.0, v55
	v_rcp_f32_e32 v52, v52
	v_rcp_f32_e32 v53, v53
	v_rcp_f32_e32 v54, v54
	v_rcp_f32_e32 v55, v55
	v_mul_f32_e32 v48, 0xbfb8aa3b, v48
	v_mul_f32_e32 v49, 0xbfb8aa3b, v49
	v_mul_f32_e32 v50, 0xbfb8aa3b, v50
	v_mul_f32_e32 v51, 0xbfb8aa3b, v51
	v_exp_f32_e32 v48, v48
	s_waitcnt vmcnt(0)
	v_lshlrev_b32_e32 v156, 16, v120
	v_and_b32_e32 v157, 0xffff0000, v120
	v_lshlrev_b32_e32 v120, 16, v121
	v_and_b32_e32 v121, 0xffff0000, v121
	v_pk_fma_f32 v[112:113], v[112:113], v[156:157], v[116:117]
	v_pk_fma_f32 v[114:115], v[114:115], v[120:121], v[118:119]
	global_store_dwordx4 v[146:147], v[112:115], off offset:576
	global_load_dwordx2 v[116:117], v[126:127], off
	v_lshl_add_u64 v[118:119], v[122:123], 2, s[54:55]
	global_load_dwordx4 v[112:115], v[118:119], off
	v_or_b32_e32 v120, 32, v124
	v_mov_b32_e32 v121, v125
	v_lshl_add_u64 v[120:121], s[0:1], 0, v[120:121]
	v_exp_f32_e32 v49, v49
	v_exp_f32_e32 v50, v50
	v_exp_f32_e32 v51, v51
	v_add_f32_e32 v48, 1.0, v48
	v_add_f32_e32 v49, 1.0, v49
	v_add_f32_e32 v50, 1.0, v50
	v_add_f32_e32 v51, 1.0, v51
	v_rcp_f32_e32 v48, v48
	v_rcp_f32_e32 v49, v49
	v_rcp_f32_e32 v50, v50
	v_rcp_f32_e32 v51, v51
	v_mul_f32_e32 v44, 0xbfb8aa3b, v44
	v_mul_f32_e32 v45, 0xbfb8aa3b, v45
	v_mul_f32_e32 v46, 0xbfb8aa3b, v46
	v_mul_f32_e32 v47, 0xbfb8aa3b, v47
	v_exp_f32_e32 v44, v44
	v_exp_f32_e32 v45, v45
	v_exp_f32_e32 v46, v46
	v_exp_f32_e32 v47, v47
	v_add_f32_e32 v44, 1.0, v44
	v_add_f32_e32 v45, 1.0, v45
	v_add_f32_e32 v46, 1.0, v46
	v_add_f32_e32 v47, 1.0, v47
	v_rcp_f32_e32 v44, v44
	v_rcp_f32_e32 v45, v45
	v_rcp_f32_e32 v46, v46
	v_rcp_f32_e32 v47, v47
	v_mul_f32_e32 v40, 0xbfb8aa3b, v40
	v_mul_f32_e32 v41, 0xbfb8aa3b, v41
	v_mul_f32_e32 v42, 0xbfb8aa3b, v42
	v_mul_f32_e32 v43, 0xbfb8aa3b, v43
	v_exp_f32_e32 v40, v40
	v_exp_f32_e32 v41, v41
	v_exp_f32_e32 v42, v42
	v_exp_f32_e32 v43, v43
	v_add_f32_e32 v40, 1.0, v40
	v_add_f32_e32 v41, 1.0, v41
	v_add_f32_e32 v42, 1.0, v42
	v_add_f32_e32 v43, 1.0, v43
	v_rcp_f32_e32 v40, v40
	v_rcp_f32_e32 v41, v41
	v_rcp_f32_e32 v42, v42
	v_rcp_f32_e32 v43, v43
	v_mul_f32_e32 v36, 0xbfb8aa3b, v36
	v_mul_f32_e32 v37, 0xbfb8aa3b, v37
	v_mul_f32_e32 v38, 0xbfb8aa3b, v38
	v_mul_f32_e32 v39, 0xbfb8aa3b, v39
	v_exp_f32_e32 v36, v36
	v_exp_f32_e32 v37, v37
	v_exp_f32_e32 v38, v38
	v_exp_f32_e32 v39, v39
	v_add_f32_e32 v36, 1.0, v36
	v_add_f32_e32 v37, 1.0, v37
	v_add_f32_e32 v38, 1.0, v38
	v_add_f32_e32 v39, 1.0, v39
	v_rcp_f32_e32 v36, v36
	v_rcp_f32_e32 v37, v37
	v_rcp_f32_e32 v38, v38
	v_rcp_f32_e32 v39, v39
	v_mul_f32_e32 v32, 0xbfb8aa3b, v32
	v_mul_f32_e32 v33, 0xbfb8aa3b, v33
	v_mul_f32_e32 v34, 0xbfb8aa3b, v34
	v_mul_f32_e32 v35, 0xbfb8aa3b, v35
	v_exp_f32_e32 v32, v32
	v_exp_f32_e32 v33, v33
	v_exp_f32_e32 v34, v34
	v_exp_f32_e32 v35, v35
	v_add_f32_e32 v32, 1.0, v32
	v_add_f32_e32 v33, 1.0, v33
	v_add_f32_e32 v34, 1.0, v34
	v_add_f32_e32 v35, 1.0, v35
	v_rcp_f32_e32 v32, v32
	v_rcp_f32_e32 v33, v33
	v_rcp_f32_e32 v34, v34
	s_waitcnt vmcnt(0)
; __device__ __forceinline__ float bflo(unsigned w) { return __uint_as_float(w << 16); }
; __device__ __forceinline__ float bfhi(unsigned w) { return __uint_as_float(w & 0xffff0000u); }
; __device__ __forceinline__ float sigmoidf_(float x) { return __builtin_amdgcn_rcpf(1.0f + __expf(-x)); }
;     __device__ __forceinline__ void operator()(const AccT& acc, const Unit& u, int wr, int wc, int fr, int fq) const {
;     ...
;                     for (int n = 0; n < 2; ++n) { const size_t o = ro + bj * 128 + n * 16; const f32x4 h = *(const f32x4*)(H + o); const u32x2 pw = *(const u32x2*)(PP + o);
;                         const f32x4 a = acc[ai][bj][m][n]; f32x4 r;
;                         r[0] = h[0] + bflo(pw.x) * sigmoidf_(a[0]); r[1] = h[1] + bfhi(pw.x) * sigmoidf_(a[1]); r[2] = h[2] + bflo(pw.y) * sigmoidf_(a[2]); r[3] = h[3] + bfhi(pw.y) * sigmoidf_(a[3]);
;                         *(f32x4*)(H + o) = r; asm volatile("" ::: "memory"); } }
	v_lshlrev_b32_e32 v122, 16, v116
	v_and_b32_e32 v123, 0xffff0000, v116
	v_lshlrev_b32_e32 v116, 16, v117
	v_and_b32_e32 v117, 0xffff0000, v117
	v_pk_fma_f32 v[108:109], v[108:109], v[122:123], v[112:113]
	v_pk_fma_f32 v[110:111], v[110:111], v[116:117], v[114:115]
	global_store_dwordx4 v[118:119], v[108:111], off
	global_load_dwordx2 v[112:113], v[120:121], off
	global_load_dwordx4 v[108:111], v[118:119], off offset:64
	v_or_b32_e32 v114, 0x100, v124
	v_mov_b32_e32 v115, v125
	v_lshl_add_u64 v[114:115], s[0:1], 0, v[114:115]
	v_or_b32_e32 v124, 0x120, v124
	v_rcp_f32_e32 v35, v35
	v_mul_f32_e32 v28, 0xbfb8aa3b, v28
	v_mul_f32_e32 v29, 0xbfb8aa3b, v29
	v_mul_f32_e32 v30, 0xbfb8aa3b, v30
	v_mul_f32_e32 v31, 0xbfb8aa3b, v31
	v_exp_f32_e32 v28, v28
	v_exp_f32_e32 v29, v29
	v_exp_f32_e32 v30, v30
	v_exp_f32_e32 v31, v31
	v_add_f32_e32 v28, 1.0, v28
	v_add_f32_e32 v29, 1.0, v29
	v_add_f32_e32 v30, 1.0, v30
	v_add_f32_e32 v31, 1.0, v31
	v_rcp_f32_e32 v28, v28
	v_rcp_f32_e32 v29, v29
	v_rcp_f32_e32 v30, v30
	v_rcp_f32_e32 v31, v31
	v_mul_f32_e32 v24, 0xbfb8aa3b, v24
	v_mul_f32_e32 v25, 0xbfb8aa3b, v25
	v_mul_f32_e32 v26, 0xbfb8aa3b, v26
	v_mul_f32_e32 v27, 0xbfb8aa3b, v27
	v_exp_f32_e32 v24, v24
	v_exp_f32_e32 v25, v25
	v_exp_f32_e32 v26, v26
	v_exp_f32_e32 v27, v27
	v_add_f32_e32 v24, 1.0, v24
	v_add_f32_e32 v25, 1.0, v25
	v_add_f32_e32 v26, 1.0, v26
	v_add_f32_e32 v27, 1.0, v27
	v_rcp_f32_e32 v24, v24
	v_rcp_f32_e32 v25, v25
	v_rcp_f32_e32 v26, v26
	v_rcp_f32_e32 v27, v27
	v_mul_f32_e32 v20, 0xbfb8aa3b, v20
	v_mul_f32_e32 v21, 0xbfb8aa3b, v21
	v_mul_f32_e32 v22, 0xbfb8aa3b, v22
	v_mul_f32_e32 v23, 0xbfb8aa3b, v23
	v_exp_f32_e32 v20, v20
	v_exp_f32_e32 v21, v21
	v_exp_f32_e32 v22, v22
	v_exp_f32_e32 v23, v23
	v_add_f32_e32 v20, 1.0, v20
	v_add_f32_e32 v21, 1.0, v21
	v_add_f32_e32 v22, 1.0, v22
	v_add_f32_e32 v23, 1.0, v23
	v_rcp_f32_e32 v20, v20
	v_rcp_f32_e32 v21, v21
	v_rcp_f32_e32 v22, v22
	v_rcp_f32_e32 v23, v23
	v_mul_f32_e32 v16, 0xbfb8aa3b, v16
	v_mul_f32_e32 v17, 0xbfb8aa3b, v17
	v_mul_f32_e32 v18, 0xbfb8aa3b, v18
	v_mul_f32_e32 v19, 0xbfb8aa3b, v19
	v_exp_f32_e32 v16, v16
	v_exp_f32_e32 v17, v17
	v_exp_f32_e32 v18, v18
	v_exp_f32_e32 v19, v19
	v_add_f32_e32 v16, 1.0, v16
	v_add_f32_e32 v17, 1.0, v17
	v_add_f32_e32 v18, 1.0, v18
	v_add_f32_e32 v19, 1.0, v19
	v_rcp_f32_e32 v16, v16
	v_rcp_f32_e32 v17, v17
	v_rcp_f32_e32 v18, v18
	v_rcp_f32_e32 v19, v19
	v_mul_f32_e32 v12, 0xbfb8aa3b, v12
	v_mul_f32_e32 v13, 0xbfb8aa3b, v13
	v_mul_f32_e32 v14, 0xbfb8aa3b, v14
	v_mul_f32_e32 v15, 0xbfb8aa3b, v15
	v_exp_f32_e32 v12, v12
	v_exp_f32_e32 v13, v13
	v_exp_f32_e32 v14, v14
	v_exp_f32_e32 v15, v15
	v_add_f32_e32 v12, 1.0, v12
	s_waitcnt vmcnt(0)
	v_lshlrev_b32_e32 v116, 16, v112
	v_and_b32_e32 v117, 0xffff0000, v112
	v_lshlrev_b32_e32 v112, 16, v113
	v_and_b32_e32 v113, 0xffff0000, v113
	v_pk_fma_f32 v[104:105], v[104:105], v[116:117], v[108:109]
	v_pk_fma_f32 v[106:107], v[106:107], v[112:113], v[110:111]
	global_store_dwordx4 v[118:119], v[104:107], off offset:64
	global_load_dwordx2 v[108:109], v[114:115], off
	global_load_dwordx4 v[104:107], v[118:119], off offset:512
	v_lshl_add_u64 v[110:111], s[0:1], 0, v[124:125]
	v_add_f32_e32 v13, 1.0, v13
	v_add_f32_e32 v14, 1.0, v14
	v_add_f32_e32 v15, 1.0, v15
	v_rcp_f32_e32 v12, v12
	v_rcp_f32_e32 v13, v13
	v_rcp_f32_e32 v14, v14
	v_rcp_f32_e32 v15, v15
	v_mul_f32_e32 v8, 0xbfb8aa3b, v8
	v_mul_f32_e32 v9, 0xbfb8aa3b, v9
	v_mul_f32_e32 v10, 0xbfb8aa3b, v10
	v_mul_f32_e32 v11, 0xbfb8aa3b, v11
	v_exp_f32_e32 v8, v8
	v_exp_f32_e32 v9, v9
	v_exp_f32_e32 v10, v10
	v_exp_f32_e32 v11, v11
	v_add_f32_e32 v8, 1.0, v8
	v_add_f32_e32 v9, 1.0, v9
	v_add_f32_e32 v10, 1.0, v10
	v_add_f32_e32 v11, 1.0, v11
	v_rcp_f32_e32 v8, v8
	v_rcp_f32_e32 v9, v9
	v_rcp_f32_e32 v10, v10
	v_rcp_f32_e32 v11, v11
	v_mul_f32_e32 v4, 0xbfb8aa3b, v4
	v_mul_f32_e32 v5, 0xbfb8aa3b, v5
	v_mul_f32_e32 v6, 0xbfb8aa3b, v6
	v_mul_f32_e32 v7, 0xbfb8aa3b, v7
	v_exp_f32_e32 v4, v4
	v_exp_f32_e32 v5, v5
	v_exp_f32_e32 v6, v6
	v_exp_f32_e32 v7, v7
	v_add_f32_e32 v4, 1.0, v4
	v_add_f32_e32 v5, 1.0, v5
	v_add_f32_e32 v6, 1.0, v6
	v_add_f32_e32 v7, 1.0, v7
	v_rcp_f32_e32 v4, v4
	v_rcp_f32_e32 v5, v5
	v_rcp_f32_e32 v6, v6
	v_rcp_f32_e32 v7, v7
	v_mul_f32_e32 v0, 0xbfb8aa3b, v0
	v_mul_f32_e32 v1, 0xbfb8aa3b, v1
	v_mul_f32_e32 v2, 0xbfb8aa3b, v2
	v_mul_f32_e32 v3, 0xbfb8aa3b, v3
	v_exp_f32_e32 v0, v0
	v_exp_f32_e32 v1, v1
	v_exp_f32_e32 v2, v2
	v_exp_f32_e32 v3, v3
	v_add_f32_e32 v0, 1.0, v0
	v_add_f32_e32 v1, 1.0, v1
	v_add_f32_e32 v2, 1.0, v2
	v_add_f32_e32 v3, 1.0, v3
	v_rcp_f32_e32 v0, v0
	v_rcp_f32_e32 v1, v1
	v_rcp_f32_e32 v2, v2
	v_rcp_f32_e32 v3, v3
	s_and_b64 vcc, exec, s[4:5]
	s_mov_b32 s62, s18
	s_mov_b32 s26, s20
	s_mov_b64 s[30:31], s[24:25]
	s_mov_b64 s[28:29], s[22:23]
	s_waitcnt vmcnt(0)
	v_lshlrev_b32_e32 v112, 16, v108
	v_and_b32_e32 v113, 0xffff0000, v108
	v_lshlrev_b32_e32 v108, 16, v109
	v_and_b32_e32 v109, 0xffff0000, v109
	v_pk_fma_f32 v[100:101], v[100:101], v[112:113], v[104:105]
	v_pk_fma_f32 v[102:103], v[102:103], v[108:109], v[106:107]
	global_store_dwordx4 v[118:119], v[100:103], off offset:512
	global_load_dwordx2 v[104:105], v[110:111], off
	global_load_dwordx4 v[100:103], v[118:119], off offset:576
	v_exp_f32_e32 v108, v96
	v_exp_f32_e32 v109, v97
	v_or_b32_e32 v96, 32, v144
	v_ashrrev_i32_e32 v97, 31, v96
	v_lshlrev_b64 v[96:97], 11, v[96:97]
	v_lshl_add_u64 v[106:107], v[96:97], 0, v[142:143]
	v_add_f32_e32 v96, 1.0, v108
	v_add_f32_e32 v97, 1.0, v109
	v_rcp_f32_e32 v96, v96
	v_rcp_f32_e32 v97, v97
	v_lshlrev_b64 v[108:109], 1, v[106:107]
	v_lshl_add_u64 v[110:111], s[0:1], 0, v[108:109]
	s_waitcnt vmcnt(0)
; __device__ __forceinline__ float bflo(unsigned w) { return __uint_as_float(w << 16); }
; __device__ __forceinline__ float bfhi(unsigned w) { return __uint_as_float(w & 0xffff0000u); }
; __device__ __forceinline__ float sigmoidf_(float x) { return __builtin_amdgcn_rcpf(1.0f + __expf(-x)); }
;     __device__ __forceinline__ void operator()(const AccT& acc, const Unit& u, int wr, int wc, int fr, int fq) const {
;     ...
;                     for (int n = 0; n < 2; ++n) { const size_t o = ro + bj * 128 + n * 16; const f32x4 h = *(const f32x4*)(H + o); const u32x2 pw = *(const u32x2*)(PP + o);
;                         const f32x4 a = acc[ai][bj][m][n]; f32x4 r;
;                         r[0] = h[0] + bflo(pw.x) * sigmoidf_(a[0]); r[1] = h[1] + bfhi(pw.x) * sigmoidf_(a[1]); r[2] = h[2] + bflo(pw.y) * sigmoidf_(a[2]); r[3] = h[3] + bfhi(pw.y) * sigmoidf_(a[3]);
;                         *(f32x4*)(H + o) = r; asm volatile("" ::: "memory"); } }
	v_lshlrev_b32_e32 v112, 16, v104
	v_and_b32_e32 v113, 0xffff0000, v104
	v_lshlrev_b32_e32 v104, 16, v105
	v_and_b32_e32 v105, 0xffff0000, v105
	v_pk_fma_f32 v[96:97], v[96:97], v[112:113], v[100:101]
	v_pk_fma_f32 v[98:99], v[98:99], v[104:105], v[102:103]
	global_store_dwordx4 v[118:119], v[96:99], off offset:576
	global_load_dwordx2 v[100:101], v[110:111], off
	v_lshl_add_u64 v[102:103], v[106:107], 2, s[54:55]
	global_load_dwordx4 v[96:99], v[102:103], off
	v_or_b32_e32 v104, 32, v108
	v_mov_b32_e32 v105, v109
	v_lshl_add_u64 v[104:105], s[0:1], 0, v[104:105]
	s_waitcnt vmcnt(0)
	v_lshlrev_b32_e32 v106, 16, v100
	v_and_b32_e32 v107, 0xffff0000, v100
	v_lshlrev_b32_e32 v100, 16, v101
	v_and_b32_e32 v101, 0xffff0000, v101
	v_pk_fma_f32 v[92:93], v[92:93], v[106:107], v[96:97]
	v_pk_fma_f32 v[94:95], v[94:95], v[100:101], v[98:99]
	global_store_dwordx4 v[102:103], v[92:95], off
	global_load_dwordx2 v[96:97], v[104:105], off
	global_load_dwordx4 v[92:95], v[102:103], off offset:64
	v_or_b32_e32 v98, 0x100, v108
	v_mov_b32_e32 v99, v109
	v_lshl_add_u64 v[98:99], s[0:1], 0, v[98:99]
	v_or_b32_e32 v108, 0x120, v108
	s_waitcnt vmcnt(0)
	v_lshlrev_b32_e32 v100, 16, v96
	v_and_b32_e32 v101, 0xffff0000, v96
	v_lshlrev_b32_e32 v96, 16, v97
	v_and_b32_e32 v97, 0xffff0000, v97
	v_pk_fma_f32 v[88:89], v[88:89], v[100:101], v[92:93]
	v_pk_fma_f32 v[90:91], v[90:91], v[96:97], v[94:95]
	global_store_dwordx4 v[102:103], v[88:91], off offset:64
	global_load_dwordx2 v[92:93], v[98:99], off
	global_load_dwordx4 v[88:91], v[102:103], off offset:512
	v_lshl_add_u64 v[94:95], s[0:1], 0, v[108:109]
	s_waitcnt vmcnt(0)
	v_lshlrev_b32_e32 v96, 16, v92
	v_and_b32_e32 v97, 0xffff0000, v92
	v_lshlrev_b32_e32 v92, 16, v93
	v_and_b32_e32 v93, 0xffff0000, v93
	v_pk_fma_f32 v[84:85], v[84:85], v[96:97], v[88:89]
	v_pk_fma_f32 v[86:87], v[86:87], v[92:93], v[90:91]
	global_store_dwordx4 v[102:103], v[84:87], off offset:512
	global_load_dwordx2 v[88:89], v[94:95], off
	global_load_dwordx4 v[84:87], v[102:103], off offset:576
	v_exp_f32_e32 v92, v80
	v_exp_f32_e32 v93, v81
	v_or_b32_e32 v80, 48, v144
	v_ashrrev_i32_e32 v81, 31, v80
	v_lshlrev_b64 v[80:81], 11, v[80:81]
	v_lshl_add_u64 v[90:91], v[80:81], 0, v[142:143]
	v_add_f32_e32 v80, 1.0, v92
	v_add_f32_e32 v81, 1.0, v93
	v_rcp_f32_e32 v80, v80
	v_rcp_f32_e32 v81, v81
	v_lshlrev_b64 v[92:93], 1, v[90:91]
	v_lshl_add_u64 v[94:95], s[0:1], 0, v[92:93]
	s_waitcnt vmcnt(0)
	v_lshlrev_b32_e32 v96, 16, v88
	v_and_b32_e32 v97, 0xffff0000, v88
	v_lshlrev_b32_e32 v88, 16, v89
	v_and_b32_e32 v89, 0xffff0000, v89
	v_pk_fma_f32 v[80:81], v[80:81], v[96:97], v[84:85]
	v_pk_fma_f32 v[82:83], v[82:83], v[88:89], v[86:87]
	global_store_dwordx4 v[102:103], v[80:83], off offset:576
	global_load_dwordx2 v[84:85], v[94:95], off
	v_lshl_add_u64 v[86:87], v[90:91], 2, s[54:55]
	global_load_dwordx4 v[80:83], v[86:87], off
	v_or_b32_e32 v88, 32, v92
	v_mov_b32_e32 v89, v93
	v_lshl_add_u64 v[88:89], s[0:1], 0, v[88:89]
	s_waitcnt vmcnt(0)
	v_lshlrev_b32_e32 v90, 16, v84
	v_and_b32_e32 v91, 0xffff0000, v84
	v_lshlrev_b32_e32 v84, 16, v85
	v_and_b32_e32 v85, 0xffff0000, v85
	v_pk_fma_f32 v[76:77], v[76:77], v[90:91], v[80:81]
	v_pk_fma_f32 v[78:79], v[78:79], v[84:85], v[82:83]
	global_store_dwordx4 v[86:87], v[76:79], off
	global_load_dwordx2 v[80:81], v[88:89], off
	global_load_dwordx4 v[76:79], v[86:87], off offset:64
	v_or_b32_e32 v82, 0x100, v92
	v_mov_b32_e32 v83, v93
	v_lshl_add_u64 v[82:83], s[0:1], 0, v[82:83]
	v_or_b32_e32 v92, 0x120, v92
	s_waitcnt vmcnt(0)
	v_lshlrev_b32_e32 v84, 16, v80
	v_and_b32_e32 v85, 0xffff0000, v80
	v_lshlrev_b32_e32 v80, 16, v81
	v_and_b32_e32 v81, 0xffff0000, v81
	v_pk_fma_f32 v[72:73], v[72:73], v[84:85], v[76:77]
	v_pk_fma_f32 v[74:75], v[74:75], v[80:81], v[78:79]
	global_store_dwordx4 v[86:87], v[72:75], off offset:64
	global_load_dwordx2 v[76:77], v[82:83], off
	global_load_dwordx4 v[72:75], v[86:87], off offset:512
	v_lshl_add_u64 v[78:79], s[0:1], 0, v[92:93]
	s_waitcnt vmcnt(0)
	v_lshlrev_b32_e32 v80, 16, v76
	v_and_b32_e32 v81, 0xffff0000, v76
	v_lshlrev_b32_e32 v76, 16, v77
	v_and_b32_e32 v77, 0xffff0000, v77
	v_pk_fma_f32 v[68:69], v[68:69], v[80:81], v[72:73]
	v_pk_fma_f32 v[70:71], v[70:71], v[76:77], v[74:75]
	global_store_dwordx4 v[86:87], v[68:71], off offset:512
	global_load_dwordx2 v[72:73], v[78:79], off
	global_load_dwordx4 v[68:71], v[86:87], off offset:576
	v_lshl_add_u64 v[74:75], v[140:141], 0, s[8:9]
	v_lshlrev_b64 v[76:77], 1, v[74:75]
	v_lshl_add_u64 v[78:79], s[0:1], 0, v[76:77]
	s_waitcnt vmcnt(0)
	v_lshlrev_b32_e32 v80, 16, v72
	v_and_b32_e32 v81, 0xffff0000, v72
	v_lshlrev_b32_e32 v72, 16, v73
	v_and_b32_e32 v73, 0xffff0000, v73
	v_pk_fma_f32 v[64:65], v[64:65], v[80:81], v[68:69]
	v_pk_fma_f32 v[66:67], v[66:67], v[72:73], v[70:71]
	global_store_dwordx4 v[86:87], v[64:67], off offset:576
	global_load_dwordx2 v[68:69], v[78:79], off
	v_lshl_add_u64 v[70:71], v[74:75], 2, s[54:55]
	global_load_dwordx4 v[64:67], v[70:71], off
	v_or_b32_e32 v72, 32, v76
	v_mov_b32_e32 v73, v77
	v_lshl_add_u64 v[72:73], s[0:1], 0, v[72:73]
	s_waitcnt vmcnt(0)
	v_lshlrev_b32_e32 v74, 16, v68
	v_and_b32_e32 v75, 0xffff0000, v68
	v_lshlrev_b32_e32 v68, 16, v69
	v_and_b32_e32 v69, 0xffff0000, v69
	v_pk_fma_f32 v[60:61], v[60:61], v[74:75], v[64:65]
	v_pk_fma_f32 v[62:63], v[62:63], v[68:69], v[66:67]
	global_store_dwordx4 v[70:71], v[60:63], off
	global_load_dwordx2 v[64:65], v[72:73], off
	global_load_dwordx4 v[60:63], v[70:71], off offset:64
	v_or_b32_e32 v66, 0x100, v76
	v_mov_b32_e32 v67, v77
	v_lshl_add_u64 v[66:67], s[0:1], 0, v[66:67]
	v_or_b32_e32 v76, 0x120, v76
	s_waitcnt vmcnt(0)
; __device__ __forceinline__ float bflo(unsigned w) { return __uint_as_float(w << 16); }
; __device__ __forceinline__ float bfhi(unsigned w) { return __uint_as_float(w & 0xffff0000u); }
; __device__ __forceinline__ float sigmoidf_(float x) { return __builtin_amdgcn_rcpf(1.0f + __expf(-x)); }
;     __device__ __forceinline__ void operator()(const AccT& acc, const Unit& u, int wr, int wc, int fr, int fq) const {
;     ...
;                     for (int n = 0; n < 2; ++n) { const size_t o = ro + bj * 128 + n * 16; const f32x4 h = *(const f32x4*)(H + o); const u32x2 pw = *(const u32x2*)(PP + o);
;                         const f32x4 a = acc[ai][bj][m][n]; f32x4 r;
;                         r[0] = h[0] + bflo(pw.x) * sigmoidf_(a[0]); r[1] = h[1] + bfhi(pw.x) * sigmoidf_(a[1]); r[2] = h[2] + bflo(pw.y) * sigmoidf_(a[2]); r[3] = h[3] + bfhi(pw.y) * sigmoidf_(a[3]);
;                         *(f32x4*)(H + o) = r; asm volatile("" ::: "memory"); } }
	v_lshlrev_b32_e32 v68, 16, v64
	v_and_b32_e32 v69, 0xffff0000, v64
	v_lshlrev_b32_e32 v64, 16, v65
	v_and_b32_e32 v65, 0xffff0000, v65
	v_pk_fma_f32 v[56:57], v[56:57], v[68:69], v[60:61]
	v_pk_fma_f32 v[58:59], v[58:59], v[64:65], v[62:63]
	global_store_dwordx4 v[70:71], v[56:59], off offset:64
	global_load_dwordx2 v[60:61], v[66:67], off
	global_load_dwordx4 v[56:59], v[70:71], off offset:512
	v_lshl_add_u64 v[62:63], s[0:1], 0, v[76:77]
	s_waitcnt vmcnt(0)
	v_lshlrev_b32_e32 v64, 16, v60
	v_and_b32_e32 v65, 0xffff0000, v60
	v_lshlrev_b32_e32 v60, 16, v61
	v_and_b32_e32 v61, 0xffff0000, v61
	v_pk_fma_f32 v[52:53], v[52:53], v[64:65], v[56:57]
	v_pk_fma_f32 v[54:55], v[54:55], v[60:61], v[58:59]
	global_store_dwordx4 v[70:71], v[52:55], off offset:512
	global_load_dwordx2 v[56:57], v[62:63], off
	global_load_dwordx4 v[52:55], v[70:71], off offset:576
	v_lshl_add_u64 v[58:59], v[140:141], 0, s[12:13]
	v_lshlrev_b64 v[60:61], 1, v[58:59]
	v_lshl_add_u64 v[62:63], s[0:1], 0, v[60:61]
	s_waitcnt vmcnt(0)
	v_lshlrev_b32_e32 v64, 16, v56
	v_and_b32_e32 v65, 0xffff0000, v56
	v_lshlrev_b32_e32 v56, 16, v57
	v_and_b32_e32 v57, 0xffff0000, v57
	v_pk_fma_f32 v[48:49], v[48:49], v[64:65], v[52:53]
	v_pk_fma_f32 v[50:51], v[50:51], v[56:57], v[54:55]
	global_store_dwordx4 v[70:71], v[48:51], off offset:576
	global_load_dwordx2 v[52:53], v[62:63], off
	v_lshl_add_u64 v[54:55], v[58:59], 2, s[54:55]
	global_load_dwordx4 v[48:51], v[54:55], off
	v_or_b32_e32 v56, 32, v60
	v_mov_b32_e32 v57, v61
	v_lshl_add_u64 v[56:57], s[0:1], 0, v[56:57]
	s_waitcnt vmcnt(0)
	v_lshlrev_b32_e32 v58, 16, v52
	v_and_b32_e32 v59, 0xffff0000, v52
	v_lshlrev_b32_e32 v52, 16, v53
	v_and_b32_e32 v53, 0xffff0000, v53
	v_pk_fma_f32 v[44:45], v[44:45], v[58:59], v[48:49]
	v_pk_fma_f32 v[46:47], v[46:47], v[52:53], v[50:51]
	global_store_dwordx4 v[54:55], v[44:47], off
	global_load_dwordx2 v[48:49], v[56:57], off
	global_load_dwordx4 v[44:47], v[54:55], off offset:64
	v_or_b32_e32 v50, 0x100, v60
	v_mov_b32_e32 v51, v61
	v_lshl_add_u64 v[50:51], s[0:1], 0, v[50:51]
	v_or_b32_e32 v60, 0x120, v60
	s_waitcnt vmcnt(0)
	v_lshlrev_b32_e32 v52, 16, v48
	v_and_b32_e32 v53, 0xffff0000, v48
	v_lshlrev_b32_e32 v48, 16, v49
	v_and_b32_e32 v49, 0xffff0000, v49
	v_pk_fma_f32 v[40:41], v[40:41], v[52:53], v[44:45]
	v_pk_fma_f32 v[42:43], v[42:43], v[48:49], v[46:47]
	global_store_dwordx4 v[54:55], v[40:43], off offset:64
	global_load_dwordx2 v[44:45], v[50:51], off
	global_load_dwordx4 v[40:43], v[54:55], off offset:512
	v_lshl_add_u64 v[46:47], s[0:1], 0, v[60:61]
	s_waitcnt vmcnt(0)
	v_lshlrev_b32_e32 v48, 16, v44
	v_and_b32_e32 v49, 0xffff0000, v44
	v_lshlrev_b32_e32 v44, 16, v45
	v_and_b32_e32 v45, 0xffff0000, v45
	v_pk_fma_f32 v[36:37], v[36:37], v[48:49], v[40:41]
	v_pk_fma_f32 v[38:39], v[38:39], v[44:45], v[42:43]
	global_store_dwordx4 v[54:55], v[36:39], off offset:512
	global_load_dwordx2 v[40:41], v[46:47], off
	global_load_dwordx4 v[36:39], v[54:55], off offset:576
	v_lshl_add_u64 v[42:43], v[140:141], 0, s[14:15]
	v_lshlrev_b64 v[44:45], 1, v[42:43]
	v_lshl_add_u64 v[46:47], s[0:1], 0, v[44:45]
	s_waitcnt vmcnt(0)
	v_lshlrev_b32_e32 v48, 16, v40
	v_and_b32_e32 v49, 0xffff0000, v40
	v_lshlrev_b32_e32 v40, 16, v41
	v_and_b32_e32 v41, 0xffff0000, v41
	v_pk_fma_f32 v[32:33], v[32:33], v[48:49], v[36:37]
	v_pk_fma_f32 v[34:35], v[34:35], v[40:41], v[38:39]
	global_store_dwordx4 v[54:55], v[32:35], off offset:576
	global_load_dwordx2 v[36:37], v[46:47], off
	v_lshl_add_u64 v[38:39], v[42:43], 2, s[54:55]
	global_load_dwordx4 v[32:35], v[38:39], off
	v_or_b32_e32 v40, 32, v44
	v_mov_b32_e32 v41, v45
	v_lshl_add_u64 v[40:41], s[0:1], 0, v[40:41]
	s_waitcnt vmcnt(0)
; __device__ __forceinline__ float bflo(unsigned w) { return __uint_as_float(w << 16); }
; __device__ __forceinline__ float bfhi(unsigned w) { return __uint_as_float(w & 0xffff0000u); }
; __device__ __forceinline__ float sigmoidf_(float x) { return __builtin_amdgcn_rcpf(1.0f + __expf(-x)); }
; #define PG8_WAIT_V(n) asm volatile("s_waitcnt vmcnt(" #n ")" ::: "memory")
; #define PG8_BAR __builtin_amdgcn_s_barrier()
; template <class Epi>
; __device__ __forceinline__ void gemm_phase(LAS unsigned char* lds, const Gemm g, const StaticOrder& S, const Epi& E) {
;     ...
;     PG8_WAIT_V(0);
;     if (wr == 0) PG8_BAR;
;     PG8_BAR;
;     __device__ __forceinline__ void operator()(const AccT& acc, const Unit& u, int wr, int wc, int fr, int fq) const {
;     ...
;                     for (int n = 0; n < 2; ++n) { const size_t o = ro + bj * 128 + n * 16; const f32x4 h = *(const f32x4*)(H + o); const u32x2 pw = *(const u32x2*)(PP + o);
;                         const f32x4 a = acc[ai][bj][m][n]; f32x4 r;
;                         r[0] = h[0] + bflo(pw.x) * sigmoidf_(a[0]); r[1] = h[1] + bfhi(pw.x) * sigmoidf_(a[1]); r[2] = h[2] + bflo(pw.y) * sigmoidf_(a[2]); r[3] = h[3] + bfhi(pw.y) * sigmoidf_(a[3]);
;                         *(f32x4*)(H + o) = r; asm volatile("" ::: "memory"); } }
	v_lshlrev_b32_e32 v42, 16, v36
	v_and_b32_e32 v43, 0xffff0000, v36
	v_lshlrev_b32_e32 v36, 16, v37
	v_and_b32_e32 v37, 0xffff0000, v37
	v_pk_fma_f32 v[28:29], v[28:29], v[42:43], v[32:33]
	v_pk_fma_f32 v[30:31], v[30:31], v[36:37], v[34:35]
	global_store_dwordx4 v[38:39], v[28:31], off
	global_load_dwordx2 v[32:33], v[40:41], off
	global_load_dwordx4 v[28:31], v[38:39], off offset:64
	v_or_b32_e32 v34, 0x100, v44
	v_mov_b32_e32 v35, v45
	v_lshl_add_u64 v[34:35], s[0:1], 0, v[34:35]
	v_or_b32_e32 v44, 0x120, v44
	s_waitcnt vmcnt(0)
	v_lshlrev_b32_e32 v36, 16, v32
	v_and_b32_e32 v37, 0xffff0000, v32
	v_lshlrev_b32_e32 v32, 16, v33
	v_and_b32_e32 v33, 0xffff0000, v33
	v_pk_fma_f32 v[24:25], v[24:25], v[36:37], v[28:29]
	v_pk_fma_f32 v[26:27], v[26:27], v[32:33], v[30:31]
	global_store_dwordx4 v[38:39], v[24:27], off offset:64
	global_load_dwordx2 v[28:29], v[34:35], off
	global_load_dwordx4 v[24:27], v[38:39], off offset:512
	v_lshl_add_u64 v[30:31], s[0:1], 0, v[44:45]
	s_waitcnt vmcnt(0)
	v_lshlrev_b32_e32 v32, 16, v28
	v_and_b32_e32 v33, 0xffff0000, v28
	v_lshlrev_b32_e32 v28, 16, v29
	v_and_b32_e32 v29, 0xffff0000, v29
	v_pk_fma_f32 v[20:21], v[20:21], v[32:33], v[24:25]
	v_pk_fma_f32 v[22:23], v[22:23], v[28:29], v[26:27]
	global_store_dwordx4 v[38:39], v[20:23], off offset:512
	global_load_dwordx2 v[24:25], v[30:31], off
	global_load_dwordx4 v[20:23], v[38:39], off offset:576
	v_lshl_add_u64 v[26:27], v[140:141], 0, s[16:17]
	v_lshlrev_b64 v[28:29], 1, v[26:27]
	v_lshl_add_u64 v[30:31], s[0:1], 0, v[28:29]
	s_waitcnt vmcnt(0)
	v_lshlrev_b32_e32 v32, 16, v24
	v_and_b32_e32 v33, 0xffff0000, v24
	v_lshlrev_b32_e32 v24, 16, v25
	v_and_b32_e32 v25, 0xffff0000, v25
	v_pk_fma_f32 v[16:17], v[16:17], v[32:33], v[20:21]
	v_pk_fma_f32 v[18:19], v[18:19], v[24:25], v[22:23]
	global_store_dwordx4 v[38:39], v[16:19], off offset:576
	global_load_dwordx2 v[20:21], v[30:31], off
	v_lshl_add_u64 v[22:23], v[26:27], 2, s[54:55]
	global_load_dwordx4 v[16:19], v[22:23], off
	v_or_b32_e32 v24, 32, v28
	v_mov_b32_e32 v25, v29
	v_lshl_add_u64 v[24:25], s[0:1], 0, v[24:25]
	s_waitcnt vmcnt(0)
	v_lshlrev_b32_e32 v26, 16, v20
	v_and_b32_e32 v27, 0xffff0000, v20
	v_lshlrev_b32_e32 v20, 16, v21
	v_and_b32_e32 v21, 0xffff0000, v21
	v_pk_fma_f32 v[12:13], v[12:13], v[26:27], v[16:17]
	v_pk_fma_f32 v[14:15], v[14:15], v[20:21], v[18:19]
	global_store_dwordx4 v[22:23], v[12:15], off
	global_load_dwordx2 v[16:17], v[24:25], off
	global_load_dwordx4 v[12:15], v[22:23], off offset:64
	v_or_b32_e32 v18, 0x100, v28
	v_mov_b32_e32 v19, v29
	v_lshl_add_u64 v[18:19], s[0:1], 0, v[18:19]
	v_or_b32_e32 v28, 0x120, v28
	s_waitcnt vmcnt(0)
	v_lshlrev_b32_e32 v20, 16, v16
	v_and_b32_e32 v21, 0xffff0000, v16
	v_lshlrev_b32_e32 v16, 16, v17
	v_and_b32_e32 v17, 0xffff0000, v17
	v_pk_fma_f32 v[8:9], v[8:9], v[20:21], v[12:13]
	v_pk_fma_f32 v[10:11], v[10:11], v[16:17], v[14:15]
	global_store_dwordx4 v[22:23], v[8:11], off offset:64
	global_load_dwordx2 v[12:13], v[18:19], off
	global_load_dwordx4 v[8:11], v[22:23], off offset:512
	v_lshl_add_u64 v[14:15], s[0:1], 0, v[28:29]
	s_waitcnt vmcnt(0)
	v_lshlrev_b32_e32 v16, 16, v12
	v_and_b32_e32 v17, 0xffff0000, v12
	v_lshlrev_b32_e32 v12, 16, v13
	v_and_b32_e32 v13, 0xffff0000, v13
	v_pk_fma_f32 v[4:5], v[4:5], v[16:17], v[8:9]
	v_pk_fma_f32 v[6:7], v[6:7], v[12:13], v[10:11]
	global_store_dwordx4 v[22:23], v[4:7], off offset:512
	global_load_dwordx2 v[8:9], v[14:15], off
	global_load_dwordx4 v[4:7], v[22:23], off offset:576
	s_waitcnt vmcnt(0)
	v_lshlrev_b32_e32 v10, 16, v8
	v_and_b32_e32 v11, 0xffff0000, v8
	v_lshlrev_b32_e32 v8, 16, v9
	v_and_b32_e32 v9, 0xffff0000, v9
	v_pk_fma_f32 v[0:1], v[0:1], v[10:11], v[4:5]
	v_pk_fma_f32 v[2:3], v[2:3], v[8:9], v[6:7]
	global_store_dwordx4 v[22:23], v[0:3], off offset:576
	s_cbranch_vccz .LBB0_1233
	s_waitcnt vmcnt(0)
	s_cmpk_gt_u32 s3, 0xff
	s_cbranch_scc1 .LBB0_1244
	s_barrier
